# indexer scoring rewritten: key loads prefetched 3-4 blocks ahead into 4 register sets, scalar guards, no canonicalize max
# speedup vs baseline: 1.0045x; 1.0045x over previous
; #define MFMA(a, b, c) __builtin_amdgcn_mfma_f32_32x32x16_bf16((a), (b), (c), 0, 0, 0)
; DI float bf2f(unsigned b) { return __uint_as_float(b << 16); }
; DI void indexer_phase(const u16* __restrict__ P, unsigned* __restrict__ mask) {
;     ...
;     const int b = item & 7, t0 = (1023 - (item >> 3)) * 2;
;     const size_t brow = (size_t)b * SEQ;
;     const int g = (r32 >> 2) & 1, head = 4 * (r32 >> 3) + (r32 & 3);
;     bf16x8 aq[4];
; #pragma unroll
;     for (int s = 0; s < 4; ++s) aq[s] = *(const bf16x8*)(P + (brow + t0 + g) * 7808 + 2560 + head * 64 + 16 * s + 8 * hi);
;     float wv[16];
;     {
;       const u32x4 w0 = *(const u32x4*)(P + (brow + t0 + hi) * 7808 + 3648), w1 = *(const u32x4*)(P + (brow + t0 + hi) * 7808 + 3656);
; #pragma unroll
;       for (int j = 0; j < 4; ++j) { wv[2 * j] = bf2f(w0[j] & 0xffffu); wv[2 * j + 1] = bf2f(w0[j] >> 16); wv[8 + 2 * j] = bf2f(w1[j] & 0xffffu); wv[8 + 2 * j + 1] = bf2f(w1[j] >> 16); }
;     }
;     const int tme = t0 + hi, kbmax = (t0 + 1) >> 5;
;     unsigned sc[64];
; #pragma unroll
;     for (int kb = 0; kb < 64; ++kb) {
;       unsigned u = 0u;
;       if (kb <= kbmax) {
;         f32x16 a;
; #pragma unroll
;         for (int r = 0; r < 16; ++r) a[r] = 0.f;
;         const u16* kp = P + (brow + 32 * kb + r32) * 7808 + 3584 + 8 * hi;
; #pragma unroll
;         for (int s = 0; s < 4; ++s) { const bf16x8 bk = *(const bf16x8*)(kp + 16 * s); a = MFMA(aq[s], bk, a); }
.LBB0_846:
	s_bitcmp0_b32 s87, 0
	s_cselect_b64 vcc, -1, 0
	v_cndmask_b32_e32 v2, v55, v53, vcc
	v_add_u32_e32 v3, s89, v2
	v_cmp_gt_i32_e32 vcc, s2, v3
	s_and_saveexec_b64 s[8:9], vcc
	s_cbranch_execz .LBB0_845
	v_ashrrev_i32_e32 v3, 2, v3
	v_and_b32_e32 v3, -2, v3
	v_lshlrev_b32_e32 v2, 11, v2
	v_sub_u32_e32 v144, 0x7fe, v3
	v_and_b32_e32 v126, 0x3800, v2
	v_add_u32_e32 v8, v144, v126
	v_or_b32_e32 v10, v126, v51
	v_readfirstlane_b32 s22, v144
	v_mul_u32_u24_e32 v10, 0x1e80, v10
	s_mov_b64 s[0:1], 0x7a000
	v_lshlrev_b32_e32 v10, 1, v10
	v_lshl_add_u32 v10, v54, 1, v10
	v_add_u32_e32 v10, 0x1c00, v10
	v_mov_b32_e32 v11, v1
	v_lshl_add_u64 v[124:125], s[96:97], 0, v[10:11]
	s_cmp_lt_u32 s22, 32
	global_load_dwordx4 v[64:67], v[124:125], off
	global_load_dwordx4 v[68:71], v[124:125], off offset:32
	global_load_dwordx4 v[72:75], v[124:125], off offset:64
	global_load_dwordx4 v[76:79], v[124:125], off offset:96
	v_lshl_add_u64 v[124:125], v[124:125], 0, s[0:1]
	s_cbranch_scc1 .Lix_pro_done
	global_load_dwordx4 v[80:83], v[124:125], off
	global_load_dwordx4 v[84:87], v[124:125], off offset:32
	global_load_dwordx4 v[88:91], v[124:125], off offset:64
	global_load_dwordx4 v[92:95], v[124:125], off offset:96
	v_lshl_add_u64 v[124:125], v[124:125], 0, s[0:1]
	s_cmp_lt_u32 s22, 64
	s_cbranch_scc1 .Lix_pro_done
	global_load_dwordx4 v[96:99], v[124:125], off
	global_load_dwordx4 v[100:103], v[124:125], off offset:32
	global_load_dwordx4 v[104:107], v[124:125], off offset:64
	global_load_dwordx4 v[108:111], v[124:125], off offset:96
	v_lshl_add_u64 v[124:125], v[124:125], 0, s[0:1]
	s_cmp_lt_u32 s22, 96
	s_cbranch_scc1 .Lix_pro_done
	global_load_dwordx4 v[112:115], v[124:125], off
	global_load_dwordx4 v[116:119], v[124:125], off offset:32
	global_load_dwordx4 v[120:123], v[124:125], off offset:64
	global_load_dwordx4 v[12:15], v[124:125], off offset:96
	v_lshl_add_u64 v[124:125], v[124:125], 0, s[0:1]
.Lix_pro_done:
	v_or_b32_e32 v4, v8, v52
	v_mov_b64_e32 v[2:3], s[96:97]
	s_movk_i32 s23, 0x3d00
	v_mad_u64_u32 v[4:5], s[0:1], v4, s23, v[2:3]
	v_lshl_add_u64 v[4:5], v[4:5], 0, v[0:1]
	v_lshlrev_b32_e32 v60, 1, v54
	v_mov_b32_e32 v61, v1
	v_lshl_add_u64 v[4:5], v[4:5], 0, v[60:61]
	s_mov_b64 s[0:1], 0x1400
	s_movk_i32 s22, 0x1000
	v_lshl_add_u64 v[6:7], v[4:5], 0, s[0:1]
	v_add_co_u32_e32 v4, vcc, s22, v4
	v_writelane_b32 v255, s8, 56
	s_nop 0
	v_addc_co_u32_e32 v5, vcc, 0, v5, vcc
	global_load_dwordx4 v[46:49], v[4:5], off offset:1024
	global_load_dwordx4 v[42:45], v[6:7], off offset:32
	global_load_dwordx4 v[38:41], v[6:7], off offset:64
	global_load_dwordx4 v[34:37], v[6:7], off offset:96
	v_or_b32_e32 v4, v8, v50
	v_mad_u64_u32 v[2:3], s[0:1], v4, s23, v[2:3]
	s_mov_b64 s[0:1], 0x1c80
	s_nop 0
	v_lshl_add_u64 v[6:7], v[2:3], 0, s[0:1]
	v_add_co_u32_e32 v2, vcc, s22, v2
	s_mov_b64 s[0:1], 0x1c00
	s_nop 0
	v_addc_co_u32_e32 v3, vcc, 0, v3, vcc
	global_load_dwordx4 v[2:5], v[2:3], off offset:3200
	s_nop 0
	global_load_dwordx4 v[6:9], v[6:7], off offset:16
	v_writelane_b32 v255, s9, 57
	v_or_b32_e32 v127, v144, v50
	s_brev_b32 s8, 1
	s_mov_b64 s[22:23], 0x7a000
	v_readfirstlane_b32 s0, v144
	v_sub_u32_e32 v16, v127, v51
	s_waitcnt vmcnt(0)
	v_lshlrev_b32_e32 v143, 16, v2
	v_and_b32_e32 v142, 0xffff0000, v2
	v_lshlrev_b32_e32 v141, 16, v3
	v_and_b32_e32 v140, 0xffff0000, v3
	v_lshlrev_b32_e32 v139, 16, v4
	v_and_b32_e32 v138, 0xffff0000, v4
	v_lshlrev_b32_e32 v137, 16, v5
	v_and_b32_e32 v136, 0xffff0000, v5
	v_lshlrev_b32_e32 v135, 16, v6
	v_and_b32_e32 v134, 0xffff0000, v6
	v_lshlrev_b32_e32 v133, 16, v7
	v_and_b32_e32 v132, 0xffff0000, v7
	v_lshlrev_b32_e32 v131, 16, v8
	v_and_b32_e32 v130, 0xffff0000, v8
	v_lshlrev_b32_e32 v129, 16, v9
	v_and_b32_e32 v128, 0xffff0000, v9
.Lix_b0:
	s_cmp_lt_u32 s0, 0x60
	s_cbranch_scc1 .Lix_w0
	s_waitcnt vmcnt(12)
	s_branch .Lix_m0

; #define MFMA(a, b, c) __builtin_amdgcn_mfma_f32_32x32x16_bf16((a), (b), (c), 0, 0, 0)
; DI unsigned ordkey(float f) { const unsigned b = __float_as_uint(f); return b ^ ((unsigned)((int)b >> 31) | 0x80000000u); }
; DI void indexer_phase(const u16* __restrict__ P, unsigned* __restrict__ mask) {
;     ...
;     for (int kb = 0; kb < 64; ++kb) {
;       unsigned u = 0u;
;       if (kb <= kbmax) {
;         f32x16 a;
; #pragma unroll
;         for (int r = 0; r < 16; ++r) a[r] = 0.f;
;         const u16* kp = P + (brow + 32 * kb + r32) * 7808 + 3584 + 8 * hi;
; #pragma unroll
;         for (int s = 0; s < 4; ++s) { const bf16x8 bk = *(const bf16x8*)(kp + 16 * s); a = MFMA(aq[s], bk, a); }
;         float v = 0.f;
; #pragma unroll
;         for (int i = 0; i < 16; ++i) v = fmaf(wv[i], fmaxf(a[i], 0.f), v);
;         u = (32 * kb + r32 <= tme) ? ordkey(v) : 0u;
;       }
;       sc[kb] = u;
.Lix_m0:
	v_cmp_le_i32_e32 vcc, 0, v16
	v_mfma_f32_32x32x16_bf16 v[18:33], v[46:49], v[64:67], 0
	v_mfma_f32_32x32x16_bf16 v[18:33], v[42:45], v[68:71], v[18:33]
	v_mfma_f32_32x32x16_bf16 v[18:33], v[38:41], v[72:75], v[18:33]
	v_mfma_f32_32x32x16_bf16 v[18:33], v[34:37], v[76:79], v[18:33]
	s_cmp_lt_u32 s0, 0x80
	s_cbranch_scc1 .Lix_np0
	global_load_dwordx4 v[64:67], v[124:125], off
	global_load_dwordx4 v[68:71], v[124:125], off offset:32
	global_load_dwordx4 v[72:75], v[124:125], off offset:64
	global_load_dwordx4 v[76:79], v[124:125], off offset:96
	v_lshl_add_u64 v[124:125], v[124:125], 0, s[22:23]
.Lix_np0:
	s_nop 10
	v_max_f32_e32 v18, 0, v18
	v_max_f32_e32 v19, 0, v19
	v_fma_f32 v18, v143, v18, 0
	v_fmac_f32_e32 v18, v142, v19
	v_max_f32_e32 v19, 0, v20
	v_fmac_f32_e32 v18, v141, v19
	v_max_f32_e32 v19, 0, v21
	v_fmac_f32_e32 v18, v140, v19
	v_max_f32_e32 v19, 0, v22
	v_fmac_f32_e32 v18, v139, v19
	v_max_f32_e32 v19, 0, v23
	v_fmac_f32_e32 v18, v138, v19
	v_max_f32_e32 v19, 0, v24
	v_fmac_f32_e32 v18, v137, v19
	v_max_f32_e32 v19, 0, v25
	v_fmac_f32_e32 v18, v136, v19
	v_max_f32_e32 v19, 0, v26
	v_fmac_f32_e32 v18, v135, v19
	v_max_f32_e32 v19, 0, v27
	v_fmac_f32_e32 v18, v134, v19
	v_max_f32_e32 v19, 0, v28
	v_fmac_f32_e32 v18, v133, v19
	v_max_f32_e32 v19, 0, v29
	v_fmac_f32_e32 v18, v132, v19
	v_max_f32_e32 v19, 0, v30
	v_fmac_f32_e32 v18, v131, v19
	v_max_f32_e32 v19, 0, v31
	v_fmac_f32_e32 v18, v130, v19
	v_max_f32_e32 v19, 0, v32
	v_fmac_f32_e32 v18, v129, v19
	v_max_f32_e32 v19, 0, v33
	v_fmac_f32_e32 v18, v128, v19
	v_ashrrev_i32_e32 v19, 31, v18
	v_bitop3_b32 v18, v19, v18, s8 bitop3:0x36
	v_cndmask_b32_e32 v2, 0, v18, vcc
	s_cmp_lt_u32 s0, 32
	s_cbranch_scc1 .Lix_z1
.Lix_b1:
	s_cmp_lt_u32 s0, 0x80
	s_cbranch_scc1 .Lix_w1
	s_waitcnt vmcnt(12)
	s_branch .Lix_m1

; #define MFMA(a, b, c) __builtin_amdgcn_mfma_f32_32x32x16_bf16((a), (b), (c), 0, 0, 0)
; DI unsigned ordkey(float f) { const unsigned b = __float_as_uint(f); return b ^ ((unsigned)((int)b >> 31) | 0x80000000u); }
; DI void indexer_phase(const u16* __restrict__ P, unsigned* __restrict__ mask) {
;     ...
;     for (int kb = 0; kb < 64; ++kb) {
;       unsigned u = 0u;
;       if (kb <= kbmax) {
;         f32x16 a;
; #pragma unroll
;         for (int r = 0; r < 16; ++r) a[r] = 0.f;
;         const u16* kp = P + (brow + 32 * kb + r32) * 7808 + 3584 + 8 * hi;
; #pragma unroll
;         for (int s = 0; s < 4; ++s) { const bf16x8 bk = *(const bf16x8*)(kp + 16 * s); a = MFMA(aq[s], bk, a); }
;         float v = 0.f;
; #pragma unroll
;         for (int i = 0; i < 16; ++i) v = fmaf(wv[i], fmaxf(a[i], 0.f), v);
;         u = (32 * kb + r32 <= tme) ? ordkey(v) : 0u;
;       }
;       sc[kb] = u;
.Lix_m1:
	v_cmp_le_i32_e32 vcc, 32, v16
	v_mfma_f32_32x32x16_bf16 v[18:33], v[46:49], v[80:83], 0
	v_mfma_f32_32x32x16_bf16 v[18:33], v[42:45], v[84:87], v[18:33]
	v_mfma_f32_32x32x16_bf16 v[18:33], v[38:41], v[88:91], v[18:33]
	v_mfma_f32_32x32x16_bf16 v[18:33], v[34:37], v[92:95], v[18:33]
	s_cmp_lt_u32 s0, 0xa0
	s_cbranch_scc1 .Lix_np1
	global_load_dwordx4 v[80:83], v[124:125], off
	global_load_dwordx4 v[84:87], v[124:125], off offset:32
	global_load_dwordx4 v[88:91], v[124:125], off offset:64
	global_load_dwordx4 v[92:95], v[124:125], off offset:96
	v_lshl_add_u64 v[124:125], v[124:125], 0, s[22:23]
.Lix_np1:
	s_nop 10
	v_max_f32_e32 v18, 0, v18
	v_max_f32_e32 v19, 0, v19
	v_fma_f32 v18, v143, v18, 0
	v_fmac_f32_e32 v18, v142, v19
	v_max_f32_e32 v19, 0, v20
	v_fmac_f32_e32 v18, v141, v19
	v_max_f32_e32 v19, 0, v21
	v_fmac_f32_e32 v18, v140, v19
	v_max_f32_e32 v19, 0, v22
	v_fmac_f32_e32 v18, v139, v19
	v_max_f32_e32 v19, 0, v23
	v_fmac_f32_e32 v18, v138, v19
	v_max_f32_e32 v19, 0, v24
	v_fmac_f32_e32 v18, v137, v19
	v_max_f32_e32 v19, 0, v25
	v_fmac_f32_e32 v18, v136, v19
	v_max_f32_e32 v19, 0, v26
	v_fmac_f32_e32 v18, v135, v19
	v_max_f32_e32 v19, 0, v27
	v_fmac_f32_e32 v18, v134, v19
	v_max_f32_e32 v19, 0, v28
	v_fmac_f32_e32 v18, v133, v19
	v_max_f32_e32 v19, 0, v29
	v_fmac_f32_e32 v18, v132, v19
	v_max_f32_e32 v19, 0, v30
	v_fmac_f32_e32 v18, v131, v19
	v_max_f32_e32 v19, 0, v31
	v_fmac_f32_e32 v18, v130, v19
	v_max_f32_e32 v19, 0, v32
	v_fmac_f32_e32 v18, v129, v19
	v_max_f32_e32 v19, 0, v33
	v_fmac_f32_e32 v18, v128, v19
	v_ashrrev_i32_e32 v19, 31, v18
	v_bitop3_b32 v18, v19, v18, s8 bitop3:0x36
	v_cndmask_b32_e32 v146, 0, v18, vcc
	s_cmp_lt_u32 s0, 64
	s_cbranch_scc1 .Lix_z2
.Lix_b2:
	s_cmp_lt_u32 s0, 0xa0
	s_cbranch_scc1 .Lix_w2
	s_waitcnt vmcnt(12)
	s_branch .Lix_m2

; #define MFMA(a, b, c) __builtin_amdgcn_mfma_f32_32x32x16_bf16((a), (b), (c), 0, 0, 0)
; DI unsigned ordkey(float f) { const unsigned b = __float_as_uint(f); return b ^ ((unsigned)((int)b >> 31) | 0x80000000u); }
; DI void indexer_phase(const u16* __restrict__ P, unsigned* __restrict__ mask) {
;     ...
;     for (int kb = 0; kb < 64; ++kb) {
;       unsigned u = 0u;
;       if (kb <= kbmax) {
;         f32x16 a;
; #pragma unroll
;         for (int r = 0; r < 16; ++r) a[r] = 0.f;
;         const u16* kp = P + (brow + 32 * kb + r32) * 7808 + 3584 + 8 * hi;
; #pragma unroll
;         for (int s = 0; s < 4; ++s) { const bf16x8 bk = *(const bf16x8*)(kp + 16 * s); a = MFMA(aq[s], bk, a); }
;         float v = 0.f;
; #pragma unroll
;         for (int i = 0; i < 16; ++i) v = fmaf(wv[i], fmaxf(a[i], 0.f), v);
;         u = (32 * kb + r32 <= tme) ? ordkey(v) : 0u;
;       }
;       sc[kb] = u;
.Lix_m2:
	v_cmp_le_i32_e32 vcc, 64, v16
	v_mfma_f32_32x32x16_bf16 v[18:33], v[46:49], v[96:99], 0
	v_mfma_f32_32x32x16_bf16 v[18:33], v[42:45], v[100:103], v[18:33]
	v_mfma_f32_32x32x16_bf16 v[18:33], v[38:41], v[104:107], v[18:33]
	v_mfma_f32_32x32x16_bf16 v[18:33], v[34:37], v[108:111], v[18:33]
	s_cmp_lt_u32 s0, 0xc0
	s_cbranch_scc1 .Lix_np2
	global_load_dwordx4 v[96:99], v[124:125], off
	global_load_dwordx4 v[100:103], v[124:125], off offset:32
	global_load_dwordx4 v[104:107], v[124:125], off offset:64
	global_load_dwordx4 v[108:111], v[124:125], off offset:96
	v_lshl_add_u64 v[124:125], v[124:125], 0, s[22:23]
.Lix_np2:
	s_nop 10
	v_max_f32_e32 v18, 0, v18
	v_max_f32_e32 v19, 0, v19
	v_fma_f32 v18, v143, v18, 0
	v_fmac_f32_e32 v18, v142, v19
	v_max_f32_e32 v19, 0, v20
	v_fmac_f32_e32 v18, v141, v19
	v_max_f32_e32 v19, 0, v21
	v_fmac_f32_e32 v18, v140, v19
	v_max_f32_e32 v19, 0, v22
	v_fmac_f32_e32 v18, v139, v19
	v_max_f32_e32 v19, 0, v23
	v_fmac_f32_e32 v18, v138, v19
	v_max_f32_e32 v19, 0, v24
	v_fmac_f32_e32 v18, v137, v19
	v_max_f32_e32 v19, 0, v25
	v_fmac_f32_e32 v18, v136, v19
	v_max_f32_e32 v19, 0, v26
	v_fmac_f32_e32 v18, v135, v19
	v_max_f32_e32 v19, 0, v27
	v_fmac_f32_e32 v18, v134, v19
	v_max_f32_e32 v19, 0, v28
	v_fmac_f32_e32 v18, v133, v19
	v_max_f32_e32 v19, 0, v29
	v_fmac_f32_e32 v18, v132, v19
	v_max_f32_e32 v19, 0, v30
	v_fmac_f32_e32 v18, v131, v19
	v_max_f32_e32 v19, 0, v31
	v_fmac_f32_e32 v18, v130, v19
	v_max_f32_e32 v19, 0, v32
	v_fmac_f32_e32 v18, v129, v19
	v_max_f32_e32 v19, 0, v33
	v_fmac_f32_e32 v18, v128, v19
	v_ashrrev_i32_e32 v19, 31, v18
	v_bitop3_b32 v18, v19, v18, s8 bitop3:0x36
	v_cndmask_b32_e32 v145, 0, v18, vcc
	s_cmp_lt_u32 s0, 0x60
	s_cbranch_scc1 .Lix_z3
.Lix_b3:
	s_cmp_lt_u32 s0, 0xc0
	s_cbranch_scc1 .Lix_w3
	s_waitcnt vmcnt(12)
	s_branch .Lix_m3

; #define MFMA(a, b, c) __builtin_amdgcn_mfma_f32_32x32x16_bf16((a), (b), (c), 0, 0, 0)
; DI unsigned ordkey(float f) { const unsigned b = __float_as_uint(f); return b ^ ((unsigned)((int)b >> 31) | 0x80000000u); }
; DI void indexer_phase(const u16* __restrict__ P, unsigned* __restrict__ mask) {
;     ...
;     for (int kb = 0; kb < 64; ++kb) {
;       unsigned u = 0u;
;       if (kb <= kbmax) {
;         f32x16 a;
; #pragma unroll
;         for (int r = 0; r < 16; ++r) a[r] = 0.f;
;         const u16* kp = P + (brow + 32 * kb + r32) * 7808 + 3584 + 8 * hi;
; #pragma unroll
;         for (int s = 0; s < 4; ++s) { const bf16x8 bk = *(const bf16x8*)(kp + 16 * s); a = MFMA(aq[s], bk, a); }
;         float v = 0.f;
; #pragma unroll
;         for (int i = 0; i < 16; ++i) v = fmaf(wv[i], fmaxf(a[i], 0.f), v);
;         u = (32 * kb + r32 <= tme) ? ordkey(v) : 0u;
;       }
;       sc[kb] = u;
.Lix_m3:
	v_cmp_le_i32_e32 vcc, 0x60, v16
	v_mfma_f32_32x32x16_bf16 v[18:33], v[46:49], v[112:115], 0
	v_mfma_f32_32x32x16_bf16 v[18:33], v[42:45], v[116:119], v[18:33]
	v_mfma_f32_32x32x16_bf16 v[18:33], v[38:41], v[120:123], v[18:33]
	v_mfma_f32_32x32x16_bf16 v[18:33], v[34:37], v[12:15], v[18:33]
	s_cmp_lt_u32 s0, 0xe0
	s_cbranch_scc1 .Lix_np3
	global_load_dwordx4 v[112:115], v[124:125], off
	global_load_dwordx4 v[116:119], v[124:125], off offset:32
	global_load_dwordx4 v[120:123], v[124:125], off offset:64
	global_load_dwordx4 v[12:15], v[124:125], off offset:96
	v_lshl_add_u64 v[124:125], v[124:125], 0, s[22:23]
.Lix_np3:
	s_nop 10
	v_max_f32_e32 v18, 0, v18
	v_max_f32_e32 v19, 0, v19
	v_fma_f32 v18, v143, v18, 0
	v_fmac_f32_e32 v18, v142, v19
	v_max_f32_e32 v19, 0, v20
	v_fmac_f32_e32 v18, v141, v19
	v_max_f32_e32 v19, 0, v21
	v_fmac_f32_e32 v18, v140, v19
	v_max_f32_e32 v19, 0, v22
	v_fmac_f32_e32 v18, v139, v19
	v_max_f32_e32 v19, 0, v23
	v_fmac_f32_e32 v18, v138, v19
	v_max_f32_e32 v19, 0, v24
	v_fmac_f32_e32 v18, v137, v19
	v_max_f32_e32 v19, 0, v25
	v_fmac_f32_e32 v18, v136, v19
	v_max_f32_e32 v19, 0, v26
	v_fmac_f32_e32 v18, v135, v19
	v_max_f32_e32 v19, 0, v27
	v_fmac_f32_e32 v18, v134, v19
	v_max_f32_e32 v19, 0, v28
	v_fmac_f32_e32 v18, v133, v19
	v_max_f32_e32 v19, 0, v29
	v_fmac_f32_e32 v18, v132, v19
	v_max_f32_e32 v19, 0, v30
	v_fmac_f32_e32 v18, v131, v19
	v_max_f32_e32 v19, 0, v31
	v_fmac_f32_e32 v18, v130, v19
	v_max_f32_e32 v19, 0, v32
	v_fmac_f32_e32 v18, v129, v19
	v_max_f32_e32 v19, 0, v33
	v_fmac_f32_e32 v18, v128, v19
	v_ashrrev_i32_e32 v19, 31, v18
	v_bitop3_b32 v18, v19, v18, s8 bitop3:0x36
	v_cndmask_b32_e32 v148, 0, v18, vcc
	s_cmp_lt_u32 s0, 0x80
	s_cbranch_scc1 .Lix_z4
.Lix_b4:
	s_cmp_lt_u32 s0, 0xe0
	s_cbranch_scc1 .Lix_w4
	s_waitcnt vmcnt(12)
	s_branch .Lix_m4

; #define MFMA(a, b, c) __builtin_amdgcn_mfma_f32_32x32x16_bf16((a), (b), (c), 0, 0, 0)
; DI unsigned ordkey(float f) { const unsigned b = __float_as_uint(f); return b ^ ((unsigned)((int)b >> 31) | 0x80000000u); }
; DI void indexer_phase(const u16* __restrict__ P, unsigned* __restrict__ mask) {
;     ...
;     for (int kb = 0; kb < 64; ++kb) {
;       unsigned u = 0u;
;       if (kb <= kbmax) {
;         f32x16 a;
; #pragma unroll
;         for (int r = 0; r < 16; ++r) a[r] = 0.f;
;         const u16* kp = P + (brow + 32 * kb + r32) * 7808 + 3584 + 8 * hi;
; #pragma unroll
;         for (int s = 0; s < 4; ++s) { const bf16x8 bk = *(const bf16x8*)(kp + 16 * s); a = MFMA(aq[s], bk, a); }
;         float v = 0.f;
; #pragma unroll
;         for (int i = 0; i < 16; ++i) v = fmaf(wv[i], fmaxf(a[i], 0.f), v);
;         u = (32 * kb + r32 <= tme) ? ordkey(v) : 0u;
;       }
;       sc[kb] = u;
.Lix_m4:
	v_cmp_le_i32_e32 vcc, 0x80, v16
	v_mfma_f32_32x32x16_bf16 v[18:33], v[46:49], v[64:67], 0
	v_mfma_f32_32x32x16_bf16 v[18:33], v[42:45], v[68:71], v[18:33]
	v_mfma_f32_32x32x16_bf16 v[18:33], v[38:41], v[72:75], v[18:33]
	v_mfma_f32_32x32x16_bf16 v[18:33], v[34:37], v[76:79], v[18:33]
	s_cmp_lt_u32 s0, 0x100
	s_cbranch_scc1 .Lix_np4
	global_load_dwordx4 v[64:67], v[124:125], off
	global_load_dwordx4 v[68:71], v[124:125], off offset:32
	global_load_dwordx4 v[72:75], v[124:125], off offset:64
	global_load_dwordx4 v[76:79], v[124:125], off offset:96
	v_lshl_add_u64 v[124:125], v[124:125], 0, s[22:23]
.Lix_np4:
	s_nop 10
	v_max_f32_e32 v18, 0, v18
	v_max_f32_e32 v19, 0, v19
	v_fma_f32 v18, v143, v18, 0
	v_fmac_f32_e32 v18, v142, v19
	v_max_f32_e32 v19, 0, v20
	v_fmac_f32_e32 v18, v141, v19
	v_max_f32_e32 v19, 0, v21
	v_fmac_f32_e32 v18, v140, v19
	v_max_f32_e32 v19, 0, v22
	v_fmac_f32_e32 v18, v139, v19
	v_max_f32_e32 v19, 0, v23
	v_fmac_f32_e32 v18, v138, v19
	v_max_f32_e32 v19, 0, v24
	v_fmac_f32_e32 v18, v137, v19
	v_max_f32_e32 v19, 0, v25
	v_fmac_f32_e32 v18, v136, v19
	v_max_f32_e32 v19, 0, v26
	v_fmac_f32_e32 v18, v135, v19
	v_max_f32_e32 v19, 0, v27
	v_fmac_f32_e32 v18, v134, v19
	v_max_f32_e32 v19, 0, v28
	v_fmac_f32_e32 v18, v133, v19
	v_max_f32_e32 v19, 0, v29
	v_fmac_f32_e32 v18, v132, v19
	v_max_f32_e32 v19, 0, v30
	v_fmac_f32_e32 v18, v131, v19
	v_max_f32_e32 v19, 0, v31
	v_fmac_f32_e32 v18, v130, v19
	v_max_f32_e32 v19, 0, v32
	v_fmac_f32_e32 v18, v129, v19
	v_max_f32_e32 v19, 0, v33
	v_fmac_f32_e32 v18, v128, v19
	v_ashrrev_i32_e32 v19, 31, v18
	v_bitop3_b32 v18, v19, v18, s8 bitop3:0x36
	v_cndmask_b32_e32 v147, 0, v18, vcc
	s_cmp_lt_u32 s0, 0xa0
	s_cbranch_scc1 .Lix_z5
.Lix_b5:
	s_cmp_lt_u32 s0, 0x100
	s_cbranch_scc1 .Lix_w5
	s_waitcnt vmcnt(12)
	s_branch .Lix_m5

; #define MFMA(a, b, c) __builtin_amdgcn_mfma_f32_32x32x16_bf16((a), (b), (c), 0, 0, 0)
; DI unsigned ordkey(float f) { const unsigned b = __float_as_uint(f); return b ^ ((unsigned)((int)b >> 31) | 0x80000000u); }
; DI void indexer_phase(const u16* __restrict__ P, unsigned* __restrict__ mask) {
;     ...
;     for (int kb = 0; kb < 64; ++kb) {
;       unsigned u = 0u;
;       if (kb <= kbmax) {
;         f32x16 a;
; #pragma unroll
;         for (int r = 0; r < 16; ++r) a[r] = 0.f;
;         const u16* kp = P + (brow + 32 * kb + r32) * 7808 + 3584 + 8 * hi;
; #pragma unroll
;         for (int s = 0; s < 4; ++s) { const bf16x8 bk = *(const bf16x8*)(kp + 16 * s); a = MFMA(aq[s], bk, a); }
;         float v = 0.f;
; #pragma unroll
;         for (int i = 0; i < 16; ++i) v = fmaf(wv[i], fmaxf(a[i], 0.f), v);
;         u = (32 * kb + r32 <= tme) ? ordkey(v) : 0u;
;       }
;       sc[kb] = u;
.Lix_m5:
	v_cmp_le_i32_e32 vcc, 0xa0, v16
	v_mfma_f32_32x32x16_bf16 v[18:33], v[46:49], v[80:83], 0
	v_mfma_f32_32x32x16_bf16 v[18:33], v[42:45], v[84:87], v[18:33]
	v_mfma_f32_32x32x16_bf16 v[18:33], v[38:41], v[88:91], v[18:33]
	v_mfma_f32_32x32x16_bf16 v[18:33], v[34:37], v[92:95], v[18:33]
	s_cmp_lt_u32 s0, 0x120
	s_cbranch_scc1 .Lix_np5
	global_load_dwordx4 v[80:83], v[124:125], off
	global_load_dwordx4 v[84:87], v[124:125], off offset:32
	global_load_dwordx4 v[88:91], v[124:125], off offset:64
	global_load_dwordx4 v[92:95], v[124:125], off offset:96
	v_lshl_add_u64 v[124:125], v[124:125], 0, s[22:23]
.Lix_np5:
	s_nop 10
	v_max_f32_e32 v18, 0, v18
	v_max_f32_e32 v19, 0, v19
	v_fma_f32 v18, v143, v18, 0
	v_fmac_f32_e32 v18, v142, v19
	v_max_f32_e32 v19, 0, v20
	v_fmac_f32_e32 v18, v141, v19
	v_max_f32_e32 v19, 0, v21
	v_fmac_f32_e32 v18, v140, v19
	v_max_f32_e32 v19, 0, v22
	v_fmac_f32_e32 v18, v139, v19
	v_max_f32_e32 v19, 0, v23
	v_fmac_f32_e32 v18, v138, v19
	v_max_f32_e32 v19, 0, v24
	v_fmac_f32_e32 v18, v137, v19
	v_max_f32_e32 v19, 0, v25
	v_fmac_f32_e32 v18, v136, v19
	v_max_f32_e32 v19, 0, v26
	v_fmac_f32_e32 v18, v135, v19
	v_max_f32_e32 v19, 0, v27
	v_fmac_f32_e32 v18, v134, v19
	v_max_f32_e32 v19, 0, v28
	v_fmac_f32_e32 v18, v133, v19
	v_max_f32_e32 v19, 0, v29
	v_fmac_f32_e32 v18, v132, v19
	v_max_f32_e32 v19, 0, v30
	v_fmac_f32_e32 v18, v131, v19
	v_max_f32_e32 v19, 0, v31
	v_fmac_f32_e32 v18, v130, v19
	v_max_f32_e32 v19, 0, v32
	v_fmac_f32_e32 v18, v129, v19
	v_max_f32_e32 v19, 0, v33
	v_fmac_f32_e32 v18, v128, v19
	v_ashrrev_i32_e32 v19, 31, v18
	v_bitop3_b32 v18, v19, v18, s8 bitop3:0x36
	v_cndmask_b32_e32 v150, 0, v18, vcc
	s_cmp_lt_u32 s0, 0xc0
	s_cbranch_scc1 .Lix_z6
.Lix_b6:
	s_cmp_lt_u32 s0, 0x120
	s_cbranch_scc1 .Lix_w6
	s_waitcnt vmcnt(12)
	s_branch .Lix_m6

; #define MFMA(a, b, c) __builtin_amdgcn_mfma_f32_32x32x16_bf16((a), (b), (c), 0, 0, 0)
; DI unsigned ordkey(float f) { const unsigned b = __float_as_uint(f); return b ^ ((unsigned)((int)b >> 31) | 0x80000000u); }
; DI void indexer_phase(const u16* __restrict__ P, unsigned* __restrict__ mask) {
;     ...
;     for (int kb = 0; kb < 64; ++kb) {
;       unsigned u = 0u;
;       if (kb <= kbmax) {
;         f32x16 a;
; #pragma unroll
;         for (int r = 0; r < 16; ++r) a[r] = 0.f;
;         const u16* kp = P + (brow + 32 * kb + r32) * 7808 + 3584 + 8 * hi;
; #pragma unroll
;         for (int s = 0; s < 4; ++s) { const bf16x8 bk = *(const bf16x8*)(kp + 16 * s); a = MFMA(aq[s], bk, a); }
;         float v = 0.f;
; #pragma unroll
;         for (int i = 0; i < 16; ++i) v = fmaf(wv[i], fmaxf(a[i], 0.f), v);
;         u = (32 * kb + r32 <= tme) ? ordkey(v) : 0u;
;       }
;       sc[kb] = u;
.Lix_m6:
	v_cmp_le_i32_e32 vcc, 0xc0, v16
	v_mfma_f32_32x32x16_bf16 v[18:33], v[46:49], v[96:99], 0
	v_mfma_f32_32x32x16_bf16 v[18:33], v[42:45], v[100:103], v[18:33]
	v_mfma_f32_32x32x16_bf16 v[18:33], v[38:41], v[104:107], v[18:33]
	v_mfma_f32_32x32x16_bf16 v[18:33], v[34:37], v[108:111], v[18:33]
	s_cmp_lt_u32 s0, 0x140
	s_cbranch_scc1 .Lix_np6
	global_load_dwordx4 v[96:99], v[124:125], off
	global_load_dwordx4 v[100:103], v[124:125], off offset:32
	global_load_dwordx4 v[104:107], v[124:125], off offset:64
	global_load_dwordx4 v[108:111], v[124:125], off offset:96
	v_lshl_add_u64 v[124:125], v[124:125], 0, s[22:23]
.Lix_np6:
	s_nop 10
	v_max_f32_e32 v18, 0, v18
	v_max_f32_e32 v19, 0, v19
	v_fma_f32 v18, v143, v18, 0
	v_fmac_f32_e32 v18, v142, v19
	v_max_f32_e32 v19, 0, v20
	v_fmac_f32_e32 v18, v141, v19
	v_max_f32_e32 v19, 0, v21
	v_fmac_f32_e32 v18, v140, v19
	v_max_f32_e32 v19, 0, v22
	v_fmac_f32_e32 v18, v139, v19
	v_max_f32_e32 v19, 0, v23
	v_fmac_f32_e32 v18, v138, v19
	v_max_f32_e32 v19, 0, v24
	v_fmac_f32_e32 v18, v137, v19
	v_max_f32_e32 v19, 0, v25
	v_fmac_f32_e32 v18, v136, v19
	v_max_f32_e32 v19, 0, v26
	v_fmac_f32_e32 v18, v135, v19
	v_max_f32_e32 v19, 0, v27
	v_fmac_f32_e32 v18, v134, v19
	v_max_f32_e32 v19, 0, v28
	v_fmac_f32_e32 v18, v133, v19
	v_max_f32_e32 v19, 0, v29
	v_fmac_f32_e32 v18, v132, v19
	v_max_f32_e32 v19, 0, v30
	v_fmac_f32_e32 v18, v131, v19
	v_max_f32_e32 v19, 0, v31
	v_fmac_f32_e32 v18, v130, v19
	v_max_f32_e32 v19, 0, v32
	v_fmac_f32_e32 v18, v129, v19
	v_max_f32_e32 v19, 0, v33
	v_fmac_f32_e32 v18, v128, v19
	v_ashrrev_i32_e32 v19, 31, v18
	v_bitop3_b32 v18, v19, v18, s8 bitop3:0x36
	v_cndmask_b32_e32 v149, 0, v18, vcc
	s_cmp_lt_u32 s0, 0xe0
	s_cbranch_scc1 .Lix_z7
.Lix_b7:
	s_cmp_lt_u32 s0, 0x140
	s_cbranch_scc1 .Lix_w7
	s_waitcnt vmcnt(12)
	s_branch .Lix_m7

; #define MFMA(a, b, c) __builtin_amdgcn_mfma_f32_32x32x16_bf16((a), (b), (c), 0, 0, 0)
; DI unsigned ordkey(float f) { const unsigned b = __float_as_uint(f); return b ^ ((unsigned)((int)b >> 31) | 0x80000000u); }
; DI void indexer_phase(const u16* __restrict__ P, unsigned* __restrict__ mask) {
;     ...
;     for (int kb = 0; kb < 64; ++kb) {
;       unsigned u = 0u;
;       if (kb <= kbmax) {
;         f32x16 a;
; #pragma unroll
;         for (int r = 0; r < 16; ++r) a[r] = 0.f;
;         const u16* kp = P + (brow + 32 * kb + r32) * 7808 + 3584 + 8 * hi;
; #pragma unroll
;         for (int s = 0; s < 4; ++s) { const bf16x8 bk = *(const bf16x8*)(kp + 16 * s); a = MFMA(aq[s], bk, a); }
;         float v = 0.f;
; #pragma unroll
;         for (int i = 0; i < 16; ++i) v = fmaf(wv[i], fmaxf(a[i], 0.f), v);
;         u = (32 * kb + r32 <= tme) ? ordkey(v) : 0u;
;       }
;       sc[kb] = u;
.Lix_m7:
	v_cmp_le_i32_e32 vcc, 0xe0, v16
	v_mfma_f32_32x32x16_bf16 v[18:33], v[46:49], v[112:115], 0
	v_mfma_f32_32x32x16_bf16 v[18:33], v[42:45], v[116:119], v[18:33]
	v_mfma_f32_32x32x16_bf16 v[18:33], v[38:41], v[120:123], v[18:33]
	v_mfma_f32_32x32x16_bf16 v[18:33], v[34:37], v[12:15], v[18:33]
	s_cmp_lt_u32 s0, 0x160
	s_cbranch_scc1 .Lix_np7
	global_load_dwordx4 v[112:115], v[124:125], off
	global_load_dwordx4 v[116:119], v[124:125], off offset:32
	global_load_dwordx4 v[120:123], v[124:125], off offset:64
	global_load_dwordx4 v[12:15], v[124:125], off offset:96
	v_lshl_add_u64 v[124:125], v[124:125], 0, s[22:23]
.Lix_np7:
	s_nop 10
	v_max_f32_e32 v18, 0, v18
	v_max_f32_e32 v19, 0, v19
	v_fma_f32 v18, v143, v18, 0
	v_fmac_f32_e32 v18, v142, v19
	v_max_f32_e32 v19, 0, v20
	v_fmac_f32_e32 v18, v141, v19
	v_max_f32_e32 v19, 0, v21
	v_fmac_f32_e32 v18, v140, v19
	v_max_f32_e32 v19, 0, v22
	v_fmac_f32_e32 v18, v139, v19
	v_max_f32_e32 v19, 0, v23
	v_fmac_f32_e32 v18, v138, v19
	v_max_f32_e32 v19, 0, v24
	v_fmac_f32_e32 v18, v137, v19
	v_max_f32_e32 v19, 0, v25
	v_fmac_f32_e32 v18, v136, v19
	v_max_f32_e32 v19, 0, v26
	v_fmac_f32_e32 v18, v135, v19
	v_max_f32_e32 v19, 0, v27
	v_fmac_f32_e32 v18, v134, v19
	v_max_f32_e32 v19, 0, v28
	v_fmac_f32_e32 v18, v133, v19
	v_max_f32_e32 v19, 0, v29
	v_fmac_f32_e32 v18, v132, v19
	v_max_f32_e32 v19, 0, v30
	v_fmac_f32_e32 v18, v131, v19
	v_max_f32_e32 v19, 0, v31
	v_fmac_f32_e32 v18, v130, v19
	v_max_f32_e32 v19, 0, v32
	v_fmac_f32_e32 v18, v129, v19
	v_max_f32_e32 v19, 0, v33
	v_fmac_f32_e32 v18, v128, v19
	v_ashrrev_i32_e32 v19, 31, v18
	v_bitop3_b32 v18, v19, v18, s8 bitop3:0x36
	v_cndmask_b32_e32 v152, 0, v18, vcc
	s_cmp_lt_u32 s0, 0x100
	s_cbranch_scc1 .Lix_z8
.Lix_b8:
	s_cmp_lt_u32 s0, 0x160
	s_cbranch_scc1 .Lix_w8
	s_waitcnt vmcnt(12)
	s_branch .Lix_m8

; #define MFMA(a, b, c) __builtin_amdgcn_mfma_f32_32x32x16_bf16((a), (b), (c), 0, 0, 0)
; DI unsigned ordkey(float f) { const unsigned b = __float_as_uint(f); return b ^ ((unsigned)((int)b >> 31) | 0x80000000u); }
; DI void indexer_phase(const u16* __restrict__ P, unsigned* __restrict__ mask) {
;     ...
;     for (int kb = 0; kb < 64; ++kb) {
;       unsigned u = 0u;
;       if (kb <= kbmax) {
;         f32x16 a;
; #pragma unroll
;         for (int r = 0; r < 16; ++r) a[r] = 0.f;
;         const u16* kp = P + (brow + 32 * kb + r32) * 7808 + 3584 + 8 * hi;
; #pragma unroll
;         for (int s = 0; s < 4; ++s) { const bf16x8 bk = *(const bf16x8*)(kp + 16 * s); a = MFMA(aq[s], bk, a); }
;         float v = 0.f;
; #pragma unroll
;         for (int i = 0; i < 16; ++i) v = fmaf(wv[i], fmaxf(a[i], 0.f), v);
;         u = (32 * kb + r32 <= tme) ? ordkey(v) : 0u;
;       }
;       sc[kb] = u;
.Lix_m8:
	v_cmp_le_i32_e32 vcc, 0x100, v16
	v_mfma_f32_32x32x16_bf16 v[18:33], v[46:49], v[64:67], 0
	v_mfma_f32_32x32x16_bf16 v[18:33], v[42:45], v[68:71], v[18:33]
	v_mfma_f32_32x32x16_bf16 v[18:33], v[38:41], v[72:75], v[18:33]
	v_mfma_f32_32x32x16_bf16 v[18:33], v[34:37], v[76:79], v[18:33]
	s_cmp_lt_u32 s0, 0x180
	s_cbranch_scc1 .Lix_np8
	global_load_dwordx4 v[64:67], v[124:125], off
	global_load_dwordx4 v[68:71], v[124:125], off offset:32
	global_load_dwordx4 v[72:75], v[124:125], off offset:64
	global_load_dwordx4 v[76:79], v[124:125], off offset:96
	v_lshl_add_u64 v[124:125], v[124:125], 0, s[22:23]
.Lix_np8:
	s_nop 10
	v_max_f32_e32 v18, 0, v18
	v_max_f32_e32 v19, 0, v19
	v_fma_f32 v18, v143, v18, 0
	v_fmac_f32_e32 v18, v142, v19
	v_max_f32_e32 v19, 0, v20
	v_fmac_f32_e32 v18, v141, v19
	v_max_f32_e32 v19, 0, v21
	v_fmac_f32_e32 v18, v140, v19
	v_max_f32_e32 v19, 0, v22
	v_fmac_f32_e32 v18, v139, v19
	v_max_f32_e32 v19, 0, v23
	v_fmac_f32_e32 v18, v138, v19
	v_max_f32_e32 v19, 0, v24
	v_fmac_f32_e32 v18, v137, v19
	v_max_f32_e32 v19, 0, v25
	v_fmac_f32_e32 v18, v136, v19
	v_max_f32_e32 v19, 0, v26
	v_fmac_f32_e32 v18, v135, v19
	v_max_f32_e32 v19, 0, v27
	v_fmac_f32_e32 v18, v134, v19
	v_max_f32_e32 v19, 0, v28
	v_fmac_f32_e32 v18, v133, v19
	v_max_f32_e32 v19, 0, v29
	v_fmac_f32_e32 v18, v132, v19
	v_max_f32_e32 v19, 0, v30
	v_fmac_f32_e32 v18, v131, v19
	v_max_f32_e32 v19, 0, v31
	v_fmac_f32_e32 v18, v130, v19
	v_max_f32_e32 v19, 0, v32
	v_fmac_f32_e32 v18, v129, v19
	v_max_f32_e32 v19, 0, v33
	v_fmac_f32_e32 v18, v128, v19
	v_ashrrev_i32_e32 v19, 31, v18
	v_bitop3_b32 v18, v19, v18, s8 bitop3:0x36
	v_cndmask_b32_e32 v151, 0, v18, vcc
	s_cmp_lt_u32 s0, 0x120
	s_cbranch_scc1 .Lix_z9
.Lix_b9:
	s_cmp_lt_u32 s0, 0x180
	s_cbranch_scc1 .Lix_w9
	s_waitcnt vmcnt(12)
	s_branch .Lix_m9

; #define MFMA(a, b, c) __builtin_amdgcn_mfma_f32_32x32x16_bf16((a), (b), (c), 0, 0, 0)
; DI unsigned ordkey(float f) { const unsigned b = __float_as_uint(f); return b ^ ((unsigned)((int)b >> 31) | 0x80000000u); }
; DI void indexer_phase(const u16* __restrict__ P, unsigned* __restrict__ mask) {
;     ...
;     for (int kb = 0; kb < 64; ++kb) {
;       unsigned u = 0u;
;       if (kb <= kbmax) {
;         f32x16 a;
; #pragma unroll
;         for (int r = 0; r < 16; ++r) a[r] = 0.f;
;         const u16* kp = P + (brow + 32 * kb + r32) * 7808 + 3584 + 8 * hi;
; #pragma unroll
;         for (int s = 0; s < 4; ++s) { const bf16x8 bk = *(const bf16x8*)(kp + 16 * s); a = MFMA(aq[s], bk, a); }
;         float v = 0.f;
; #pragma unroll
;         for (int i = 0; i < 16; ++i) v = fmaf(wv[i], fmaxf(a[i], 0.f), v);
;         u = (32 * kb + r32 <= tme) ? ordkey(v) : 0u;
;       }
;       sc[kb] = u;
.Lix_m9:
	v_cmp_le_i32_e32 vcc, 0x120, v16
	v_mfma_f32_32x32x16_bf16 v[18:33], v[46:49], v[80:83], 0
	v_mfma_f32_32x32x16_bf16 v[18:33], v[42:45], v[84:87], v[18:33]
	v_mfma_f32_32x32x16_bf16 v[18:33], v[38:41], v[88:91], v[18:33]
	v_mfma_f32_32x32x16_bf16 v[18:33], v[34:37], v[92:95], v[18:33]
	s_cmp_lt_u32 s0, 0x1a0
	s_cbranch_scc1 .Lix_np9
	global_load_dwordx4 v[80:83], v[124:125], off
	global_load_dwordx4 v[84:87], v[124:125], off offset:32
	global_load_dwordx4 v[88:91], v[124:125], off offset:64
	global_load_dwordx4 v[92:95], v[124:125], off offset:96
	v_lshl_add_u64 v[124:125], v[124:125], 0, s[22:23]
.Lix_np9:
	s_nop 10
	v_max_f32_e32 v18, 0, v18
	v_max_f32_e32 v19, 0, v19
	v_fma_f32 v18, v143, v18, 0
	v_fmac_f32_e32 v18, v142, v19
	v_max_f32_e32 v19, 0, v20
	v_fmac_f32_e32 v18, v141, v19
	v_max_f32_e32 v19, 0, v21
	v_fmac_f32_e32 v18, v140, v19
	v_max_f32_e32 v19, 0, v22
	v_fmac_f32_e32 v18, v139, v19
	v_max_f32_e32 v19, 0, v23
	v_fmac_f32_e32 v18, v138, v19
	v_max_f32_e32 v19, 0, v24
	v_fmac_f32_e32 v18, v137, v19
	v_max_f32_e32 v19, 0, v25
	v_fmac_f32_e32 v18, v136, v19
	v_max_f32_e32 v19, 0, v26
	v_fmac_f32_e32 v18, v135, v19
	v_max_f32_e32 v19, 0, v27
	v_fmac_f32_e32 v18, v134, v19
	v_max_f32_e32 v19, 0, v28
	v_fmac_f32_e32 v18, v133, v19
	v_max_f32_e32 v19, 0, v29
	v_fmac_f32_e32 v18, v132, v19
	v_max_f32_e32 v19, 0, v30
	v_fmac_f32_e32 v18, v131, v19
	v_max_f32_e32 v19, 0, v31
	v_fmac_f32_e32 v18, v130, v19
	v_max_f32_e32 v19, 0, v32
	v_fmac_f32_e32 v18, v129, v19
	v_max_f32_e32 v19, 0, v33
	v_fmac_f32_e32 v18, v128, v19
	v_ashrrev_i32_e32 v19, 31, v18
	v_bitop3_b32 v18, v19, v18, s8 bitop3:0x36
	v_cndmask_b32_e32 v154, 0, v18, vcc
	s_cmp_lt_u32 s0, 0x140
	s_cbranch_scc1 .Lix_z10
.Lix_b10:
	s_cmp_lt_u32 s0, 0x1a0
	s_cbranch_scc1 .Lix_w10
	s_waitcnt vmcnt(12)
	s_branch .Lix_m10

; #define MFMA(a, b, c) __builtin_amdgcn_mfma_f32_32x32x16_bf16((a), (b), (c), 0, 0, 0)
; DI unsigned ordkey(float f) { const unsigned b = __float_as_uint(f); return b ^ ((unsigned)((int)b >> 31) | 0x80000000u); }
; DI void indexer_phase(const u16* __restrict__ P, unsigned* __restrict__ mask) {
;     ...
;     for (int kb = 0; kb < 64; ++kb) {
;       unsigned u = 0u;
;       if (kb <= kbmax) {
;         f32x16 a;
; #pragma unroll
;         for (int r = 0; r < 16; ++r) a[r] = 0.f;
;         const u16* kp = P + (brow + 32 * kb + r32) * 7808 + 3584 + 8 * hi;
; #pragma unroll
;         for (int s = 0; s < 4; ++s) { const bf16x8 bk = *(const bf16x8*)(kp + 16 * s); a = MFMA(aq[s], bk, a); }
;         float v = 0.f;
; #pragma unroll
;         for (int i = 0; i < 16; ++i) v = fmaf(wv[i], fmaxf(a[i], 0.f), v);
;         u = (32 * kb + r32 <= tme) ? ordkey(v) : 0u;
;       }
;       sc[kb] = u;
.Lix_m10:
	v_cmp_le_i32_e32 vcc, 0x140, v16
	v_mfma_f32_32x32x16_bf16 v[18:33], v[46:49], v[96:99], 0
	v_mfma_f32_32x32x16_bf16 v[18:33], v[42:45], v[100:103], v[18:33]
	v_mfma_f32_32x32x16_bf16 v[18:33], v[38:41], v[104:107], v[18:33]
	v_mfma_f32_32x32x16_bf16 v[18:33], v[34:37], v[108:111], v[18:33]
	s_cmp_lt_u32 s0, 0x1c0
	s_cbranch_scc1 .Lix_np10
	global_load_dwordx4 v[96:99], v[124:125], off
	global_load_dwordx4 v[100:103], v[124:125], off offset:32
	global_load_dwordx4 v[104:107], v[124:125], off offset:64
	global_load_dwordx4 v[108:111], v[124:125], off offset:96
	v_lshl_add_u64 v[124:125], v[124:125], 0, s[22:23]
.Lix_np10:
	s_nop 10
	v_max_f32_e32 v18, 0, v18
	v_max_f32_e32 v19, 0, v19
	v_fma_f32 v18, v143, v18, 0
	v_fmac_f32_e32 v18, v142, v19
	v_max_f32_e32 v19, 0, v20
	v_fmac_f32_e32 v18, v141, v19
	v_max_f32_e32 v19, 0, v21
	v_fmac_f32_e32 v18, v140, v19
	v_max_f32_e32 v19, 0, v22
	v_fmac_f32_e32 v18, v139, v19
	v_max_f32_e32 v19, 0, v23
	v_fmac_f32_e32 v18, v138, v19
	v_max_f32_e32 v19, 0, v24
	v_fmac_f32_e32 v18, v137, v19
	v_max_f32_e32 v19, 0, v25
	v_fmac_f32_e32 v18, v136, v19
	v_max_f32_e32 v19, 0, v26
	v_fmac_f32_e32 v18, v135, v19
	v_max_f32_e32 v19, 0, v27
	v_fmac_f32_e32 v18, v134, v19
	v_max_f32_e32 v19, 0, v28
	v_fmac_f32_e32 v18, v133, v19
	v_max_f32_e32 v19, 0, v29
	v_fmac_f32_e32 v18, v132, v19
	v_max_f32_e32 v19, 0, v30
	v_fmac_f32_e32 v18, v131, v19
	v_max_f32_e32 v19, 0, v31
	v_fmac_f32_e32 v18, v130, v19
	v_max_f32_e32 v19, 0, v32
	v_fmac_f32_e32 v18, v129, v19
	v_max_f32_e32 v19, 0, v33
	v_fmac_f32_e32 v18, v128, v19
	v_ashrrev_i32_e32 v19, 31, v18
	v_bitop3_b32 v18, v19, v18, s8 bitop3:0x36
	v_cndmask_b32_e32 v153, 0, v18, vcc
	s_cmp_lt_u32 s0, 0x160
	s_cbranch_scc1 .Lix_z11
.Lix_b11:
	s_cmp_lt_u32 s0, 0x1c0
	s_cbranch_scc1 .Lix_w11
	s_waitcnt vmcnt(12)
	s_branch .Lix_m11

; #define MFMA(a, b, c) __builtin_amdgcn_mfma_f32_32x32x16_bf16((a), (b), (c), 0, 0, 0)
; DI unsigned ordkey(float f) { const unsigned b = __float_as_uint(f); return b ^ ((unsigned)((int)b >> 31) | 0x80000000u); }
; DI void indexer_phase(const u16* __restrict__ P, unsigned* __restrict__ mask) {
;     ...
;     for (int kb = 0; kb < 64; ++kb) {
;       unsigned u = 0u;
;       if (kb <= kbmax) {
;         f32x16 a;
; #pragma unroll
;         for (int r = 0; r < 16; ++r) a[r] = 0.f;
;         const u16* kp = P + (brow + 32 * kb + r32) * 7808 + 3584 + 8 * hi;
; #pragma unroll
;         for (int s = 0; s < 4; ++s) { const bf16x8 bk = *(const bf16x8*)(kp + 16 * s); a = MFMA(aq[s], bk, a); }
;         float v = 0.f;
; #pragma unroll
;         for (int i = 0; i < 16; ++i) v = fmaf(wv[i], fmaxf(a[i], 0.f), v);
;         u = (32 * kb + r32 <= tme) ? ordkey(v) : 0u;
;       }
;       sc[kb] = u;
.Lix_m11:
	v_cmp_le_i32_e32 vcc, 0x160, v16
	v_mfma_f32_32x32x16_bf16 v[18:33], v[46:49], v[112:115], 0
	v_mfma_f32_32x32x16_bf16 v[18:33], v[42:45], v[116:119], v[18:33]
	v_mfma_f32_32x32x16_bf16 v[18:33], v[38:41], v[120:123], v[18:33]
	v_mfma_f32_32x32x16_bf16 v[18:33], v[34:37], v[12:15], v[18:33]
	s_cmp_lt_u32 s0, 0x1e0
	s_cbranch_scc1 .Lix_np11
	global_load_dwordx4 v[112:115], v[124:125], off
	global_load_dwordx4 v[116:119], v[124:125], off offset:32
	global_load_dwordx4 v[120:123], v[124:125], off offset:64
	global_load_dwordx4 v[12:15], v[124:125], off offset:96
	v_lshl_add_u64 v[124:125], v[124:125], 0, s[22:23]
.Lix_np11:
	s_nop 10
	v_max_f32_e32 v18, 0, v18
	v_max_f32_e32 v19, 0, v19
	v_fma_f32 v18, v143, v18, 0
	v_fmac_f32_e32 v18, v142, v19
	v_max_f32_e32 v19, 0, v20
	v_fmac_f32_e32 v18, v141, v19
	v_max_f32_e32 v19, 0, v21
	v_fmac_f32_e32 v18, v140, v19
	v_max_f32_e32 v19, 0, v22
	v_fmac_f32_e32 v18, v139, v19
	v_max_f32_e32 v19, 0, v23
	v_fmac_f32_e32 v18, v138, v19
	v_max_f32_e32 v19, 0, v24
	v_fmac_f32_e32 v18, v137, v19
	v_max_f32_e32 v19, 0, v25
	v_fmac_f32_e32 v18, v136, v19
	v_max_f32_e32 v19, 0, v26
	v_fmac_f32_e32 v18, v135, v19
	v_max_f32_e32 v19, 0, v27
	v_fmac_f32_e32 v18, v134, v19
	v_max_f32_e32 v19, 0, v28
	v_fmac_f32_e32 v18, v133, v19
	v_max_f32_e32 v19, 0, v29
	v_fmac_f32_e32 v18, v132, v19
	v_max_f32_e32 v19, 0, v30
	v_fmac_f32_e32 v18, v131, v19
	v_max_f32_e32 v19, 0, v31
	v_fmac_f32_e32 v18, v130, v19
	v_max_f32_e32 v19, 0, v32
	v_fmac_f32_e32 v18, v129, v19
	v_max_f32_e32 v19, 0, v33
	v_fmac_f32_e32 v18, v128, v19
	v_ashrrev_i32_e32 v19, 31, v18
	v_bitop3_b32 v18, v19, v18, s8 bitop3:0x36
	v_cndmask_b32_e32 v156, 0, v18, vcc
	s_cmp_lt_u32 s0, 0x180
	s_cbranch_scc1 .Lix_z12
.Lix_b12:
	s_cmp_lt_u32 s0, 0x1e0
	s_cbranch_scc1 .Lix_w12
	s_waitcnt vmcnt(12)
	s_branch .Lix_m12

; #define MFMA(a, b, c) __builtin_amdgcn_mfma_f32_32x32x16_bf16((a), (b), (c), 0, 0, 0)
; DI unsigned ordkey(float f) { const unsigned b = __float_as_uint(f); return b ^ ((unsigned)((int)b >> 31) | 0x80000000u); }
; DI void indexer_phase(const u16* __restrict__ P, unsigned* __restrict__ mask) {
;     ...
;     for (int kb = 0; kb < 64; ++kb) {
;       unsigned u = 0u;
;       if (kb <= kbmax) {
;         f32x16 a;
; #pragma unroll
;         for (int r = 0; r < 16; ++r) a[r] = 0.f;
;         const u16* kp = P + (brow + 32 * kb + r32) * 7808 + 3584 + 8 * hi;
; #pragma unroll
;         for (int s = 0; s < 4; ++s) { const bf16x8 bk = *(const bf16x8*)(kp + 16 * s); a = MFMA(aq[s], bk, a); }
;         float v = 0.f;
; #pragma unroll
;         for (int i = 0; i < 16; ++i) v = fmaf(wv[i], fmaxf(a[i], 0.f), v);
;         u = (32 * kb + r32 <= tme) ? ordkey(v) : 0u;
;       }
;       sc[kb] = u;
.Lix_m12:
	v_cmp_le_i32_e32 vcc, 0x180, v16
	v_mfma_f32_32x32x16_bf16 v[18:33], v[46:49], v[64:67], 0
	v_mfma_f32_32x32x16_bf16 v[18:33], v[42:45], v[68:71], v[18:33]
	v_mfma_f32_32x32x16_bf16 v[18:33], v[38:41], v[72:75], v[18:33]
	v_mfma_f32_32x32x16_bf16 v[18:33], v[34:37], v[76:79], v[18:33]
	s_cmp_lt_u32 s0, 0x200
	s_cbranch_scc1 .Lix_np12
	global_load_dwordx4 v[64:67], v[124:125], off
	global_load_dwordx4 v[68:71], v[124:125], off offset:32
	global_load_dwordx4 v[72:75], v[124:125], off offset:64
	global_load_dwordx4 v[76:79], v[124:125], off offset:96
	v_lshl_add_u64 v[124:125], v[124:125], 0, s[22:23]
.Lix_np12:
	s_nop 10
	v_max_f32_e32 v18, 0, v18
	v_max_f32_e32 v19, 0, v19
	v_fma_f32 v18, v143, v18, 0
	v_fmac_f32_e32 v18, v142, v19
	v_max_f32_e32 v19, 0, v20
	v_fmac_f32_e32 v18, v141, v19
	v_max_f32_e32 v19, 0, v21
	v_fmac_f32_e32 v18, v140, v19
	v_max_f32_e32 v19, 0, v22
	v_fmac_f32_e32 v18, v139, v19
	v_max_f32_e32 v19, 0, v23
	v_fmac_f32_e32 v18, v138, v19
	v_max_f32_e32 v19, 0, v24
	v_fmac_f32_e32 v18, v137, v19
	v_max_f32_e32 v19, 0, v25
	v_fmac_f32_e32 v18, v136, v19
	v_max_f32_e32 v19, 0, v26
	v_fmac_f32_e32 v18, v135, v19
	v_max_f32_e32 v19, 0, v27
	v_fmac_f32_e32 v18, v134, v19
	v_max_f32_e32 v19, 0, v28
	v_fmac_f32_e32 v18, v133, v19
	v_max_f32_e32 v19, 0, v29
	v_fmac_f32_e32 v18, v132, v19
	v_max_f32_e32 v19, 0, v30
	v_fmac_f32_e32 v18, v131, v19
	v_max_f32_e32 v19, 0, v31
	v_fmac_f32_e32 v18, v130, v19
	v_max_f32_e32 v19, 0, v32
	v_fmac_f32_e32 v18, v129, v19
	v_max_f32_e32 v19, 0, v33
	v_fmac_f32_e32 v18, v128, v19
	v_ashrrev_i32_e32 v19, 31, v18
	v_bitop3_b32 v18, v19, v18, s8 bitop3:0x36
	v_cndmask_b32_e32 v155, 0, v18, vcc
	s_cmp_lt_u32 s0, 0x1a0
	s_cbranch_scc1 .Lix_z13
.Lix_b13:
	s_cmp_lt_u32 s0, 0x200
	s_cbranch_scc1 .Lix_w13
	s_waitcnt vmcnt(12)
	s_branch .Lix_m13

; #define MFMA(a, b, c) __builtin_amdgcn_mfma_f32_32x32x16_bf16((a), (b), (c), 0, 0, 0)
; DI unsigned ordkey(float f) { const unsigned b = __float_as_uint(f); return b ^ ((unsigned)((int)b >> 31) | 0x80000000u); }
; DI void indexer_phase(const u16* __restrict__ P, unsigned* __restrict__ mask) {
;     ...
;     for (int kb = 0; kb < 64; ++kb) {
;       unsigned u = 0u;
;       if (kb <= kbmax) {
;         f32x16 a;
; #pragma unroll
;         for (int r = 0; r < 16; ++r) a[r] = 0.f;
;         const u16* kp = P + (brow + 32 * kb + r32) * 7808 + 3584 + 8 * hi;
; #pragma unroll
;         for (int s = 0; s < 4; ++s) { const bf16x8 bk = *(const bf16x8*)(kp + 16 * s); a = MFMA(aq[s], bk, a); }
;         float v = 0.f;
; #pragma unroll
;         for (int i = 0; i < 16; ++i) v = fmaf(wv[i], fmaxf(a[i], 0.f), v);
;         u = (32 * kb + r32 <= tme) ? ordkey(v) : 0u;
;       }
;       sc[kb] = u;
.Lix_m13:
	v_cmp_le_i32_e32 vcc, 0x1a0, v16
	v_mfma_f32_32x32x16_bf16 v[18:33], v[46:49], v[80:83], 0
	v_mfma_f32_32x32x16_bf16 v[18:33], v[42:45], v[84:87], v[18:33]
	v_mfma_f32_32x32x16_bf16 v[18:33], v[38:41], v[88:91], v[18:33]
	v_mfma_f32_32x32x16_bf16 v[18:33], v[34:37], v[92:95], v[18:33]
	s_cmp_lt_u32 s0, 0x220
	s_cbranch_scc1 .Lix_np13
	global_load_dwordx4 v[80:83], v[124:125], off
	global_load_dwordx4 v[84:87], v[124:125], off offset:32
	global_load_dwordx4 v[88:91], v[124:125], off offset:64
	global_load_dwordx4 v[92:95], v[124:125], off offset:96
	v_lshl_add_u64 v[124:125], v[124:125], 0, s[22:23]
.Lix_np13:
	s_nop 10
	v_max_f32_e32 v18, 0, v18
	v_max_f32_e32 v19, 0, v19
	v_fma_f32 v18, v143, v18, 0
	v_fmac_f32_e32 v18, v142, v19
	v_max_f32_e32 v19, 0, v20
	v_fmac_f32_e32 v18, v141, v19
	v_max_f32_e32 v19, 0, v21
	v_fmac_f32_e32 v18, v140, v19
	v_max_f32_e32 v19, 0, v22
	v_fmac_f32_e32 v18, v139, v19
	v_max_f32_e32 v19, 0, v23
	v_fmac_f32_e32 v18, v138, v19
	v_max_f32_e32 v19, 0, v24
	v_fmac_f32_e32 v18, v137, v19
	v_max_f32_e32 v19, 0, v25
	v_fmac_f32_e32 v18, v136, v19
	v_max_f32_e32 v19, 0, v26
	v_fmac_f32_e32 v18, v135, v19
	v_max_f32_e32 v19, 0, v27
	v_fmac_f32_e32 v18, v134, v19
	v_max_f32_e32 v19, 0, v28
	v_fmac_f32_e32 v18, v133, v19
	v_max_f32_e32 v19, 0, v29
	v_fmac_f32_e32 v18, v132, v19
	v_max_f32_e32 v19, 0, v30
	v_fmac_f32_e32 v18, v131, v19
	v_max_f32_e32 v19, 0, v31
	v_fmac_f32_e32 v18, v130, v19
	v_max_f32_e32 v19, 0, v32
	v_fmac_f32_e32 v18, v129, v19
	v_max_f32_e32 v19, 0, v33
	v_fmac_f32_e32 v18, v128, v19
	v_ashrrev_i32_e32 v19, 31, v18
	v_bitop3_b32 v18, v19, v18, s8 bitop3:0x36
	v_cndmask_b32_e32 v158, 0, v18, vcc
	s_cmp_lt_u32 s0, 0x1c0
	s_cbranch_scc1 .Lix_z14
.Lix_b14:
	s_cmp_lt_u32 s0, 0x220
	s_cbranch_scc1 .Lix_w14
	s_waitcnt vmcnt(12)
	s_branch .Lix_m14

; #define MFMA(a, b, c) __builtin_amdgcn_mfma_f32_32x32x16_bf16((a), (b), (c), 0, 0, 0)
; DI unsigned ordkey(float f) { const unsigned b = __float_as_uint(f); return b ^ ((unsigned)((int)b >> 31) | 0x80000000u); }
; DI void indexer_phase(const u16* __restrict__ P, unsigned* __restrict__ mask) {
;     ...
;     for (int kb = 0; kb < 64; ++kb) {
;       unsigned u = 0u;
;       if (kb <= kbmax) {
;         f32x16 a;
; #pragma unroll
;         for (int r = 0; r < 16; ++r) a[r] = 0.f;
;         const u16* kp = P + (brow + 32 * kb + r32) * 7808 + 3584 + 8 * hi;
; #pragma unroll
;         for (int s = 0; s < 4; ++s) { const bf16x8 bk = *(const bf16x8*)(kp + 16 * s); a = MFMA(aq[s], bk, a); }
;         float v = 0.f;
; #pragma unroll
;         for (int i = 0; i < 16; ++i) v = fmaf(wv[i], fmaxf(a[i], 0.f), v);
;         u = (32 * kb + r32 <= tme) ? ordkey(v) : 0u;
;       }
;       sc[kb] = u;
.Lix_m14:
	v_cmp_le_i32_e32 vcc, 0x1c0, v16
	v_mfma_f32_32x32x16_bf16 v[18:33], v[46:49], v[96:99], 0
	v_mfma_f32_32x32x16_bf16 v[18:33], v[42:45], v[100:103], v[18:33]
	v_mfma_f32_32x32x16_bf16 v[18:33], v[38:41], v[104:107], v[18:33]
	v_mfma_f32_32x32x16_bf16 v[18:33], v[34:37], v[108:111], v[18:33]
	s_cmp_lt_u32 s0, 0x240
	s_cbranch_scc1 .Lix_np14
	global_load_dwordx4 v[96:99], v[124:125], off
	global_load_dwordx4 v[100:103], v[124:125], off offset:32
	global_load_dwordx4 v[104:107], v[124:125], off offset:64
	global_load_dwordx4 v[108:111], v[124:125], off offset:96
	v_lshl_add_u64 v[124:125], v[124:125], 0, s[22:23]
.Lix_np14:
	s_nop 10
	v_max_f32_e32 v18, 0, v18
	v_max_f32_e32 v19, 0, v19
	v_fma_f32 v18, v143, v18, 0
	v_fmac_f32_e32 v18, v142, v19
	v_max_f32_e32 v19, 0, v20
	v_fmac_f32_e32 v18, v141, v19
	v_max_f32_e32 v19, 0, v21
	v_fmac_f32_e32 v18, v140, v19
	v_max_f32_e32 v19, 0, v22
	v_fmac_f32_e32 v18, v139, v19
	v_max_f32_e32 v19, 0, v23
	v_fmac_f32_e32 v18, v138, v19
	v_max_f32_e32 v19, 0, v24
	v_fmac_f32_e32 v18, v137, v19
	v_max_f32_e32 v19, 0, v25
	v_fmac_f32_e32 v18, v136, v19
	v_max_f32_e32 v19, 0, v26
	v_fmac_f32_e32 v18, v135, v19
	v_max_f32_e32 v19, 0, v27
	v_fmac_f32_e32 v18, v134, v19
	v_max_f32_e32 v19, 0, v28
	v_fmac_f32_e32 v18, v133, v19
	v_max_f32_e32 v19, 0, v29
	v_fmac_f32_e32 v18, v132, v19
	v_max_f32_e32 v19, 0, v30
	v_fmac_f32_e32 v18, v131, v19
	v_max_f32_e32 v19, 0, v31
	v_fmac_f32_e32 v18, v130, v19
	v_max_f32_e32 v19, 0, v32
	v_fmac_f32_e32 v18, v129, v19
	v_max_f32_e32 v19, 0, v33
	v_fmac_f32_e32 v18, v128, v19
	v_ashrrev_i32_e32 v19, 31, v18
	v_bitop3_b32 v18, v19, v18, s8 bitop3:0x36
	v_cndmask_b32_e32 v157, 0, v18, vcc
	s_cmp_lt_u32 s0, 0x1e0
	s_cbranch_scc1 .Lix_z15
.Lix_b15:
	s_cmp_lt_u32 s0, 0x240
	s_cbranch_scc1 .Lix_w15
	s_waitcnt vmcnt(12)
	s_branch .Lix_m15

; #define MFMA(a, b, c) __builtin_amdgcn_mfma_f32_32x32x16_bf16((a), (b), (c), 0, 0, 0)
; DI unsigned ordkey(float f) { const unsigned b = __float_as_uint(f); return b ^ ((unsigned)((int)b >> 31) | 0x80000000u); }
; DI void indexer_phase(const u16* __restrict__ P, unsigned* __restrict__ mask) {
;     ...
;     for (int kb = 0; kb < 64; ++kb) {
;       unsigned u = 0u;
;       if (kb <= kbmax) {
;         f32x16 a;
; #pragma unroll
;         for (int r = 0; r < 16; ++r) a[r] = 0.f;
;         const u16* kp = P + (brow + 32 * kb + r32) * 7808 + 3584 + 8 * hi;
; #pragma unroll
;         for (int s = 0; s < 4; ++s) { const bf16x8 bk = *(const bf16x8*)(kp + 16 * s); a = MFMA(aq[s], bk, a); }
;         float v = 0.f;
; #pragma unroll
;         for (int i = 0; i < 16; ++i) v = fmaf(wv[i], fmaxf(a[i], 0.f), v);
;         u = (32 * kb + r32 <= tme) ? ordkey(v) : 0u;
;       }
;       sc[kb] = u;
.Lix_m15:
	v_cmp_le_i32_e32 vcc, 0x1e0, v16
	v_mfma_f32_32x32x16_bf16 v[18:33], v[46:49], v[112:115], 0
	v_mfma_f32_32x32x16_bf16 v[18:33], v[42:45], v[116:119], v[18:33]
	v_mfma_f32_32x32x16_bf16 v[18:33], v[38:41], v[120:123], v[18:33]
	v_mfma_f32_32x32x16_bf16 v[18:33], v[34:37], v[12:15], v[18:33]
	s_cmp_lt_u32 s0, 0x260
	s_cbranch_scc1 .Lix_np15
	global_load_dwordx4 v[112:115], v[124:125], off
	global_load_dwordx4 v[116:119], v[124:125], off offset:32
	global_load_dwordx4 v[120:123], v[124:125], off offset:64
	global_load_dwordx4 v[12:15], v[124:125], off offset:96
	v_lshl_add_u64 v[124:125], v[124:125], 0, s[22:23]
.Lix_np15:
	s_nop 10
	v_max_f32_e32 v18, 0, v18
	v_max_f32_e32 v19, 0, v19
	v_fma_f32 v18, v143, v18, 0
	v_fmac_f32_e32 v18, v142, v19
	v_max_f32_e32 v19, 0, v20
	v_fmac_f32_e32 v18, v141, v19
	v_max_f32_e32 v19, 0, v21
	v_fmac_f32_e32 v18, v140, v19
	v_max_f32_e32 v19, 0, v22
	v_fmac_f32_e32 v18, v139, v19
	v_max_f32_e32 v19, 0, v23
	v_fmac_f32_e32 v18, v138, v19
	v_max_f32_e32 v19, 0, v24
	v_fmac_f32_e32 v18, v137, v19
	v_max_f32_e32 v19, 0, v25
	v_fmac_f32_e32 v18, v136, v19
	v_max_f32_e32 v19, 0, v26
	v_fmac_f32_e32 v18, v135, v19
	v_max_f32_e32 v19, 0, v27
	v_fmac_f32_e32 v18, v134, v19
	v_max_f32_e32 v19, 0, v28
	v_fmac_f32_e32 v18, v133, v19
	v_max_f32_e32 v19, 0, v29
	v_fmac_f32_e32 v18, v132, v19
	v_max_f32_e32 v19, 0, v30
	v_fmac_f32_e32 v18, v131, v19
	v_max_f32_e32 v19, 0, v31
	v_fmac_f32_e32 v18, v130, v19
	v_max_f32_e32 v19, 0, v32
	v_fmac_f32_e32 v18, v129, v19
	v_max_f32_e32 v19, 0, v33
	v_fmac_f32_e32 v18, v128, v19
	v_ashrrev_i32_e32 v19, 31, v18
	v_bitop3_b32 v18, v19, v18, s8 bitop3:0x36
	v_cndmask_b32_e32 v160, 0, v18, vcc
	s_cmp_lt_u32 s0, 0x200
	s_cbranch_scc1 .Lix_z16
.Lix_b16:
	s_cmp_lt_u32 s0, 0x260
	s_cbranch_scc1 .Lix_w16
	s_waitcnt vmcnt(12)
	s_branch .Lix_m16

; #define MFMA(a, b, c) __builtin_amdgcn_mfma_f32_32x32x16_bf16((a), (b), (c), 0, 0, 0)
; DI unsigned ordkey(float f) { const unsigned b = __float_as_uint(f); return b ^ ((unsigned)((int)b >> 31) | 0x80000000u); }
; DI void indexer_phase(const u16* __restrict__ P, unsigned* __restrict__ mask) {
;     ...
;     for (int kb = 0; kb < 64; ++kb) {
;       unsigned u = 0u;
;       if (kb <= kbmax) {
;         f32x16 a;
; #pragma unroll
;         for (int r = 0; r < 16; ++r) a[r] = 0.f;
;         const u16* kp = P + (brow + 32 * kb + r32) * 7808 + 3584 + 8 * hi;
; #pragma unroll
;         for (int s = 0; s < 4; ++s) { const bf16x8 bk = *(const bf16x8*)(kp + 16 * s); a = MFMA(aq[s], bk, a); }
;         float v = 0.f;
; #pragma unroll
;         for (int i = 0; i < 16; ++i) v = fmaf(wv[i], fmaxf(a[i], 0.f), v);
;         u = (32 * kb + r32 <= tme) ? ordkey(v) : 0u;
;       }
;       sc[kb] = u;
.Lix_m16:
	v_cmp_le_i32_e32 vcc, 0x200, v16
	v_mfma_f32_32x32x16_bf16 v[18:33], v[46:49], v[64:67], 0
	v_mfma_f32_32x32x16_bf16 v[18:33], v[42:45], v[68:71], v[18:33]
	v_mfma_f32_32x32x16_bf16 v[18:33], v[38:41], v[72:75], v[18:33]
	v_mfma_f32_32x32x16_bf16 v[18:33], v[34:37], v[76:79], v[18:33]
	s_cmp_lt_u32 s0, 0x280
	s_cbranch_scc1 .Lix_np16
	global_load_dwordx4 v[64:67], v[124:125], off
	global_load_dwordx4 v[68:71], v[124:125], off offset:32
	global_load_dwordx4 v[72:75], v[124:125], off offset:64
	global_load_dwordx4 v[76:79], v[124:125], off offset:96
	v_lshl_add_u64 v[124:125], v[124:125], 0, s[22:23]
.Lix_np16:
	s_nop 10
	v_max_f32_e32 v18, 0, v18
	v_max_f32_e32 v19, 0, v19
	v_fma_f32 v18, v143, v18, 0
	v_fmac_f32_e32 v18, v142, v19
	v_max_f32_e32 v19, 0, v20
	v_fmac_f32_e32 v18, v141, v19
	v_max_f32_e32 v19, 0, v21
	v_fmac_f32_e32 v18, v140, v19
	v_max_f32_e32 v19, 0, v22
	v_fmac_f32_e32 v18, v139, v19
	v_max_f32_e32 v19, 0, v23
	v_fmac_f32_e32 v18, v138, v19
	v_max_f32_e32 v19, 0, v24
	v_fmac_f32_e32 v18, v137, v19
	v_max_f32_e32 v19, 0, v25
	v_fmac_f32_e32 v18, v136, v19
	v_max_f32_e32 v19, 0, v26
	v_fmac_f32_e32 v18, v135, v19
	v_max_f32_e32 v19, 0, v27
	v_fmac_f32_e32 v18, v134, v19
	v_max_f32_e32 v19, 0, v28
	v_fmac_f32_e32 v18, v133, v19
	v_max_f32_e32 v19, 0, v29
	v_fmac_f32_e32 v18, v132, v19
	v_max_f32_e32 v19, 0, v30
	v_fmac_f32_e32 v18, v131, v19
	v_max_f32_e32 v19, 0, v31
	v_fmac_f32_e32 v18, v130, v19
	v_max_f32_e32 v19, 0, v32
	v_fmac_f32_e32 v18, v129, v19
	v_max_f32_e32 v19, 0, v33
	v_fmac_f32_e32 v18, v128, v19
	v_ashrrev_i32_e32 v19, 31, v18
	v_bitop3_b32 v18, v19, v18, s8 bitop3:0x36
	v_cndmask_b32_e32 v159, 0, v18, vcc
	s_cmp_lt_u32 s0, 0x220
	s_cbranch_scc1 .Lix_z17
.Lix_b17:
	s_cmp_lt_u32 s0, 0x280
	s_cbranch_scc1 .Lix_w17
	s_waitcnt vmcnt(12)
	s_branch .Lix_m17

; #define MFMA(a, b, c) __builtin_amdgcn_mfma_f32_32x32x16_bf16((a), (b), (c), 0, 0, 0)
; DI unsigned ordkey(float f) { const unsigned b = __float_as_uint(f); return b ^ ((unsigned)((int)b >> 31) | 0x80000000u); }
; DI void indexer_phase(const u16* __restrict__ P, unsigned* __restrict__ mask) {
;     ...
;     for (int kb = 0; kb < 64; ++kb) {
;       unsigned u = 0u;
;       if (kb <= kbmax) {
;         f32x16 a;
; #pragma unroll
;         for (int r = 0; r < 16; ++r) a[r] = 0.f;
;         const u16* kp = P + (brow + 32 * kb + r32) * 7808 + 3584 + 8 * hi;
; #pragma unroll
;         for (int s = 0; s < 4; ++s) { const bf16x8 bk = *(const bf16x8*)(kp + 16 * s); a = MFMA(aq[s], bk, a); }
;         float v = 0.f;
; #pragma unroll
;         for (int i = 0; i < 16; ++i) v = fmaf(wv[i], fmaxf(a[i], 0.f), v);
;         u = (32 * kb + r32 <= tme) ? ordkey(v) : 0u;
;       }
;       sc[kb] = u;
.Lix_m17:
	v_cmp_le_i32_e32 vcc, 0x220, v16
	v_mfma_f32_32x32x16_bf16 v[18:33], v[46:49], v[80:83], 0
	v_mfma_f32_32x32x16_bf16 v[18:33], v[42:45], v[84:87], v[18:33]
	v_mfma_f32_32x32x16_bf16 v[18:33], v[38:41], v[88:91], v[18:33]
	v_mfma_f32_32x32x16_bf16 v[18:33], v[34:37], v[92:95], v[18:33]
	s_cmp_lt_u32 s0, 0x2a0
	s_cbranch_scc1 .Lix_np17
	global_load_dwordx4 v[80:83], v[124:125], off
	global_load_dwordx4 v[84:87], v[124:125], off offset:32
	global_load_dwordx4 v[88:91], v[124:125], off offset:64
	global_load_dwordx4 v[92:95], v[124:125], off offset:96
	v_lshl_add_u64 v[124:125], v[124:125], 0, s[22:23]
.Lix_np17:
	s_nop 10
	v_max_f32_e32 v18, 0, v18
	v_max_f32_e32 v19, 0, v19
	v_fma_f32 v18, v143, v18, 0
	v_fmac_f32_e32 v18, v142, v19
	v_max_f32_e32 v19, 0, v20
	v_fmac_f32_e32 v18, v141, v19
	v_max_f32_e32 v19, 0, v21
	v_fmac_f32_e32 v18, v140, v19
	v_max_f32_e32 v19, 0, v22
	v_fmac_f32_e32 v18, v139, v19
	v_max_f32_e32 v19, 0, v23
	v_fmac_f32_e32 v18, v138, v19
	v_max_f32_e32 v19, 0, v24
	v_fmac_f32_e32 v18, v137, v19
	v_max_f32_e32 v19, 0, v25
	v_fmac_f32_e32 v18, v136, v19
	v_max_f32_e32 v19, 0, v26
	v_fmac_f32_e32 v18, v135, v19
	v_max_f32_e32 v19, 0, v27
	v_fmac_f32_e32 v18, v134, v19
	v_max_f32_e32 v19, 0, v28
	v_fmac_f32_e32 v18, v133, v19
	v_max_f32_e32 v19, 0, v29
	v_fmac_f32_e32 v18, v132, v19
	v_max_f32_e32 v19, 0, v30
	v_fmac_f32_e32 v18, v131, v19
	v_max_f32_e32 v19, 0, v31
	v_fmac_f32_e32 v18, v130, v19
	v_max_f32_e32 v19, 0, v32
	v_fmac_f32_e32 v18, v129, v19
	v_max_f32_e32 v19, 0, v33
	v_fmac_f32_e32 v18, v128, v19
	v_ashrrev_i32_e32 v19, 31, v18
	v_bitop3_b32 v18, v19, v18, s8 bitop3:0x36
	v_cndmask_b32_e32 v162, 0, v18, vcc
	s_cmp_lt_u32 s0, 0x240
	s_cbranch_scc1 .Lix_z18
.Lix_b18:
	s_cmp_lt_u32 s0, 0x2a0
	s_cbranch_scc1 .Lix_w18
	s_waitcnt vmcnt(12)
	s_branch .Lix_m18

; #define MFMA(a, b, c) __builtin_amdgcn_mfma_f32_32x32x16_bf16((a), (b), (c), 0, 0, 0)
; DI unsigned ordkey(float f) { const unsigned b = __float_as_uint(f); return b ^ ((unsigned)((int)b >> 31) | 0x80000000u); }
; DI void indexer_phase(const u16* __restrict__ P, unsigned* __restrict__ mask) {
;     ...
;     for (int kb = 0; kb < 64; ++kb) {
;       unsigned u = 0u;
;       if (kb <= kbmax) {
;         f32x16 a;
; #pragma unroll
;         for (int r = 0; r < 16; ++r) a[r] = 0.f;
;         const u16* kp = P + (brow + 32 * kb + r32) * 7808 + 3584 + 8 * hi;
; #pragma unroll
;         for (int s = 0; s < 4; ++s) { const bf16x8 bk = *(const bf16x8*)(kp + 16 * s); a = MFMA(aq[s], bk, a); }
;         float v = 0.f;
; #pragma unroll
;         for (int i = 0; i < 16; ++i) v = fmaf(wv[i], fmaxf(a[i], 0.f), v);
;         u = (32 * kb + r32 <= tme) ? ordkey(v) : 0u;
;       }
;       sc[kb] = u;
.Lix_m18:
	v_cmp_le_i32_e32 vcc, 0x240, v16
	v_mfma_f32_32x32x16_bf16 v[18:33], v[46:49], v[96:99], 0
	v_mfma_f32_32x32x16_bf16 v[18:33], v[42:45], v[100:103], v[18:33]
	v_mfma_f32_32x32x16_bf16 v[18:33], v[38:41], v[104:107], v[18:33]
	v_mfma_f32_32x32x16_bf16 v[18:33], v[34:37], v[108:111], v[18:33]
	s_cmp_lt_u32 s0, 0x2c0
	s_cbranch_scc1 .Lix_np18
	global_load_dwordx4 v[96:99], v[124:125], off
	global_load_dwordx4 v[100:103], v[124:125], off offset:32
	global_load_dwordx4 v[104:107], v[124:125], off offset:64
	global_load_dwordx4 v[108:111], v[124:125], off offset:96
	v_lshl_add_u64 v[124:125], v[124:125], 0, s[22:23]
.Lix_np18:
	s_nop 10
	v_max_f32_e32 v18, 0, v18
	v_max_f32_e32 v19, 0, v19
	v_fma_f32 v18, v143, v18, 0
	v_fmac_f32_e32 v18, v142, v19
	v_max_f32_e32 v19, 0, v20
	v_fmac_f32_e32 v18, v141, v19
	v_max_f32_e32 v19, 0, v21
	v_fmac_f32_e32 v18, v140, v19
	v_max_f32_e32 v19, 0, v22
	v_fmac_f32_e32 v18, v139, v19
	v_max_f32_e32 v19, 0, v23
	v_fmac_f32_e32 v18, v138, v19
	v_max_f32_e32 v19, 0, v24
	v_fmac_f32_e32 v18, v137, v19
	v_max_f32_e32 v19, 0, v25
	v_fmac_f32_e32 v18, v136, v19
	v_max_f32_e32 v19, 0, v26
	v_fmac_f32_e32 v18, v135, v19
	v_max_f32_e32 v19, 0, v27
	v_fmac_f32_e32 v18, v134, v19
	v_max_f32_e32 v19, 0, v28
	v_fmac_f32_e32 v18, v133, v19
	v_max_f32_e32 v19, 0, v29
	v_fmac_f32_e32 v18, v132, v19
	v_max_f32_e32 v19, 0, v30
	v_fmac_f32_e32 v18, v131, v19
	v_max_f32_e32 v19, 0, v31
	v_fmac_f32_e32 v18, v130, v19
	v_max_f32_e32 v19, 0, v32
	v_fmac_f32_e32 v18, v129, v19
	v_max_f32_e32 v19, 0, v33
	v_fmac_f32_e32 v18, v128, v19
	v_ashrrev_i32_e32 v19, 31, v18
	v_bitop3_b32 v18, v19, v18, s8 bitop3:0x36
	v_cndmask_b32_e32 v161, 0, v18, vcc
	s_cmp_lt_u32 s0, 0x260
	s_cbranch_scc1 .Lix_z19
.Lix_b19:
	s_cmp_lt_u32 s0, 0x2c0
	s_cbranch_scc1 .Lix_w19
	s_waitcnt vmcnt(12)
	s_branch .Lix_m19

; #define MFMA(a, b, c) __builtin_amdgcn_mfma_f32_32x32x16_bf16((a), (b), (c), 0, 0, 0)
; DI unsigned ordkey(float f) { const unsigned b = __float_as_uint(f); return b ^ ((unsigned)((int)b >> 31) | 0x80000000u); }
; DI void indexer_phase(const u16* __restrict__ P, unsigned* __restrict__ mask) {
;     ...
;     for (int kb = 0; kb < 64; ++kb) {
;       unsigned u = 0u;
;       if (kb <= kbmax) {
;         f32x16 a;
; #pragma unroll
;         for (int r = 0; r < 16; ++r) a[r] = 0.f;
;         const u16* kp = P + (brow + 32 * kb + r32) * 7808 + 3584 + 8 * hi;
; #pragma unroll
;         for (int s = 0; s < 4; ++s) { const bf16x8 bk = *(const bf16x8*)(kp + 16 * s); a = MFMA(aq[s], bk, a); }
;         float v = 0.f;
; #pragma unroll
;         for (int i = 0; i < 16; ++i) v = fmaf(wv[i], fmaxf(a[i], 0.f), v);
;         u = (32 * kb + r32 <= tme) ? ordkey(v) : 0u;
;       }
;       sc[kb] = u;
.Lix_m19:
	v_cmp_le_i32_e32 vcc, 0x260, v16
	v_mfma_f32_32x32x16_bf16 v[18:33], v[46:49], v[112:115], 0
	v_mfma_f32_32x32x16_bf16 v[18:33], v[42:45], v[116:119], v[18:33]
	v_mfma_f32_32x32x16_bf16 v[18:33], v[38:41], v[120:123], v[18:33]
	v_mfma_f32_32x32x16_bf16 v[18:33], v[34:37], v[12:15], v[18:33]
	s_cmp_lt_u32 s0, 0x2e0
	s_cbranch_scc1 .Lix_np19
	global_load_dwordx4 v[112:115], v[124:125], off
	global_load_dwordx4 v[116:119], v[124:125], off offset:32
	global_load_dwordx4 v[120:123], v[124:125], off offset:64
	global_load_dwordx4 v[12:15], v[124:125], off offset:96
	v_lshl_add_u64 v[124:125], v[124:125], 0, s[22:23]
.Lix_np19:
	s_nop 10
	v_max_f32_e32 v18, 0, v18
	v_max_f32_e32 v19, 0, v19
	v_fma_f32 v18, v143, v18, 0
	v_fmac_f32_e32 v18, v142, v19
	v_max_f32_e32 v19, 0, v20
	v_fmac_f32_e32 v18, v141, v19
	v_max_f32_e32 v19, 0, v21
	v_fmac_f32_e32 v18, v140, v19
	v_max_f32_e32 v19, 0, v22
	v_fmac_f32_e32 v18, v139, v19
	v_max_f32_e32 v19, 0, v23
	v_fmac_f32_e32 v18, v138, v19
	v_max_f32_e32 v19, 0, v24
	v_fmac_f32_e32 v18, v137, v19
	v_max_f32_e32 v19, 0, v25
	v_fmac_f32_e32 v18, v136, v19
	v_max_f32_e32 v19, 0, v26
	v_fmac_f32_e32 v18, v135, v19
	v_max_f32_e32 v19, 0, v27
	v_fmac_f32_e32 v18, v134, v19
	v_max_f32_e32 v19, 0, v28
	v_fmac_f32_e32 v18, v133, v19
	v_max_f32_e32 v19, 0, v29
	v_fmac_f32_e32 v18, v132, v19
	v_max_f32_e32 v19, 0, v30
	v_fmac_f32_e32 v18, v131, v19
	v_max_f32_e32 v19, 0, v31
	v_fmac_f32_e32 v18, v130, v19
	v_max_f32_e32 v19, 0, v32
	v_fmac_f32_e32 v18, v129, v19
	v_max_f32_e32 v19, 0, v33
	v_fmac_f32_e32 v18, v128, v19
	v_ashrrev_i32_e32 v19, 31, v18
	v_bitop3_b32 v18, v19, v18, s8 bitop3:0x36
	v_cndmask_b32_e32 v164, 0, v18, vcc
	s_cmp_lt_u32 s0, 0x280
	s_cbranch_scc1 .Lix_z20
.Lix_b20:
	s_cmp_lt_u32 s0, 0x2e0
	s_cbranch_scc1 .Lix_w20
	s_waitcnt vmcnt(12)
	s_branch .Lix_m20

; #define MFMA(a, b, c) __builtin_amdgcn_mfma_f32_32x32x16_bf16((a), (b), (c), 0, 0, 0)
; DI unsigned ordkey(float f) { const unsigned b = __float_as_uint(f); return b ^ ((unsigned)((int)b >> 31) | 0x80000000u); }
; DI void indexer_phase(const u16* __restrict__ P, unsigned* __restrict__ mask) {
;     ...
;     for (int kb = 0; kb < 64; ++kb) {
;       unsigned u = 0u;
;       if (kb <= kbmax) {
;         f32x16 a;
; #pragma unroll
;         for (int r = 0; r < 16; ++r) a[r] = 0.f;
;         const u16* kp = P + (brow + 32 * kb + r32) * 7808 + 3584 + 8 * hi;
; #pragma unroll
;         for (int s = 0; s < 4; ++s) { const bf16x8 bk = *(const bf16x8*)(kp + 16 * s); a = MFMA(aq[s], bk, a); }
;         float v = 0.f;
; #pragma unroll
;         for (int i = 0; i < 16; ++i) v = fmaf(wv[i], fmaxf(a[i], 0.f), v);
;         u = (32 * kb + r32 <= tme) ? ordkey(v) : 0u;
;       }
;       sc[kb] = u;
.Lix_m20:
	v_cmp_le_i32_e32 vcc, 0x280, v16
	v_mfma_f32_32x32x16_bf16 v[18:33], v[46:49], v[64:67], 0
	v_mfma_f32_32x32x16_bf16 v[18:33], v[42:45], v[68:71], v[18:33]
	v_mfma_f32_32x32x16_bf16 v[18:33], v[38:41], v[72:75], v[18:33]
	v_mfma_f32_32x32x16_bf16 v[18:33], v[34:37], v[76:79], v[18:33]
	s_cmp_lt_u32 s0, 0x300
	s_cbranch_scc1 .Lix_np20
	global_load_dwordx4 v[64:67], v[124:125], off
	global_load_dwordx4 v[68:71], v[124:125], off offset:32
	global_load_dwordx4 v[72:75], v[124:125], off offset:64
	global_load_dwordx4 v[76:79], v[124:125], off offset:96
	v_lshl_add_u64 v[124:125], v[124:125], 0, s[22:23]
.Lix_np20:
	s_nop 10
	v_max_f32_e32 v18, 0, v18
	v_max_f32_e32 v19, 0, v19
	v_fma_f32 v18, v143, v18, 0
	v_fmac_f32_e32 v18, v142, v19
	v_max_f32_e32 v19, 0, v20
	v_fmac_f32_e32 v18, v141, v19
	v_max_f32_e32 v19, 0, v21
	v_fmac_f32_e32 v18, v140, v19
	v_max_f32_e32 v19, 0, v22
	v_fmac_f32_e32 v18, v139, v19
	v_max_f32_e32 v19, 0, v23
	v_fmac_f32_e32 v18, v138, v19
	v_max_f32_e32 v19, 0, v24
	v_fmac_f32_e32 v18, v137, v19
	v_max_f32_e32 v19, 0, v25
	v_fmac_f32_e32 v18, v136, v19
	v_max_f32_e32 v19, 0, v26
	v_fmac_f32_e32 v18, v135, v19
	v_max_f32_e32 v19, 0, v27
	v_fmac_f32_e32 v18, v134, v19
	v_max_f32_e32 v19, 0, v28
	v_fmac_f32_e32 v18, v133, v19
	v_max_f32_e32 v19, 0, v29
	v_fmac_f32_e32 v18, v132, v19
	v_max_f32_e32 v19, 0, v30
	v_fmac_f32_e32 v18, v131, v19
	v_max_f32_e32 v19, 0, v31
	v_fmac_f32_e32 v18, v130, v19
	v_max_f32_e32 v19, 0, v32
	v_fmac_f32_e32 v18, v129, v19
	v_max_f32_e32 v19, 0, v33
	v_fmac_f32_e32 v18, v128, v19
	v_ashrrev_i32_e32 v19, 31, v18
	v_bitop3_b32 v18, v19, v18, s8 bitop3:0x36
	v_cndmask_b32_e32 v163, 0, v18, vcc
	s_cmp_lt_u32 s0, 0x2a0
	s_cbranch_scc1 .Lix_z21
.Lix_b21:
	s_cmp_lt_u32 s0, 0x300
	s_cbranch_scc1 .Lix_w21
	s_waitcnt vmcnt(12)
	s_branch .Lix_m21

; #define MFMA(a, b, c) __builtin_amdgcn_mfma_f32_32x32x16_bf16((a), (b), (c), 0, 0, 0)
; DI unsigned ordkey(float f) { const unsigned b = __float_as_uint(f); return b ^ ((unsigned)((int)b >> 31) | 0x80000000u); }
; DI void indexer_phase(const u16* __restrict__ P, unsigned* __restrict__ mask) {
;     ...
;     for (int kb = 0; kb < 64; ++kb) {
;       unsigned u = 0u;
;       if (kb <= kbmax) {
;         f32x16 a;
; #pragma unroll
;         for (int r = 0; r < 16; ++r) a[r] = 0.f;
;         const u16* kp = P + (brow + 32 * kb + r32) * 7808 + 3584 + 8 * hi;
; #pragma unroll
;         for (int s = 0; s < 4; ++s) { const bf16x8 bk = *(const bf16x8*)(kp + 16 * s); a = MFMA(aq[s], bk, a); }
;         float v = 0.f;
; #pragma unroll
;         for (int i = 0; i < 16; ++i) v = fmaf(wv[i], fmaxf(a[i], 0.f), v);
;         u = (32 * kb + r32 <= tme) ? ordkey(v) : 0u;
;       }
;       sc[kb] = u;
.Lix_m21:
	v_cmp_le_i32_e32 vcc, 0x2a0, v16
	v_mfma_f32_32x32x16_bf16 v[18:33], v[46:49], v[80:83], 0
	v_mfma_f32_32x32x16_bf16 v[18:33], v[42:45], v[84:87], v[18:33]
	v_mfma_f32_32x32x16_bf16 v[18:33], v[38:41], v[88:91], v[18:33]
	v_mfma_f32_32x32x16_bf16 v[18:33], v[34:37], v[92:95], v[18:33]
	s_cmp_lt_u32 s0, 0x320
	s_cbranch_scc1 .Lix_np21
	global_load_dwordx4 v[80:83], v[124:125], off
	global_load_dwordx4 v[84:87], v[124:125], off offset:32
	global_load_dwordx4 v[88:91], v[124:125], off offset:64
	global_load_dwordx4 v[92:95], v[124:125], off offset:96
	v_lshl_add_u64 v[124:125], v[124:125], 0, s[22:23]
.Lix_np21:
	s_nop 10
	v_max_f32_e32 v18, 0, v18
	v_max_f32_e32 v19, 0, v19
	v_fma_f32 v18, v143, v18, 0
	v_fmac_f32_e32 v18, v142, v19
	v_max_f32_e32 v19, 0, v20
	v_fmac_f32_e32 v18, v141, v19
	v_max_f32_e32 v19, 0, v21
	v_fmac_f32_e32 v18, v140, v19
	v_max_f32_e32 v19, 0, v22
	v_fmac_f32_e32 v18, v139, v19
	v_max_f32_e32 v19, 0, v23
	v_fmac_f32_e32 v18, v138, v19
	v_max_f32_e32 v19, 0, v24
	v_fmac_f32_e32 v18, v137, v19
	v_max_f32_e32 v19, 0, v25
	v_fmac_f32_e32 v18, v136, v19
	v_max_f32_e32 v19, 0, v26
	v_fmac_f32_e32 v18, v135, v19
	v_max_f32_e32 v19, 0, v27
	v_fmac_f32_e32 v18, v134, v19
	v_max_f32_e32 v19, 0, v28
	v_fmac_f32_e32 v18, v133, v19
	v_max_f32_e32 v19, 0, v29
	v_fmac_f32_e32 v18, v132, v19
	v_max_f32_e32 v19, 0, v30
	v_fmac_f32_e32 v18, v131, v19
	v_max_f32_e32 v19, 0, v31
	v_fmac_f32_e32 v18, v130, v19
	v_max_f32_e32 v19, 0, v32
	v_fmac_f32_e32 v18, v129, v19
	v_max_f32_e32 v19, 0, v33
	v_fmac_f32_e32 v18, v128, v19
	v_ashrrev_i32_e32 v19, 31, v18
	v_bitop3_b32 v18, v19, v18, s8 bitop3:0x36
	v_cndmask_b32_e32 v166, 0, v18, vcc
	s_cmp_lt_u32 s0, 0x2c0
	s_cbranch_scc1 .Lix_z22
.Lix_b22:
	s_cmp_lt_u32 s0, 0x320
	s_cbranch_scc1 .Lix_w22
	s_waitcnt vmcnt(12)
	s_branch .Lix_m22

; #define MFMA(a, b, c) __builtin_amdgcn_mfma_f32_32x32x16_bf16((a), (b), (c), 0, 0, 0)
; DI unsigned ordkey(float f) { const unsigned b = __float_as_uint(f); return b ^ ((unsigned)((int)b >> 31) | 0x80000000u); }
; DI void indexer_phase(const u16* __restrict__ P, unsigned* __restrict__ mask) {
;     ...
;     for (int kb = 0; kb < 64; ++kb) {
;       unsigned u = 0u;
;       if (kb <= kbmax) {
;         f32x16 a;
; #pragma unroll
;         for (int r = 0; r < 16; ++r) a[r] = 0.f;
;         const u16* kp = P + (brow + 32 * kb + r32) * 7808 + 3584 + 8 * hi;
; #pragma unroll
;         for (int s = 0; s < 4; ++s) { const bf16x8 bk = *(const bf16x8*)(kp + 16 * s); a = MFMA(aq[s], bk, a); }
;         float v = 0.f;
; #pragma unroll
;         for (int i = 0; i < 16; ++i) v = fmaf(wv[i], fmaxf(a[i], 0.f), v);
;         u = (32 * kb + r32 <= tme) ? ordkey(v) : 0u;
;       }
;       sc[kb] = u;
.Lix_m22:
	v_cmp_le_i32_e32 vcc, 0x2c0, v16
	v_mfma_f32_32x32x16_bf16 v[18:33], v[46:49], v[96:99], 0
	v_mfma_f32_32x32x16_bf16 v[18:33], v[42:45], v[100:103], v[18:33]
	v_mfma_f32_32x32x16_bf16 v[18:33], v[38:41], v[104:107], v[18:33]
	v_mfma_f32_32x32x16_bf16 v[18:33], v[34:37], v[108:111], v[18:33]
	s_cmp_lt_u32 s0, 0x340
	s_cbranch_scc1 .Lix_np22
	global_load_dwordx4 v[96:99], v[124:125], off
	global_load_dwordx4 v[100:103], v[124:125], off offset:32
	global_load_dwordx4 v[104:107], v[124:125], off offset:64
	global_load_dwordx4 v[108:111], v[124:125], off offset:96
	v_lshl_add_u64 v[124:125], v[124:125], 0, s[22:23]
.Lix_np22:
	s_nop 10
	v_max_f32_e32 v18, 0, v18
	v_max_f32_e32 v19, 0, v19
	v_fma_f32 v18, v143, v18, 0
	v_fmac_f32_e32 v18, v142, v19
	v_max_f32_e32 v19, 0, v20
	v_fmac_f32_e32 v18, v141, v19
	v_max_f32_e32 v19, 0, v21
	v_fmac_f32_e32 v18, v140, v19
	v_max_f32_e32 v19, 0, v22
	v_fmac_f32_e32 v18, v139, v19
	v_max_f32_e32 v19, 0, v23
	v_fmac_f32_e32 v18, v138, v19
	v_max_f32_e32 v19, 0, v24
	v_fmac_f32_e32 v18, v137, v19
	v_max_f32_e32 v19, 0, v25
	v_fmac_f32_e32 v18, v136, v19
	v_max_f32_e32 v19, 0, v26
	v_fmac_f32_e32 v18, v135, v19
	v_max_f32_e32 v19, 0, v27
	v_fmac_f32_e32 v18, v134, v19
	v_max_f32_e32 v19, 0, v28
	v_fmac_f32_e32 v18, v133, v19
	v_max_f32_e32 v19, 0, v29
	v_fmac_f32_e32 v18, v132, v19
	v_max_f32_e32 v19, 0, v30
	v_fmac_f32_e32 v18, v131, v19
	v_max_f32_e32 v19, 0, v31
	v_fmac_f32_e32 v18, v130, v19
	v_max_f32_e32 v19, 0, v32
	v_fmac_f32_e32 v18, v129, v19
	v_max_f32_e32 v19, 0, v33
	v_fmac_f32_e32 v18, v128, v19
	v_ashrrev_i32_e32 v19, 31, v18
	v_bitop3_b32 v18, v19, v18, s8 bitop3:0x36
	v_cndmask_b32_e32 v165, 0, v18, vcc
	s_cmp_lt_u32 s0, 0x2e0
	s_cbranch_scc1 .Lix_z23
.Lix_b23:
	s_cmp_lt_u32 s0, 0x340
	s_cbranch_scc1 .Lix_w23
	s_waitcnt vmcnt(12)
	s_branch .Lix_m23

; #define MFMA(a, b, c) __builtin_amdgcn_mfma_f32_32x32x16_bf16((a), (b), (c), 0, 0, 0)
; DI unsigned ordkey(float f) { const unsigned b = __float_as_uint(f); return b ^ ((unsigned)((int)b >> 31) | 0x80000000u); }
; DI void indexer_phase(const u16* __restrict__ P, unsigned* __restrict__ mask) {
;     ...
;     for (int kb = 0; kb < 64; ++kb) {
;       unsigned u = 0u;
;       if (kb <= kbmax) {
;         f32x16 a;
; #pragma unroll
;         for (int r = 0; r < 16; ++r) a[r] = 0.f;
;         const u16* kp = P + (brow + 32 * kb + r32) * 7808 + 3584 + 8 * hi;
; #pragma unroll
;         for (int s = 0; s < 4; ++s) { const bf16x8 bk = *(const bf16x8*)(kp + 16 * s); a = MFMA(aq[s], bk, a); }
;         float v = 0.f;
; #pragma unroll
;         for (int i = 0; i < 16; ++i) v = fmaf(wv[i], fmaxf(a[i], 0.f), v);
;         u = (32 * kb + r32 <= tme) ? ordkey(v) : 0u;
;       }
;       sc[kb] = u;
.Lix_m23:
	v_cmp_le_i32_e32 vcc, 0x2e0, v16
	v_mfma_f32_32x32x16_bf16 v[18:33], v[46:49], v[112:115], 0
	v_mfma_f32_32x32x16_bf16 v[18:33], v[42:45], v[116:119], v[18:33]
	v_mfma_f32_32x32x16_bf16 v[18:33], v[38:41], v[120:123], v[18:33]
	v_mfma_f32_32x32x16_bf16 v[18:33], v[34:37], v[12:15], v[18:33]
	s_cmp_lt_u32 s0, 0x360
	s_cbranch_scc1 .Lix_np23
	global_load_dwordx4 v[112:115], v[124:125], off
	global_load_dwordx4 v[116:119], v[124:125], off offset:32
	global_load_dwordx4 v[120:123], v[124:125], off offset:64
	global_load_dwordx4 v[12:15], v[124:125], off offset:96
	v_lshl_add_u64 v[124:125], v[124:125], 0, s[22:23]
.Lix_np23:
	s_nop 10
	v_max_f32_e32 v18, 0, v18
	v_max_f32_e32 v19, 0, v19
	v_fma_f32 v18, v143, v18, 0
	v_fmac_f32_e32 v18, v142, v19
	v_max_f32_e32 v19, 0, v20
	v_fmac_f32_e32 v18, v141, v19
	v_max_f32_e32 v19, 0, v21
	v_fmac_f32_e32 v18, v140, v19
	v_max_f32_e32 v19, 0, v22
	v_fmac_f32_e32 v18, v139, v19
	v_max_f32_e32 v19, 0, v23
	v_fmac_f32_e32 v18, v138, v19
	v_max_f32_e32 v19, 0, v24
	v_fmac_f32_e32 v18, v137, v19
	v_max_f32_e32 v19, 0, v25
	v_fmac_f32_e32 v18, v136, v19
	v_max_f32_e32 v19, 0, v26
	v_fmac_f32_e32 v18, v135, v19
	v_max_f32_e32 v19, 0, v27
	v_fmac_f32_e32 v18, v134, v19
	v_max_f32_e32 v19, 0, v28
	v_fmac_f32_e32 v18, v133, v19
	v_max_f32_e32 v19, 0, v29
	v_fmac_f32_e32 v18, v132, v19
	v_max_f32_e32 v19, 0, v30
	v_fmac_f32_e32 v18, v131, v19
	v_max_f32_e32 v19, 0, v31
	v_fmac_f32_e32 v18, v130, v19
	v_max_f32_e32 v19, 0, v32
	v_fmac_f32_e32 v18, v129, v19
	v_max_f32_e32 v19, 0, v33
	v_fmac_f32_e32 v18, v128, v19
	v_ashrrev_i32_e32 v19, 31, v18
	v_bitop3_b32 v18, v19, v18, s8 bitop3:0x36
	v_cndmask_b32_e32 v168, 0, v18, vcc
	s_cmp_lt_u32 s0, 0x300
	s_cbranch_scc1 .Lix_z24
.Lix_b24:
	s_cmp_lt_u32 s0, 0x360
	s_cbranch_scc1 .Lix_w24
	s_waitcnt vmcnt(12)
	s_branch .Lix_m24

; #define MFMA(a, b, c) __builtin_amdgcn_mfma_f32_32x32x16_bf16((a), (b), (c), 0, 0, 0)
; DI unsigned ordkey(float f) { const unsigned b = __float_as_uint(f); return b ^ ((unsigned)((int)b >> 31) | 0x80000000u); }
; DI void indexer_phase(const u16* __restrict__ P, unsigned* __restrict__ mask) {
;     ...
;     for (int kb = 0; kb < 64; ++kb) {
;       unsigned u = 0u;
;       if (kb <= kbmax) {
;         f32x16 a;
; #pragma unroll
;         for (int r = 0; r < 16; ++r) a[r] = 0.f;
;         const u16* kp = P + (brow + 32 * kb + r32) * 7808 + 3584 + 8 * hi;
; #pragma unroll
;         for (int s = 0; s < 4; ++s) { const bf16x8 bk = *(const bf16x8*)(kp + 16 * s); a = MFMA(aq[s], bk, a); }
;         float v = 0.f;
; #pragma unroll
;         for (int i = 0; i < 16; ++i) v = fmaf(wv[i], fmaxf(a[i], 0.f), v);
;         u = (32 * kb + r32 <= tme) ? ordkey(v) : 0u;
;       }
;       sc[kb] = u;
.Lix_m24:
	v_cmp_le_i32_e32 vcc, 0x300, v16
	v_mfma_f32_32x32x16_bf16 v[18:33], v[46:49], v[64:67], 0
	v_mfma_f32_32x32x16_bf16 v[18:33], v[42:45], v[68:71], v[18:33]
	v_mfma_f32_32x32x16_bf16 v[18:33], v[38:41], v[72:75], v[18:33]
	v_mfma_f32_32x32x16_bf16 v[18:33], v[34:37], v[76:79], v[18:33]
	s_cmp_lt_u32 s0, 0x380
	s_cbranch_scc1 .Lix_np24
	global_load_dwordx4 v[64:67], v[124:125], off
	global_load_dwordx4 v[68:71], v[124:125], off offset:32
	global_load_dwordx4 v[72:75], v[124:125], off offset:64
	global_load_dwordx4 v[76:79], v[124:125], off offset:96
	v_lshl_add_u64 v[124:125], v[124:125], 0, s[22:23]
.Lix_np24:
	s_nop 10
	v_max_f32_e32 v18, 0, v18
	v_max_f32_e32 v19, 0, v19
	v_fma_f32 v18, v143, v18, 0
	v_fmac_f32_e32 v18, v142, v19
	v_max_f32_e32 v19, 0, v20
	v_fmac_f32_e32 v18, v141, v19
	v_max_f32_e32 v19, 0, v21
	v_fmac_f32_e32 v18, v140, v19
	v_max_f32_e32 v19, 0, v22
	v_fmac_f32_e32 v18, v139, v19
	v_max_f32_e32 v19, 0, v23
	v_fmac_f32_e32 v18, v138, v19
	v_max_f32_e32 v19, 0, v24
	v_fmac_f32_e32 v18, v137, v19
	v_max_f32_e32 v19, 0, v25
	v_fmac_f32_e32 v18, v136, v19
	v_max_f32_e32 v19, 0, v26
	v_fmac_f32_e32 v18, v135, v19
	v_max_f32_e32 v19, 0, v27
	v_fmac_f32_e32 v18, v134, v19
	v_max_f32_e32 v19, 0, v28
	v_fmac_f32_e32 v18, v133, v19
	v_max_f32_e32 v19, 0, v29
	v_fmac_f32_e32 v18, v132, v19
	v_max_f32_e32 v19, 0, v30
	v_fmac_f32_e32 v18, v131, v19
	v_max_f32_e32 v19, 0, v31
	v_fmac_f32_e32 v18, v130, v19
	v_max_f32_e32 v19, 0, v32
	v_fmac_f32_e32 v18, v129, v19
	v_max_f32_e32 v19, 0, v33
	v_fmac_f32_e32 v18, v128, v19
	v_ashrrev_i32_e32 v19, 31, v18
	v_bitop3_b32 v18, v19, v18, s8 bitop3:0x36
	v_cndmask_b32_e32 v167, 0, v18, vcc
	s_cmp_lt_u32 s0, 0x320
	s_cbranch_scc1 .Lix_z25
.Lix_b25:
	s_cmp_lt_u32 s0, 0x380
	s_cbranch_scc1 .Lix_w25
	s_waitcnt vmcnt(12)
	s_branch .Lix_m25

; #define MFMA(a, b, c) __builtin_amdgcn_mfma_f32_32x32x16_bf16((a), (b), (c), 0, 0, 0)
; DI unsigned ordkey(float f) { const unsigned b = __float_as_uint(f); return b ^ ((unsigned)((int)b >> 31) | 0x80000000u); }
; DI void indexer_phase(const u16* __restrict__ P, unsigned* __restrict__ mask) {
;     ...
;     for (int kb = 0; kb < 64; ++kb) {
;       unsigned u = 0u;
;       if (kb <= kbmax) {
;         f32x16 a;
; #pragma unroll
;         for (int r = 0; r < 16; ++r) a[r] = 0.f;
;         const u16* kp = P + (brow + 32 * kb + r32) * 7808 + 3584 + 8 * hi;
; #pragma unroll
;         for (int s = 0; s < 4; ++s) { const bf16x8 bk = *(const bf16x8*)(kp + 16 * s); a = MFMA(aq[s], bk, a); }
;         float v = 0.f;
; #pragma unroll
;         for (int i = 0; i < 16; ++i) v = fmaf(wv[i], fmaxf(a[i], 0.f), v);
;         u = (32 * kb + r32 <= tme) ? ordkey(v) : 0u;
;       }
;       sc[kb] = u;
.Lix_m25:
	v_cmp_le_i32_e32 vcc, 0x320, v16
	v_mfma_f32_32x32x16_bf16 v[18:33], v[46:49], v[80:83], 0
	v_mfma_f32_32x32x16_bf16 v[18:33], v[42:45], v[84:87], v[18:33]
	v_mfma_f32_32x32x16_bf16 v[18:33], v[38:41], v[88:91], v[18:33]
	v_mfma_f32_32x32x16_bf16 v[18:33], v[34:37], v[92:95], v[18:33]
	s_cmp_lt_u32 s0, 0x3a0
	s_cbranch_scc1 .Lix_np25
	global_load_dwordx4 v[80:83], v[124:125], off
	global_load_dwordx4 v[84:87], v[124:125], off offset:32
	global_load_dwordx4 v[88:91], v[124:125], off offset:64
	global_load_dwordx4 v[92:95], v[124:125], off offset:96
	v_lshl_add_u64 v[124:125], v[124:125], 0, s[22:23]
.Lix_np25:
	s_nop 10
	v_max_f32_e32 v18, 0, v18
	v_max_f32_e32 v19, 0, v19
	v_fma_f32 v18, v143, v18, 0
	v_fmac_f32_e32 v18, v142, v19
	v_max_f32_e32 v19, 0, v20
	v_fmac_f32_e32 v18, v141, v19
	v_max_f32_e32 v19, 0, v21
	v_fmac_f32_e32 v18, v140, v19
	v_max_f32_e32 v19, 0, v22
	v_fmac_f32_e32 v18, v139, v19
	v_max_f32_e32 v19, 0, v23
	v_fmac_f32_e32 v18, v138, v19
	v_max_f32_e32 v19, 0, v24
	v_fmac_f32_e32 v18, v137, v19
	v_max_f32_e32 v19, 0, v25
	v_fmac_f32_e32 v18, v136, v19
	v_max_f32_e32 v19, 0, v26
	v_fmac_f32_e32 v18, v135, v19
	v_max_f32_e32 v19, 0, v27
	v_fmac_f32_e32 v18, v134, v19
	v_max_f32_e32 v19, 0, v28
	v_fmac_f32_e32 v18, v133, v19
	v_max_f32_e32 v19, 0, v29
	v_fmac_f32_e32 v18, v132, v19
	v_max_f32_e32 v19, 0, v30
	v_fmac_f32_e32 v18, v131, v19
	v_max_f32_e32 v19, 0, v31
	v_fmac_f32_e32 v18, v130, v19
	v_max_f32_e32 v19, 0, v32
	v_fmac_f32_e32 v18, v129, v19
	v_max_f32_e32 v19, 0, v33
	v_fmac_f32_e32 v18, v128, v19
	v_ashrrev_i32_e32 v19, 31, v18
	v_bitop3_b32 v18, v19, v18, s8 bitop3:0x36
	v_cndmask_b32_e32 v170, 0, v18, vcc
	s_cmp_lt_u32 s0, 0x340
	s_cbranch_scc1 .Lix_z26
.Lix_b26:
	s_cmp_lt_u32 s0, 0x3a0
	s_cbranch_scc1 .Lix_w26
	s_waitcnt vmcnt(12)
	s_branch .Lix_m26

; #define MFMA(a, b, c) __builtin_amdgcn_mfma_f32_32x32x16_bf16((a), (b), (c), 0, 0, 0)
; DI unsigned ordkey(float f) { const unsigned b = __float_as_uint(f); return b ^ ((unsigned)((int)b >> 31) | 0x80000000u); }
; DI void indexer_phase(const u16* __restrict__ P, unsigned* __restrict__ mask) {
;     ...
;     for (int kb = 0; kb < 64; ++kb) {
;       unsigned u = 0u;
;       if (kb <= kbmax) {
;         f32x16 a;
; #pragma unroll
;         for (int r = 0; r < 16; ++r) a[r] = 0.f;
;         const u16* kp = P + (brow + 32 * kb + r32) * 7808 + 3584 + 8 * hi;
; #pragma unroll
;         for (int s = 0; s < 4; ++s) { const bf16x8 bk = *(const bf16x8*)(kp + 16 * s); a = MFMA(aq[s], bk, a); }
;         float v = 0.f;
; #pragma unroll
;         for (int i = 0; i < 16; ++i) v = fmaf(wv[i], fmaxf(a[i], 0.f), v);
;         u = (32 * kb + r32 <= tme) ? ordkey(v) : 0u;
;       }
;       sc[kb] = u;
.Lix_m26:
	v_cmp_le_i32_e32 vcc, 0x340, v16
	v_mfma_f32_32x32x16_bf16 v[18:33], v[46:49], v[96:99], 0
	v_mfma_f32_32x32x16_bf16 v[18:33], v[42:45], v[100:103], v[18:33]
	v_mfma_f32_32x32x16_bf16 v[18:33], v[38:41], v[104:107], v[18:33]
	v_mfma_f32_32x32x16_bf16 v[18:33], v[34:37], v[108:111], v[18:33]
	s_cmp_lt_u32 s0, 0x3c0
	s_cbranch_scc1 .Lix_np26
	global_load_dwordx4 v[96:99], v[124:125], off
	global_load_dwordx4 v[100:103], v[124:125], off offset:32
	global_load_dwordx4 v[104:107], v[124:125], off offset:64
	global_load_dwordx4 v[108:111], v[124:125], off offset:96
	v_lshl_add_u64 v[124:125], v[124:125], 0, s[22:23]
.Lix_np26:
	s_nop 10
	v_max_f32_e32 v18, 0, v18
	v_max_f32_e32 v19, 0, v19
	v_fma_f32 v18, v143, v18, 0
	v_fmac_f32_e32 v18, v142, v19
	v_max_f32_e32 v19, 0, v20
	v_fmac_f32_e32 v18, v141, v19
	v_max_f32_e32 v19, 0, v21
	v_fmac_f32_e32 v18, v140, v19
	v_max_f32_e32 v19, 0, v22
	v_fmac_f32_e32 v18, v139, v19
	v_max_f32_e32 v19, 0, v23
	v_fmac_f32_e32 v18, v138, v19
	v_max_f32_e32 v19, 0, v24
	v_fmac_f32_e32 v18, v137, v19
	v_max_f32_e32 v19, 0, v25
	v_fmac_f32_e32 v18, v136, v19
	v_max_f32_e32 v19, 0, v26
	v_fmac_f32_e32 v18, v135, v19
	v_max_f32_e32 v19, 0, v27
	v_fmac_f32_e32 v18, v134, v19
	v_max_f32_e32 v19, 0, v28
	v_fmac_f32_e32 v18, v133, v19
	v_max_f32_e32 v19, 0, v29
	v_fmac_f32_e32 v18, v132, v19
	v_max_f32_e32 v19, 0, v30
	v_fmac_f32_e32 v18, v131, v19
	v_max_f32_e32 v19, 0, v31
	v_fmac_f32_e32 v18, v130, v19
	v_max_f32_e32 v19, 0, v32
	v_fmac_f32_e32 v18, v129, v19
	v_max_f32_e32 v19, 0, v33
	v_fmac_f32_e32 v18, v128, v19
	v_ashrrev_i32_e32 v19, 31, v18
	v_bitop3_b32 v18, v19, v18, s8 bitop3:0x36
	v_cndmask_b32_e32 v169, 0, v18, vcc
	s_cmp_lt_u32 s0, 0x360
	s_cbranch_scc1 .Lix_z27
.Lix_b27:
	s_cmp_lt_u32 s0, 0x3c0
	s_cbranch_scc1 .Lix_w27
	s_waitcnt vmcnt(12)
	s_branch .Lix_m27

; #define MFMA(a, b, c) __builtin_amdgcn_mfma_f32_32x32x16_bf16((a), (b), (c), 0, 0, 0)
; DI unsigned ordkey(float f) { const unsigned b = __float_as_uint(f); return b ^ ((unsigned)((int)b >> 31) | 0x80000000u); }
; DI void indexer_phase(const u16* __restrict__ P, unsigned* __restrict__ mask) {
;     ...
;     for (int kb = 0; kb < 64; ++kb) {
;       unsigned u = 0u;
;       if (kb <= kbmax) {
;         f32x16 a;
; #pragma unroll
;         for (int r = 0; r < 16; ++r) a[r] = 0.f;
;         const u16* kp = P + (brow + 32 * kb + r32) * 7808 + 3584 + 8 * hi;
; #pragma unroll
;         for (int s = 0; s < 4; ++s) { const bf16x8 bk = *(const bf16x8*)(kp + 16 * s); a = MFMA(aq[s], bk, a); }
;         float v = 0.f;
; #pragma unroll
;         for (int i = 0; i < 16; ++i) v = fmaf(wv[i], fmaxf(a[i], 0.f), v);
;         u = (32 * kb + r32 <= tme) ? ordkey(v) : 0u;
;       }
;       sc[kb] = u;
.Lix_m27:
	v_cmp_le_i32_e32 vcc, 0x360, v16
	v_mfma_f32_32x32x16_bf16 v[18:33], v[46:49], v[112:115], 0
	v_mfma_f32_32x32x16_bf16 v[18:33], v[42:45], v[116:119], v[18:33]
	v_mfma_f32_32x32x16_bf16 v[18:33], v[38:41], v[120:123], v[18:33]
	v_mfma_f32_32x32x16_bf16 v[18:33], v[34:37], v[12:15], v[18:33]
	s_cmp_lt_u32 s0, 0x3e0
	s_cbranch_scc1 .Lix_np27
	global_load_dwordx4 v[112:115], v[124:125], off
	global_load_dwordx4 v[116:119], v[124:125], off offset:32
	global_load_dwordx4 v[120:123], v[124:125], off offset:64
	global_load_dwordx4 v[12:15], v[124:125], off offset:96
	v_lshl_add_u64 v[124:125], v[124:125], 0, s[22:23]
.Lix_np27:
	s_nop 10
	v_max_f32_e32 v18, 0, v18
	v_max_f32_e32 v19, 0, v19
	v_fma_f32 v18, v143, v18, 0
	v_fmac_f32_e32 v18, v142, v19
	v_max_f32_e32 v19, 0, v20
	v_fmac_f32_e32 v18, v141, v19
	v_max_f32_e32 v19, 0, v21
	v_fmac_f32_e32 v18, v140, v19
	v_max_f32_e32 v19, 0, v22
	v_fmac_f32_e32 v18, v139, v19
	v_max_f32_e32 v19, 0, v23
	v_fmac_f32_e32 v18, v138, v19
	v_max_f32_e32 v19, 0, v24
	v_fmac_f32_e32 v18, v137, v19
	v_max_f32_e32 v19, 0, v25
	v_fmac_f32_e32 v18, v136, v19
	v_max_f32_e32 v19, 0, v26
	v_fmac_f32_e32 v18, v135, v19
	v_max_f32_e32 v19, 0, v27
	v_fmac_f32_e32 v18, v134, v19
	v_max_f32_e32 v19, 0, v28
	v_fmac_f32_e32 v18, v133, v19
	v_max_f32_e32 v19, 0, v29
	v_fmac_f32_e32 v18, v132, v19
	v_max_f32_e32 v19, 0, v30
	v_fmac_f32_e32 v18, v131, v19
	v_max_f32_e32 v19, 0, v31
	v_fmac_f32_e32 v18, v130, v19
	v_max_f32_e32 v19, 0, v32
	v_fmac_f32_e32 v18, v129, v19
	v_max_f32_e32 v19, 0, v33
	v_fmac_f32_e32 v18, v128, v19
	v_ashrrev_i32_e32 v19, 31, v18
	v_bitop3_b32 v18, v19, v18, s8 bitop3:0x36
	v_cndmask_b32_e32 v172, 0, v18, vcc
	s_cmp_lt_u32 s0, 0x380
	s_cbranch_scc1 .Lix_z28
.Lix_b28:
	s_cmp_lt_u32 s0, 0x3e0
	s_cbranch_scc1 .Lix_w28
	s_waitcnt vmcnt(12)
	s_branch .Lix_m28

; #define MFMA(a, b, c) __builtin_amdgcn_mfma_f32_32x32x16_bf16((a), (b), (c), 0, 0, 0)
; DI unsigned ordkey(float f) { const unsigned b = __float_as_uint(f); return b ^ ((unsigned)((int)b >> 31) | 0x80000000u); }
; DI void indexer_phase(const u16* __restrict__ P, unsigned* __restrict__ mask) {
;     ...
;     for (int kb = 0; kb < 64; ++kb) {
;       unsigned u = 0u;
;       if (kb <= kbmax) {
;         f32x16 a;
; #pragma unroll
;         for (int r = 0; r < 16; ++r) a[r] = 0.f;
;         const u16* kp = P + (brow + 32 * kb + r32) * 7808 + 3584 + 8 * hi;
; #pragma unroll
;         for (int s = 0; s < 4; ++s) { const bf16x8 bk = *(const bf16x8*)(kp + 16 * s); a = MFMA(aq[s], bk, a); }
;         float v = 0.f;
; #pragma unroll
;         for (int i = 0; i < 16; ++i) v = fmaf(wv[i], fmaxf(a[i], 0.f), v);
;         u = (32 * kb + r32 <= tme) ? ordkey(v) : 0u;
;       }
;       sc[kb] = u;
.Lix_m28:
	v_cmp_le_i32_e32 vcc, 0x380, v16
	v_mfma_f32_32x32x16_bf16 v[18:33], v[46:49], v[64:67], 0
	v_mfma_f32_32x32x16_bf16 v[18:33], v[42:45], v[68:71], v[18:33]
	v_mfma_f32_32x32x16_bf16 v[18:33], v[38:41], v[72:75], v[18:33]
	v_mfma_f32_32x32x16_bf16 v[18:33], v[34:37], v[76:79], v[18:33]
	s_cmp_lt_u32 s0, 0x400
	s_cbranch_scc1 .Lix_np28
	global_load_dwordx4 v[64:67], v[124:125], off
	global_load_dwordx4 v[68:71], v[124:125], off offset:32
	global_load_dwordx4 v[72:75], v[124:125], off offset:64
	global_load_dwordx4 v[76:79], v[124:125], off offset:96
	v_lshl_add_u64 v[124:125], v[124:125], 0, s[22:23]
.Lix_np28:
	s_nop 10
	v_max_f32_e32 v18, 0, v18
	v_max_f32_e32 v19, 0, v19
	v_fma_f32 v18, v143, v18, 0
	v_fmac_f32_e32 v18, v142, v19
	v_max_f32_e32 v19, 0, v20
	v_fmac_f32_e32 v18, v141, v19
	v_max_f32_e32 v19, 0, v21
	v_fmac_f32_e32 v18, v140, v19
	v_max_f32_e32 v19, 0, v22
	v_fmac_f32_e32 v18, v139, v19
	v_max_f32_e32 v19, 0, v23
	v_fmac_f32_e32 v18, v138, v19
	v_max_f32_e32 v19, 0, v24
	v_fmac_f32_e32 v18, v137, v19
	v_max_f32_e32 v19, 0, v25
	v_fmac_f32_e32 v18, v136, v19
	v_max_f32_e32 v19, 0, v26
	v_fmac_f32_e32 v18, v135, v19
	v_max_f32_e32 v19, 0, v27
	v_fmac_f32_e32 v18, v134, v19
	v_max_f32_e32 v19, 0, v28
	v_fmac_f32_e32 v18, v133, v19
	v_max_f32_e32 v19, 0, v29
	v_fmac_f32_e32 v18, v132, v19
	v_max_f32_e32 v19, 0, v30
	v_fmac_f32_e32 v18, v131, v19
	v_max_f32_e32 v19, 0, v31
	v_fmac_f32_e32 v18, v130, v19
	v_max_f32_e32 v19, 0, v32
	v_fmac_f32_e32 v18, v129, v19
	v_max_f32_e32 v19, 0, v33
	v_fmac_f32_e32 v18, v128, v19
	v_ashrrev_i32_e32 v19, 31, v18
	v_bitop3_b32 v18, v19, v18, s8 bitop3:0x36
	v_cndmask_b32_e32 v171, 0, v18, vcc
	s_cmp_lt_u32 s0, 0x3a0
	s_cbranch_scc1 .Lix_z29
.Lix_b29:
	s_cmp_lt_u32 s0, 0x400
	s_cbranch_scc1 .Lix_w29
	s_waitcnt vmcnt(12)
	s_branch .Lix_m29

; #define MFMA(a, b, c) __builtin_amdgcn_mfma_f32_32x32x16_bf16((a), (b), (c), 0, 0, 0)
; DI unsigned ordkey(float f) { const unsigned b = __float_as_uint(f); return b ^ ((unsigned)((int)b >> 31) | 0x80000000u); }
; DI void indexer_phase(const u16* __restrict__ P, unsigned* __restrict__ mask) {
;     ...
;     for (int kb = 0; kb < 64; ++kb) {
;       unsigned u = 0u;
;       if (kb <= kbmax) {
;         f32x16 a;
; #pragma unroll
;         for (int r = 0; r < 16; ++r) a[r] = 0.f;
;         const u16* kp = P + (brow + 32 * kb + r32) * 7808 + 3584 + 8 * hi;
; #pragma unroll
;         for (int s = 0; s < 4; ++s) { const bf16x8 bk = *(const bf16x8*)(kp + 16 * s); a = MFMA(aq[s], bk, a); }
;         float v = 0.f;
; #pragma unroll
;         for (int i = 0; i < 16; ++i) v = fmaf(wv[i], fmaxf(a[i], 0.f), v);
;         u = (32 * kb + r32 <= tme) ? ordkey(v) : 0u;
;       }
;       sc[kb] = u;
.Lix_m29:
	v_cmp_le_i32_e32 vcc, 0x3a0, v16
	v_mfma_f32_32x32x16_bf16 v[18:33], v[46:49], v[80:83], 0
	v_mfma_f32_32x32x16_bf16 v[18:33], v[42:45], v[84:87], v[18:33]
	v_mfma_f32_32x32x16_bf16 v[18:33], v[38:41], v[88:91], v[18:33]
	v_mfma_f32_32x32x16_bf16 v[18:33], v[34:37], v[92:95], v[18:33]
	s_cmp_lt_u32 s0, 0x420
	s_cbranch_scc1 .Lix_np29
	global_load_dwordx4 v[80:83], v[124:125], off
	global_load_dwordx4 v[84:87], v[124:125], off offset:32
	global_load_dwordx4 v[88:91], v[124:125], off offset:64
	global_load_dwordx4 v[92:95], v[124:125], off offset:96
	v_lshl_add_u64 v[124:125], v[124:125], 0, s[22:23]
.Lix_np29:
	s_nop 10
	v_max_f32_e32 v18, 0, v18
	v_max_f32_e32 v19, 0, v19
	v_fma_f32 v18, v143, v18, 0
	v_fmac_f32_e32 v18, v142, v19
	v_max_f32_e32 v19, 0, v20
	v_fmac_f32_e32 v18, v141, v19
	v_max_f32_e32 v19, 0, v21
	v_fmac_f32_e32 v18, v140, v19
	v_max_f32_e32 v19, 0, v22
	v_fmac_f32_e32 v18, v139, v19
	v_max_f32_e32 v19, 0, v23
	v_fmac_f32_e32 v18, v138, v19
	v_max_f32_e32 v19, 0, v24
	v_fmac_f32_e32 v18, v137, v19
	v_max_f32_e32 v19, 0, v25
	v_fmac_f32_e32 v18, v136, v19
	v_max_f32_e32 v19, 0, v26
	v_fmac_f32_e32 v18, v135, v19
	v_max_f32_e32 v19, 0, v27
	v_fmac_f32_e32 v18, v134, v19
	v_max_f32_e32 v19, 0, v28
	v_fmac_f32_e32 v18, v133, v19
	v_max_f32_e32 v19, 0, v29
	v_fmac_f32_e32 v18, v132, v19
	v_max_f32_e32 v19, 0, v30
	v_fmac_f32_e32 v18, v131, v19
	v_max_f32_e32 v19, 0, v31
	v_fmac_f32_e32 v18, v130, v19
	v_max_f32_e32 v19, 0, v32
	v_fmac_f32_e32 v18, v129, v19
	v_max_f32_e32 v19, 0, v33
	v_fmac_f32_e32 v18, v128, v19
	v_ashrrev_i32_e32 v19, 31, v18
	v_bitop3_b32 v18, v19, v18, s8 bitop3:0x36
	v_cndmask_b32_e32 v174, 0, v18, vcc
	s_cmp_lt_u32 s0, 0x3c0
	s_cbranch_scc1 .Lix_z30
.Lix_b30:
	s_cmp_lt_u32 s0, 0x420
	s_cbranch_scc1 .Lix_w30
	s_waitcnt vmcnt(12)
	s_branch .Lix_m30

; #define MFMA(a, b, c) __builtin_amdgcn_mfma_f32_32x32x16_bf16((a), (b), (c), 0, 0, 0)
; DI unsigned ordkey(float f) { const unsigned b = __float_as_uint(f); return b ^ ((unsigned)((int)b >> 31) | 0x80000000u); }
; DI void indexer_phase(const u16* __restrict__ P, unsigned* __restrict__ mask) {
;     ...
;     for (int kb = 0; kb < 64; ++kb) {
;       unsigned u = 0u;
;       if (kb <= kbmax) {
;         f32x16 a;
; #pragma unroll
;         for (int r = 0; r < 16; ++r) a[r] = 0.f;
;         const u16* kp = P + (brow + 32 * kb + r32) * 7808 + 3584 + 8 * hi;
; #pragma unroll
;         for (int s = 0; s < 4; ++s) { const bf16x8 bk = *(const bf16x8*)(kp + 16 * s); a = MFMA(aq[s], bk, a); }
;         float v = 0.f;
; #pragma unroll
;         for (int i = 0; i < 16; ++i) v = fmaf(wv[i], fmaxf(a[i], 0.f), v);
;         u = (32 * kb + r32 <= tme) ? ordkey(v) : 0u;
;       }
;       sc[kb] = u;
.Lix_m30:
	v_cmp_le_i32_e32 vcc, 0x3c0, v16
	v_mfma_f32_32x32x16_bf16 v[18:33], v[46:49], v[96:99], 0
	v_mfma_f32_32x32x16_bf16 v[18:33], v[42:45], v[100:103], v[18:33]
	v_mfma_f32_32x32x16_bf16 v[18:33], v[38:41], v[104:107], v[18:33]
	v_mfma_f32_32x32x16_bf16 v[18:33], v[34:37], v[108:111], v[18:33]
	s_cmp_lt_u32 s0, 0x440
	s_cbranch_scc1 .Lix_np30
	global_load_dwordx4 v[96:99], v[124:125], off
	global_load_dwordx4 v[100:103], v[124:125], off offset:32
	global_load_dwordx4 v[104:107], v[124:125], off offset:64
	global_load_dwordx4 v[108:111], v[124:125], off offset:96
	v_lshl_add_u64 v[124:125], v[124:125], 0, s[22:23]
.Lix_np30:
	s_nop 10
	v_max_f32_e32 v18, 0, v18
	v_max_f32_e32 v19, 0, v19
	v_fma_f32 v18, v143, v18, 0
	v_fmac_f32_e32 v18, v142, v19
	v_max_f32_e32 v19, 0, v20
	v_fmac_f32_e32 v18, v141, v19
	v_max_f32_e32 v19, 0, v21
	v_fmac_f32_e32 v18, v140, v19
	v_max_f32_e32 v19, 0, v22
	v_fmac_f32_e32 v18, v139, v19
	v_max_f32_e32 v19, 0, v23
	v_fmac_f32_e32 v18, v138, v19
	v_max_f32_e32 v19, 0, v24
	v_fmac_f32_e32 v18, v137, v19
	v_max_f32_e32 v19, 0, v25
	v_fmac_f32_e32 v18, v136, v19
	v_max_f32_e32 v19, 0, v26
	v_fmac_f32_e32 v18, v135, v19
	v_max_f32_e32 v19, 0, v27
	v_fmac_f32_e32 v18, v134, v19
	v_max_f32_e32 v19, 0, v28
	v_fmac_f32_e32 v18, v133, v19
	v_max_f32_e32 v19, 0, v29
	v_fmac_f32_e32 v18, v132, v19
	v_max_f32_e32 v19, 0, v30
	v_fmac_f32_e32 v18, v131, v19
	v_max_f32_e32 v19, 0, v31
	v_fmac_f32_e32 v18, v130, v19
	v_max_f32_e32 v19, 0, v32
	v_fmac_f32_e32 v18, v129, v19
	v_max_f32_e32 v19, 0, v33
	v_fmac_f32_e32 v18, v128, v19
	v_ashrrev_i32_e32 v19, 31, v18
	v_bitop3_b32 v18, v19, v18, s8 bitop3:0x36
	v_cndmask_b32_e32 v173, 0, v18, vcc
	s_cmp_lt_u32 s0, 0x3e0
	s_cbranch_scc1 .Lix_z31
.Lix_b31:
	s_cmp_lt_u32 s0, 0x440
	s_cbranch_scc1 .Lix_w31
	s_waitcnt vmcnt(12)
	s_branch .Lix_m31

; #define MFMA(a, b, c) __builtin_amdgcn_mfma_f32_32x32x16_bf16((a), (b), (c), 0, 0, 0)
; DI unsigned ordkey(float f) { const unsigned b = __float_as_uint(f); return b ^ ((unsigned)((int)b >> 31) | 0x80000000u); }
; DI void indexer_phase(const u16* __restrict__ P, unsigned* __restrict__ mask) {
;     ...
;     for (int kb = 0; kb < 64; ++kb) {
;       unsigned u = 0u;
;       if (kb <= kbmax) {
;         f32x16 a;
; #pragma unroll
;         for (int r = 0; r < 16; ++r) a[r] = 0.f;
;         const u16* kp = P + (brow + 32 * kb + r32) * 7808 + 3584 + 8 * hi;
; #pragma unroll
;         for (int s = 0; s < 4; ++s) { const bf16x8 bk = *(const bf16x8*)(kp + 16 * s); a = MFMA(aq[s], bk, a); }
;         float v = 0.f;
; #pragma unroll
;         for (int i = 0; i < 16; ++i) v = fmaf(wv[i], fmaxf(a[i], 0.f), v);
;         u = (32 * kb + r32 <= tme) ? ordkey(v) : 0u;
;       }
;       sc[kb] = u;
.Lix_m31:
	v_cmp_le_i32_e32 vcc, 0x3e0, v16
	v_mfma_f32_32x32x16_bf16 v[18:33], v[46:49], v[112:115], 0
	v_mfma_f32_32x32x16_bf16 v[18:33], v[42:45], v[116:119], v[18:33]
	v_mfma_f32_32x32x16_bf16 v[18:33], v[38:41], v[120:123], v[18:33]
	v_mfma_f32_32x32x16_bf16 v[18:33], v[34:37], v[12:15], v[18:33]
	s_cmp_lt_u32 s0, 0x460
	s_cbranch_scc1 .Lix_np31
	global_load_dwordx4 v[112:115], v[124:125], off
	global_load_dwordx4 v[116:119], v[124:125], off offset:32
	global_load_dwordx4 v[120:123], v[124:125], off offset:64
	global_load_dwordx4 v[12:15], v[124:125], off offset:96
	v_lshl_add_u64 v[124:125], v[124:125], 0, s[22:23]
.Lix_np31:
	s_nop 10
	v_max_f32_e32 v18, 0, v18
	v_max_f32_e32 v19, 0, v19
	v_fma_f32 v18, v143, v18, 0
	v_fmac_f32_e32 v18, v142, v19
	v_max_f32_e32 v19, 0, v20
	v_fmac_f32_e32 v18, v141, v19
	v_max_f32_e32 v19, 0, v21
	v_fmac_f32_e32 v18, v140, v19
	v_max_f32_e32 v19, 0, v22
	v_fmac_f32_e32 v18, v139, v19
	v_max_f32_e32 v19, 0, v23
	v_fmac_f32_e32 v18, v138, v19
	v_max_f32_e32 v19, 0, v24
	v_fmac_f32_e32 v18, v137, v19
	v_max_f32_e32 v19, 0, v25
	v_fmac_f32_e32 v18, v136, v19
	v_max_f32_e32 v19, 0, v26
	v_fmac_f32_e32 v18, v135, v19
	v_max_f32_e32 v19, 0, v27
	v_fmac_f32_e32 v18, v134, v19
	v_max_f32_e32 v19, 0, v28
	v_fmac_f32_e32 v18, v133, v19
	v_max_f32_e32 v19, 0, v29
	v_fmac_f32_e32 v18, v132, v19
	v_max_f32_e32 v19, 0, v30
	v_fmac_f32_e32 v18, v131, v19
	v_max_f32_e32 v19, 0, v31
	v_fmac_f32_e32 v18, v130, v19
	v_max_f32_e32 v19, 0, v32
	v_fmac_f32_e32 v18, v129, v19
	v_max_f32_e32 v19, 0, v33
	v_fmac_f32_e32 v18, v128, v19
	v_ashrrev_i32_e32 v19, 31, v18
	v_bitop3_b32 v18, v19, v18, s8 bitop3:0x36
	v_cndmask_b32_e32 v182, 0, v18, vcc
	s_cmp_lt_u32 s0, 0x400
	s_cbranch_scc1 .Lix_z32
.Lix_b32:
	s_cmp_lt_u32 s0, 0x460
	s_cbranch_scc1 .Lix_w32
	s_waitcnt vmcnt(12)
	s_branch .Lix_m32

; #define MFMA(a, b, c) __builtin_amdgcn_mfma_f32_32x32x16_bf16((a), (b), (c), 0, 0, 0)
; DI unsigned ordkey(float f) { const unsigned b = __float_as_uint(f); return b ^ ((unsigned)((int)b >> 31) | 0x80000000u); }
; DI void indexer_phase(const u16* __restrict__ P, unsigned* __restrict__ mask) {
;     ...
;     for (int kb = 0; kb < 64; ++kb) {
;       unsigned u = 0u;
;       if (kb <= kbmax) {
;         f32x16 a;
; #pragma unroll
;         for (int r = 0; r < 16; ++r) a[r] = 0.f;
;         const u16* kp = P + (brow + 32 * kb + r32) * 7808 + 3584 + 8 * hi;
; #pragma unroll
;         for (int s = 0; s < 4; ++s) { const bf16x8 bk = *(const bf16x8*)(kp + 16 * s); a = MFMA(aq[s], bk, a); }
;         float v = 0.f;
; #pragma unroll
;         for (int i = 0; i < 16; ++i) v = fmaf(wv[i], fmaxf(a[i], 0.f), v);
;         u = (32 * kb + r32 <= tme) ? ordkey(v) : 0u;
;       }
;       sc[kb] = u;
.Lix_m32:
	v_cmp_le_i32_e32 vcc, 0x400, v16
	v_mfma_f32_32x32x16_bf16 v[18:33], v[46:49], v[64:67], 0
	v_mfma_f32_32x32x16_bf16 v[18:33], v[42:45], v[68:71], v[18:33]
	v_mfma_f32_32x32x16_bf16 v[18:33], v[38:41], v[72:75], v[18:33]
	v_mfma_f32_32x32x16_bf16 v[18:33], v[34:37], v[76:79], v[18:33]
	s_cmp_lt_u32 s0, 0x480
	s_cbranch_scc1 .Lix_np32
	global_load_dwordx4 v[64:67], v[124:125], off
	global_load_dwordx4 v[68:71], v[124:125], off offset:32
	global_load_dwordx4 v[72:75], v[124:125], off offset:64
	global_load_dwordx4 v[76:79], v[124:125], off offset:96
	v_lshl_add_u64 v[124:125], v[124:125], 0, s[22:23]
.Lix_np32:
	s_nop 10
	v_max_f32_e32 v18, 0, v18
	v_max_f32_e32 v19, 0, v19
	v_fma_f32 v18, v143, v18, 0
	v_fmac_f32_e32 v18, v142, v19
	v_max_f32_e32 v19, 0, v20
	v_fmac_f32_e32 v18, v141, v19
	v_max_f32_e32 v19, 0, v21
	v_fmac_f32_e32 v18, v140, v19
	v_max_f32_e32 v19, 0, v22
	v_fmac_f32_e32 v18, v139, v19
	v_max_f32_e32 v19, 0, v23
	v_fmac_f32_e32 v18, v138, v19
	v_max_f32_e32 v19, 0, v24
	v_fmac_f32_e32 v18, v137, v19
	v_max_f32_e32 v19, 0, v25
	v_fmac_f32_e32 v18, v136, v19
	v_max_f32_e32 v19, 0, v26
	v_fmac_f32_e32 v18, v135, v19
	v_max_f32_e32 v19, 0, v27
	v_fmac_f32_e32 v18, v134, v19
	v_max_f32_e32 v19, 0, v28
	v_fmac_f32_e32 v18, v133, v19
	v_max_f32_e32 v19, 0, v29
	v_fmac_f32_e32 v18, v132, v19
	v_max_f32_e32 v19, 0, v30
	v_fmac_f32_e32 v18, v131, v19
	v_max_f32_e32 v19, 0, v31
	v_fmac_f32_e32 v18, v130, v19
	v_max_f32_e32 v19, 0, v32
	v_fmac_f32_e32 v18, v129, v19
	v_max_f32_e32 v19, 0, v33
	v_fmac_f32_e32 v18, v128, v19
	v_ashrrev_i32_e32 v19, 31, v18
	v_bitop3_b32 v18, v19, v18, s8 bitop3:0x36
	v_cndmask_b32_e32 v175, 0, v18, vcc
	s_cmp_lt_u32 s0, 0x420
	s_cbranch_scc1 .Lix_z33
.Lix_b33:
	s_cmp_lt_u32 s0, 0x480
	s_cbranch_scc1 .Lix_w33
	s_waitcnt vmcnt(12)
	s_branch .Lix_m33

; #define MFMA(a, b, c) __builtin_amdgcn_mfma_f32_32x32x16_bf16((a), (b), (c), 0, 0, 0)
; DI unsigned ordkey(float f) { const unsigned b = __float_as_uint(f); return b ^ ((unsigned)((int)b >> 31) | 0x80000000u); }
; DI void indexer_phase(const u16* __restrict__ P, unsigned* __restrict__ mask) {
;     ...
;     for (int kb = 0; kb < 64; ++kb) {
;       unsigned u = 0u;
;       if (kb <= kbmax) {
;         f32x16 a;
; #pragma unroll
;         for (int r = 0; r < 16; ++r) a[r] = 0.f;
;         const u16* kp = P + (brow + 32 * kb + r32) * 7808 + 3584 + 8 * hi;
; #pragma unroll
;         for (int s = 0; s < 4; ++s) { const bf16x8 bk = *(const bf16x8*)(kp + 16 * s); a = MFMA(aq[s], bk, a); }
;         float v = 0.f;
; #pragma unroll
;         for (int i = 0; i < 16; ++i) v = fmaf(wv[i], fmaxf(a[i], 0.f), v);
;         u = (32 * kb + r32 <= tme) ? ordkey(v) : 0u;
;       }
;       sc[kb] = u;
.Lix_m33:
	v_cmp_le_i32_e32 vcc, 0x420, v16
	v_mfma_f32_32x32x16_bf16 v[18:33], v[46:49], v[80:83], 0
	v_mfma_f32_32x32x16_bf16 v[18:33], v[42:45], v[84:87], v[18:33]
	v_mfma_f32_32x32x16_bf16 v[18:33], v[38:41], v[88:91], v[18:33]
	v_mfma_f32_32x32x16_bf16 v[18:33], v[34:37], v[92:95], v[18:33]
	s_cmp_lt_u32 s0, 0x4a0
	s_cbranch_scc1 .Lix_np33
	global_load_dwordx4 v[80:83], v[124:125], off
	global_load_dwordx4 v[84:87], v[124:125], off offset:32
	global_load_dwordx4 v[88:91], v[124:125], off offset:64
	global_load_dwordx4 v[92:95], v[124:125], off offset:96
	v_lshl_add_u64 v[124:125], v[124:125], 0, s[22:23]
.Lix_np33:
	s_nop 10
	v_max_f32_e32 v18, 0, v18
	v_max_f32_e32 v19, 0, v19
	v_fma_f32 v18, v143, v18, 0
	v_fmac_f32_e32 v18, v142, v19
	v_max_f32_e32 v19, 0, v20
	v_fmac_f32_e32 v18, v141, v19
	v_max_f32_e32 v19, 0, v21
	v_fmac_f32_e32 v18, v140, v19
	v_max_f32_e32 v19, 0, v22
	v_fmac_f32_e32 v18, v139, v19
	v_max_f32_e32 v19, 0, v23
	v_fmac_f32_e32 v18, v138, v19
	v_max_f32_e32 v19, 0, v24
	v_fmac_f32_e32 v18, v137, v19
	v_max_f32_e32 v19, 0, v25
	v_fmac_f32_e32 v18, v136, v19
	v_max_f32_e32 v19, 0, v26
	v_fmac_f32_e32 v18, v135, v19
	v_max_f32_e32 v19, 0, v27
	v_fmac_f32_e32 v18, v134, v19
	v_max_f32_e32 v19, 0, v28
	v_fmac_f32_e32 v18, v133, v19
	v_max_f32_e32 v19, 0, v29
	v_fmac_f32_e32 v18, v132, v19
	v_max_f32_e32 v19, 0, v30
	v_fmac_f32_e32 v18, v131, v19
	v_max_f32_e32 v19, 0, v31
	v_fmac_f32_e32 v18, v130, v19
	v_max_f32_e32 v19, 0, v32
	v_fmac_f32_e32 v18, v129, v19
	v_max_f32_e32 v19, 0, v33
	v_fmac_f32_e32 v18, v128, v19
	v_ashrrev_i32_e32 v19, 31, v18
	v_bitop3_b32 v18, v19, v18, s8 bitop3:0x36
	v_cndmask_b32_e32 v184, 0, v18, vcc
	s_cmp_lt_u32 s0, 0x440
	s_cbranch_scc1 .Lix_z34
.Lix_b34:
	s_cmp_lt_u32 s0, 0x4a0
	s_cbranch_scc1 .Lix_w34
	s_waitcnt vmcnt(12)
	s_branch .Lix_m34

; #define MFMA(a, b, c) __builtin_amdgcn_mfma_f32_32x32x16_bf16((a), (b), (c), 0, 0, 0)
; DI unsigned ordkey(float f) { const unsigned b = __float_as_uint(f); return b ^ ((unsigned)((int)b >> 31) | 0x80000000u); }
; DI void indexer_phase(const u16* __restrict__ P, unsigned* __restrict__ mask) {
;     ...
;     for (int kb = 0; kb < 64; ++kb) {
;       unsigned u = 0u;
;       if (kb <= kbmax) {
;         f32x16 a;
; #pragma unroll
;         for (int r = 0; r < 16; ++r) a[r] = 0.f;
;         const u16* kp = P + (brow + 32 * kb + r32) * 7808 + 3584 + 8 * hi;
; #pragma unroll
;         for (int s = 0; s < 4; ++s) { const bf16x8 bk = *(const bf16x8*)(kp + 16 * s); a = MFMA(aq[s], bk, a); }
;         float v = 0.f;
; #pragma unroll
;         for (int i = 0; i < 16; ++i) v = fmaf(wv[i], fmaxf(a[i], 0.f), v);
;         u = (32 * kb + r32 <= tme) ? ordkey(v) : 0u;
;       }
;       sc[kb] = u;
.Lix_m34:
	v_cmp_le_i32_e32 vcc, 0x440, v16
	v_mfma_f32_32x32x16_bf16 v[18:33], v[46:49], v[96:99], 0
	v_mfma_f32_32x32x16_bf16 v[18:33], v[42:45], v[100:103], v[18:33]
	v_mfma_f32_32x32x16_bf16 v[18:33], v[38:41], v[104:107], v[18:33]
	v_mfma_f32_32x32x16_bf16 v[18:33], v[34:37], v[108:111], v[18:33]
	s_cmp_lt_u32 s0, 0x4c0
	s_cbranch_scc1 .Lix_np34
	global_load_dwordx4 v[96:99], v[124:125], off
	global_load_dwordx4 v[100:103], v[124:125], off offset:32
	global_load_dwordx4 v[104:107], v[124:125], off offset:64
	global_load_dwordx4 v[108:111], v[124:125], off offset:96
	v_lshl_add_u64 v[124:125], v[124:125], 0, s[22:23]
.Lix_np34:
	s_nop 10
	v_max_f32_e32 v18, 0, v18
	v_max_f32_e32 v19, 0, v19
	v_fma_f32 v18, v143, v18, 0
	v_fmac_f32_e32 v18, v142, v19
	v_max_f32_e32 v19, 0, v20
	v_fmac_f32_e32 v18, v141, v19
	v_max_f32_e32 v19, 0, v21
	v_fmac_f32_e32 v18, v140, v19
	v_max_f32_e32 v19, 0, v22
	v_fmac_f32_e32 v18, v139, v19
	v_max_f32_e32 v19, 0, v23
	v_fmac_f32_e32 v18, v138, v19
	v_max_f32_e32 v19, 0, v24
	v_fmac_f32_e32 v18, v137, v19
	v_max_f32_e32 v19, 0, v25
	v_fmac_f32_e32 v18, v136, v19
	v_max_f32_e32 v19, 0, v26
	v_fmac_f32_e32 v18, v135, v19
	v_max_f32_e32 v19, 0, v27
	v_fmac_f32_e32 v18, v134, v19
	v_max_f32_e32 v19, 0, v28
	v_fmac_f32_e32 v18, v133, v19
	v_max_f32_e32 v19, 0, v29
	v_fmac_f32_e32 v18, v132, v19
	v_max_f32_e32 v19, 0, v30
	v_fmac_f32_e32 v18, v131, v19
	v_max_f32_e32 v19, 0, v31
	v_fmac_f32_e32 v18, v130, v19
	v_max_f32_e32 v19, 0, v32
	v_fmac_f32_e32 v18, v129, v19
	v_max_f32_e32 v19, 0, v33
	v_fmac_f32_e32 v18, v128, v19
	v_ashrrev_i32_e32 v19, 31, v18
	v_bitop3_b32 v18, v19, v18, s8 bitop3:0x36
	v_cndmask_b32_e32 v183, 0, v18, vcc
	s_cmp_lt_u32 s0, 0x460
	s_cbranch_scc1 .Lix_z35
.Lix_b35:
	s_cmp_lt_u32 s0, 0x4c0
	s_cbranch_scc1 .Lix_w35
	s_waitcnt vmcnt(12)
	s_branch .Lix_m35

; #define MFMA(a, b, c) __builtin_amdgcn_mfma_f32_32x32x16_bf16((a), (b), (c), 0, 0, 0)
; DI unsigned ordkey(float f) { const unsigned b = __float_as_uint(f); return b ^ ((unsigned)((int)b >> 31) | 0x80000000u); }
; DI void indexer_phase(const u16* __restrict__ P, unsigned* __restrict__ mask) {
;     ...
;     for (int kb = 0; kb < 64; ++kb) {
;       unsigned u = 0u;
;       if (kb <= kbmax) {
;         f32x16 a;
; #pragma unroll
;         for (int r = 0; r < 16; ++r) a[r] = 0.f;
;         const u16* kp = P + (brow + 32 * kb + r32) * 7808 + 3584 + 8 * hi;
; #pragma unroll
;         for (int s = 0; s < 4; ++s) { const bf16x8 bk = *(const bf16x8*)(kp + 16 * s); a = MFMA(aq[s], bk, a); }
;         float v = 0.f;
; #pragma unroll
;         for (int i = 0; i < 16; ++i) v = fmaf(wv[i], fmaxf(a[i], 0.f), v);
;         u = (32 * kb + r32 <= tme) ? ordkey(v) : 0u;
;       }
;       sc[kb] = u;
.Lix_m35:
	v_cmp_le_i32_e32 vcc, 0x460, v16
	v_mfma_f32_32x32x16_bf16 v[18:33], v[46:49], v[112:115], 0
	v_mfma_f32_32x32x16_bf16 v[18:33], v[42:45], v[116:119], v[18:33]
	v_mfma_f32_32x32x16_bf16 v[18:33], v[38:41], v[120:123], v[18:33]
	v_mfma_f32_32x32x16_bf16 v[18:33], v[34:37], v[12:15], v[18:33]
	s_cmp_lt_u32 s0, 0x4e0
	s_cbranch_scc1 .Lix_np35
	global_load_dwordx4 v[112:115], v[124:125], off
	global_load_dwordx4 v[116:119], v[124:125], off offset:32
	global_load_dwordx4 v[120:123], v[124:125], off offset:64
	global_load_dwordx4 v[12:15], v[124:125], off offset:96
	v_lshl_add_u64 v[124:125], v[124:125], 0, s[22:23]
.Lix_np35:
	s_nop 10
	v_max_f32_e32 v18, 0, v18
	v_max_f32_e32 v19, 0, v19
	v_fma_f32 v18, v143, v18, 0
	v_fmac_f32_e32 v18, v142, v19
	v_max_f32_e32 v19, 0, v20
	v_fmac_f32_e32 v18, v141, v19
	v_max_f32_e32 v19, 0, v21
	v_fmac_f32_e32 v18, v140, v19
	v_max_f32_e32 v19, 0, v22
	v_fmac_f32_e32 v18, v139, v19
	v_max_f32_e32 v19, 0, v23
	v_fmac_f32_e32 v18, v138, v19
	v_max_f32_e32 v19, 0, v24
	v_fmac_f32_e32 v18, v137, v19
	v_max_f32_e32 v19, 0, v25
	v_fmac_f32_e32 v18, v136, v19
	v_max_f32_e32 v19, 0, v26
	v_fmac_f32_e32 v18, v135, v19
	v_max_f32_e32 v19, 0, v27
	v_fmac_f32_e32 v18, v134, v19
	v_max_f32_e32 v19, 0, v28
	v_fmac_f32_e32 v18, v133, v19
	v_max_f32_e32 v19, 0, v29
	v_fmac_f32_e32 v18, v132, v19
	v_max_f32_e32 v19, 0, v30
	v_fmac_f32_e32 v18, v131, v19
	v_max_f32_e32 v19, 0, v31
	v_fmac_f32_e32 v18, v130, v19
	v_max_f32_e32 v19, 0, v32
	v_fmac_f32_e32 v18, v129, v19
	v_max_f32_e32 v19, 0, v33
	v_fmac_f32_e32 v18, v128, v19
	v_ashrrev_i32_e32 v19, 31, v18
	v_bitop3_b32 v18, v19, v18, s8 bitop3:0x36
	v_cndmask_b32_e32 v186, 0, v18, vcc
	s_cmp_lt_u32 s0, 0x480
	s_cbranch_scc1 .Lix_z36
.Lix_b36:
	s_cmp_lt_u32 s0, 0x4e0
	s_cbranch_scc1 .Lix_w36
	s_waitcnt vmcnt(12)
	s_branch .Lix_m36

; #define MFMA(a, b, c) __builtin_amdgcn_mfma_f32_32x32x16_bf16((a), (b), (c), 0, 0, 0)
; DI unsigned ordkey(float f) { const unsigned b = __float_as_uint(f); return b ^ ((unsigned)((int)b >> 31) | 0x80000000u); }
; DI void indexer_phase(const u16* __restrict__ P, unsigned* __restrict__ mask) {
;     ...
;     for (int kb = 0; kb < 64; ++kb) {
;       unsigned u = 0u;
;       if (kb <= kbmax) {
;         f32x16 a;
; #pragma unroll
;         for (int r = 0; r < 16; ++r) a[r] = 0.f;
;         const u16* kp = P + (brow + 32 * kb + r32) * 7808 + 3584 + 8 * hi;
; #pragma unroll
;         for (int s = 0; s < 4; ++s) { const bf16x8 bk = *(const bf16x8*)(kp + 16 * s); a = MFMA(aq[s], bk, a); }
;         float v = 0.f;
; #pragma unroll
;         for (int i = 0; i < 16; ++i) v = fmaf(wv[i], fmaxf(a[i], 0.f), v);
;         u = (32 * kb + r32 <= tme) ? ordkey(v) : 0u;
;       }
;       sc[kb] = u;
.Lix_m36:
	v_cmp_le_i32_e32 vcc, 0x480, v16
	v_mfma_f32_32x32x16_bf16 v[18:33], v[46:49], v[64:67], 0
	v_mfma_f32_32x32x16_bf16 v[18:33], v[42:45], v[68:71], v[18:33]
	v_mfma_f32_32x32x16_bf16 v[18:33], v[38:41], v[72:75], v[18:33]
	v_mfma_f32_32x32x16_bf16 v[18:33], v[34:37], v[76:79], v[18:33]
	s_cmp_lt_u32 s0, 0x500
	s_cbranch_scc1 .Lix_np36
	global_load_dwordx4 v[64:67], v[124:125], off
	global_load_dwordx4 v[68:71], v[124:125], off offset:32
	global_load_dwordx4 v[72:75], v[124:125], off offset:64
	global_load_dwordx4 v[76:79], v[124:125], off offset:96
	v_lshl_add_u64 v[124:125], v[124:125], 0, s[22:23]
.Lix_np36:
	s_nop 10
	v_max_f32_e32 v18, 0, v18
	v_max_f32_e32 v19, 0, v19
	v_fma_f32 v18, v143, v18, 0
	v_fmac_f32_e32 v18, v142, v19
	v_max_f32_e32 v19, 0, v20
	v_fmac_f32_e32 v18, v141, v19
	v_max_f32_e32 v19, 0, v21
	v_fmac_f32_e32 v18, v140, v19
	v_max_f32_e32 v19, 0, v22
	v_fmac_f32_e32 v18, v139, v19
	v_max_f32_e32 v19, 0, v23
	v_fmac_f32_e32 v18, v138, v19
	v_max_f32_e32 v19, 0, v24
	v_fmac_f32_e32 v18, v137, v19
	v_max_f32_e32 v19, 0, v25
	v_fmac_f32_e32 v18, v136, v19
	v_max_f32_e32 v19, 0, v26
	v_fmac_f32_e32 v18, v135, v19
	v_max_f32_e32 v19, 0, v27
	v_fmac_f32_e32 v18, v134, v19
	v_max_f32_e32 v19, 0, v28
	v_fmac_f32_e32 v18, v133, v19
	v_max_f32_e32 v19, 0, v29
	v_fmac_f32_e32 v18, v132, v19
	v_max_f32_e32 v19, 0, v30
	v_fmac_f32_e32 v18, v131, v19
	v_max_f32_e32 v19, 0, v31
	v_fmac_f32_e32 v18, v130, v19
	v_max_f32_e32 v19, 0, v32
	v_fmac_f32_e32 v18, v129, v19
	v_max_f32_e32 v19, 0, v33
	v_fmac_f32_e32 v18, v128, v19
	v_ashrrev_i32_e32 v19, 31, v18
	v_bitop3_b32 v18, v19, v18, s8 bitop3:0x36
	v_cndmask_b32_e32 v185, 0, v18, vcc
	s_cmp_lt_u32 s0, 0x4a0
	s_cbranch_scc1 .Lix_z37
.Lix_b37:
	s_cmp_lt_u32 s0, 0x500
	s_cbranch_scc1 .Lix_w37
	s_waitcnt vmcnt(12)
	s_branch .Lix_m37

; #define MFMA(a, b, c) __builtin_amdgcn_mfma_f32_32x32x16_bf16((a), (b), (c), 0, 0, 0)
; DI unsigned ordkey(float f) { const unsigned b = __float_as_uint(f); return b ^ ((unsigned)((int)b >> 31) | 0x80000000u); }
; DI void indexer_phase(const u16* __restrict__ P, unsigned* __restrict__ mask) {
;     ...
;     for (int kb = 0; kb < 64; ++kb) {
;       unsigned u = 0u;
;       if (kb <= kbmax) {
;         f32x16 a;
; #pragma unroll
;         for (int r = 0; r < 16; ++r) a[r] = 0.f;
;         const u16* kp = P + (brow + 32 * kb + r32) * 7808 + 3584 + 8 * hi;
; #pragma unroll
;         for (int s = 0; s < 4; ++s) { const bf16x8 bk = *(const bf16x8*)(kp + 16 * s); a = MFMA(aq[s], bk, a); }
;         float v = 0.f;
; #pragma unroll
;         for (int i = 0; i < 16; ++i) v = fmaf(wv[i], fmaxf(a[i], 0.f), v);
;         u = (32 * kb + r32 <= tme) ? ordkey(v) : 0u;
;       }
;       sc[kb] = u;
.Lix_m37:
	v_cmp_le_i32_e32 vcc, 0x4a0, v16
	v_mfma_f32_32x32x16_bf16 v[18:33], v[46:49], v[80:83], 0
	v_mfma_f32_32x32x16_bf16 v[18:33], v[42:45], v[84:87], v[18:33]
	v_mfma_f32_32x32x16_bf16 v[18:33], v[38:41], v[88:91], v[18:33]
	v_mfma_f32_32x32x16_bf16 v[18:33], v[34:37], v[92:95], v[18:33]
	s_cmp_lt_u32 s0, 0x520
	s_cbranch_scc1 .Lix_np37
	global_load_dwordx4 v[80:83], v[124:125], off
	global_load_dwordx4 v[84:87], v[124:125], off offset:32
	global_load_dwordx4 v[88:91], v[124:125], off offset:64
	global_load_dwordx4 v[92:95], v[124:125], off offset:96
	v_lshl_add_u64 v[124:125], v[124:125], 0, s[22:23]
.Lix_np37:
	s_nop 10
	v_max_f32_e32 v18, 0, v18
	v_max_f32_e32 v19, 0, v19
	v_fma_f32 v18, v143, v18, 0
	v_fmac_f32_e32 v18, v142, v19
	v_max_f32_e32 v19, 0, v20
	v_fmac_f32_e32 v18, v141, v19
	v_max_f32_e32 v19, 0, v21
	v_fmac_f32_e32 v18, v140, v19
	v_max_f32_e32 v19, 0, v22
	v_fmac_f32_e32 v18, v139, v19
	v_max_f32_e32 v19, 0, v23
	v_fmac_f32_e32 v18, v138, v19
	v_max_f32_e32 v19, 0, v24
	v_fmac_f32_e32 v18, v137, v19
	v_max_f32_e32 v19, 0, v25
	v_fmac_f32_e32 v18, v136, v19
	v_max_f32_e32 v19, 0, v26
	v_fmac_f32_e32 v18, v135, v19
	v_max_f32_e32 v19, 0, v27
	v_fmac_f32_e32 v18, v134, v19
	v_max_f32_e32 v19, 0, v28
	v_fmac_f32_e32 v18, v133, v19
	v_max_f32_e32 v19, 0, v29
	v_fmac_f32_e32 v18, v132, v19
	v_max_f32_e32 v19, 0, v30
	v_fmac_f32_e32 v18, v131, v19
	v_max_f32_e32 v19, 0, v31
	v_fmac_f32_e32 v18, v130, v19
	v_max_f32_e32 v19, 0, v32
	v_fmac_f32_e32 v18, v129, v19
	v_max_f32_e32 v19, 0, v33
	v_fmac_f32_e32 v18, v128, v19
	v_ashrrev_i32_e32 v19, 31, v18
	v_bitop3_b32 v18, v19, v18, s8 bitop3:0x36
	v_cndmask_b32_e32 v188, 0, v18, vcc
	s_cmp_lt_u32 s0, 0x4c0
	s_cbranch_scc1 .Lix_z38
.Lix_b38:
	s_cmp_lt_u32 s0, 0x520
	s_cbranch_scc1 .Lix_w38
	s_waitcnt vmcnt(12)
	s_branch .Lix_m38

; #define MFMA(a, b, c) __builtin_amdgcn_mfma_f32_32x32x16_bf16((a), (b), (c), 0, 0, 0)
; DI unsigned ordkey(float f) { const unsigned b = __float_as_uint(f); return b ^ ((unsigned)((int)b >> 31) | 0x80000000u); }
; DI void indexer_phase(const u16* __restrict__ P, unsigned* __restrict__ mask) {
;     ...
;     for (int kb = 0; kb < 64; ++kb) {
;       unsigned u = 0u;
;       if (kb <= kbmax) {
;         f32x16 a;
; #pragma unroll
;         for (int r = 0; r < 16; ++r) a[r] = 0.f;
;         const u16* kp = P + (brow + 32 * kb + r32) * 7808 + 3584 + 8 * hi;
; #pragma unroll
;         for (int s = 0; s < 4; ++s) { const bf16x8 bk = *(const bf16x8*)(kp + 16 * s); a = MFMA(aq[s], bk, a); }
;         float v = 0.f;
; #pragma unroll
;         for (int i = 0; i < 16; ++i) v = fmaf(wv[i], fmaxf(a[i], 0.f), v);
;         u = (32 * kb + r32 <= tme) ? ordkey(v) : 0u;
;       }
;       sc[kb] = u;
.Lix_m38:
	v_cmp_le_i32_e32 vcc, 0x4c0, v16
	v_mfma_f32_32x32x16_bf16 v[18:33], v[46:49], v[96:99], 0
	v_mfma_f32_32x32x16_bf16 v[18:33], v[42:45], v[100:103], v[18:33]
	v_mfma_f32_32x32x16_bf16 v[18:33], v[38:41], v[104:107], v[18:33]
	v_mfma_f32_32x32x16_bf16 v[18:33], v[34:37], v[108:111], v[18:33]
	s_cmp_lt_u32 s0, 0x540
	s_cbranch_scc1 .Lix_np38
	global_load_dwordx4 v[96:99], v[124:125], off
	global_load_dwordx4 v[100:103], v[124:125], off offset:32
	global_load_dwordx4 v[104:107], v[124:125], off offset:64
	global_load_dwordx4 v[108:111], v[124:125], off offset:96
	v_lshl_add_u64 v[124:125], v[124:125], 0, s[22:23]
.Lix_np38:
	s_nop 10
	v_max_f32_e32 v18, 0, v18
	v_max_f32_e32 v19, 0, v19
	v_fma_f32 v18, v143, v18, 0
	v_fmac_f32_e32 v18, v142, v19
	v_max_f32_e32 v19, 0, v20
	v_fmac_f32_e32 v18, v141, v19
	v_max_f32_e32 v19, 0, v21
	v_fmac_f32_e32 v18, v140, v19
	v_max_f32_e32 v19, 0, v22
	v_fmac_f32_e32 v18, v139, v19
	v_max_f32_e32 v19, 0, v23
	v_fmac_f32_e32 v18, v138, v19
	v_max_f32_e32 v19, 0, v24
	v_fmac_f32_e32 v18, v137, v19
	v_max_f32_e32 v19, 0, v25
	v_fmac_f32_e32 v18, v136, v19
	v_max_f32_e32 v19, 0, v26
	v_fmac_f32_e32 v18, v135, v19
	v_max_f32_e32 v19, 0, v27
	v_fmac_f32_e32 v18, v134, v19
	v_max_f32_e32 v19, 0, v28
	v_fmac_f32_e32 v18, v133, v19
	v_max_f32_e32 v19, 0, v29
	v_fmac_f32_e32 v18, v132, v19
	v_max_f32_e32 v19, 0, v30
	v_fmac_f32_e32 v18, v131, v19
	v_max_f32_e32 v19, 0, v31
	v_fmac_f32_e32 v18, v130, v19
	v_max_f32_e32 v19, 0, v32
	v_fmac_f32_e32 v18, v129, v19
	v_max_f32_e32 v19, 0, v33
	v_fmac_f32_e32 v18, v128, v19
	v_ashrrev_i32_e32 v19, 31, v18
	v_bitop3_b32 v18, v19, v18, s8 bitop3:0x36
	v_cndmask_b32_e32 v187, 0, v18, vcc
	s_cmp_lt_u32 s0, 0x4e0
	s_cbranch_scc1 .Lix_z39
.Lix_b39:
	s_cmp_lt_u32 s0, 0x540
	s_cbranch_scc1 .Lix_w39
	s_waitcnt vmcnt(12)
	s_branch .Lix_m39

; #define MFMA(a, b, c) __builtin_amdgcn_mfma_f32_32x32x16_bf16((a), (b), (c), 0, 0, 0)
; DI unsigned ordkey(float f) { const unsigned b = __float_as_uint(f); return b ^ ((unsigned)((int)b >> 31) | 0x80000000u); }
; DI void indexer_phase(const u16* __restrict__ P, unsigned* __restrict__ mask) {
;     ...
;     for (int kb = 0; kb < 64; ++kb) {
;       unsigned u = 0u;
;       if (kb <= kbmax) {
;         f32x16 a;
; #pragma unroll
;         for (int r = 0; r < 16; ++r) a[r] = 0.f;
;         const u16* kp = P + (brow + 32 * kb + r32) * 7808 + 3584 + 8 * hi;
; #pragma unroll
;         for (int s = 0; s < 4; ++s) { const bf16x8 bk = *(const bf16x8*)(kp + 16 * s); a = MFMA(aq[s], bk, a); }
;         float v = 0.f;
; #pragma unroll
;         for (int i = 0; i < 16; ++i) v = fmaf(wv[i], fmaxf(a[i], 0.f), v);
;         u = (32 * kb + r32 <= tme) ? ordkey(v) : 0u;
;       }
;       sc[kb] = u;
.Lix_m39:
	v_cmp_le_i32_e32 vcc, 0x4e0, v16
	v_mfma_f32_32x32x16_bf16 v[18:33], v[46:49], v[112:115], 0
	v_mfma_f32_32x32x16_bf16 v[18:33], v[42:45], v[116:119], v[18:33]
	v_mfma_f32_32x32x16_bf16 v[18:33], v[38:41], v[120:123], v[18:33]
	v_mfma_f32_32x32x16_bf16 v[18:33], v[34:37], v[12:15], v[18:33]
	s_cmp_lt_u32 s0, 0x560
	s_cbranch_scc1 .Lix_np39
	global_load_dwordx4 v[112:115], v[124:125], off
	global_load_dwordx4 v[116:119], v[124:125], off offset:32
	global_load_dwordx4 v[120:123], v[124:125], off offset:64
	global_load_dwordx4 v[12:15], v[124:125], off offset:96
	v_lshl_add_u64 v[124:125], v[124:125], 0, s[22:23]
.Lix_np39:
	s_nop 10
	v_max_f32_e32 v18, 0, v18
	v_max_f32_e32 v19, 0, v19
	v_fma_f32 v18, v143, v18, 0
	v_fmac_f32_e32 v18, v142, v19
	v_max_f32_e32 v19, 0, v20
	v_fmac_f32_e32 v18, v141, v19
	v_max_f32_e32 v19, 0, v21
	v_fmac_f32_e32 v18, v140, v19
	v_max_f32_e32 v19, 0, v22
	v_fmac_f32_e32 v18, v139, v19
	v_max_f32_e32 v19, 0, v23
	v_fmac_f32_e32 v18, v138, v19
	v_max_f32_e32 v19, 0, v24
	v_fmac_f32_e32 v18, v137, v19
	v_max_f32_e32 v19, 0, v25
	v_fmac_f32_e32 v18, v136, v19
	v_max_f32_e32 v19, 0, v26
	v_fmac_f32_e32 v18, v135, v19
	v_max_f32_e32 v19, 0, v27
	v_fmac_f32_e32 v18, v134, v19
	v_max_f32_e32 v19, 0, v28
	v_fmac_f32_e32 v18, v133, v19
	v_max_f32_e32 v19, 0, v29
	v_fmac_f32_e32 v18, v132, v19
	v_max_f32_e32 v19, 0, v30
	v_fmac_f32_e32 v18, v131, v19
	v_max_f32_e32 v19, 0, v31
	v_fmac_f32_e32 v18, v130, v19
	v_max_f32_e32 v19, 0, v32
	v_fmac_f32_e32 v18, v129, v19
	v_max_f32_e32 v19, 0, v33
	v_fmac_f32_e32 v18, v128, v19
	v_ashrrev_i32_e32 v19, 31, v18
	v_bitop3_b32 v18, v19, v18, s8 bitop3:0x36
	v_cndmask_b32_e32 v190, 0, v18, vcc
	s_cmp_lt_u32 s0, 0x500
	s_cbranch_scc1 .Lix_z40
.Lix_b40:
	s_cmp_lt_u32 s0, 0x560
	s_cbranch_scc1 .Lix_w40
	s_waitcnt vmcnt(12)
	s_branch .Lix_m40

; #define MFMA(a, b, c) __builtin_amdgcn_mfma_f32_32x32x16_bf16((a), (b), (c), 0, 0, 0)
; DI unsigned ordkey(float f) { const unsigned b = __float_as_uint(f); return b ^ ((unsigned)((int)b >> 31) | 0x80000000u); }
; DI void indexer_phase(const u16* __restrict__ P, unsigned* __restrict__ mask) {
;     ...
;     for (int kb = 0; kb < 64; ++kb) {
;       unsigned u = 0u;
;       if (kb <= kbmax) {
;         f32x16 a;
; #pragma unroll
;         for (int r = 0; r < 16; ++r) a[r] = 0.f;
;         const u16* kp = P + (brow + 32 * kb + r32) * 7808 + 3584 + 8 * hi;
; #pragma unroll
;         for (int s = 0; s < 4; ++s) { const bf16x8 bk = *(const bf16x8*)(kp + 16 * s); a = MFMA(aq[s], bk, a); }
;         float v = 0.f;
; #pragma unroll
;         for (int i = 0; i < 16; ++i) v = fmaf(wv[i], fmaxf(a[i], 0.f), v);
;         u = (32 * kb + r32 <= tme) ? ordkey(v) : 0u;
;       }
;       sc[kb] = u;
.Lix_m40:
	v_cmp_le_i32_e32 vcc, 0x500, v16
	v_mfma_f32_32x32x16_bf16 v[18:33], v[46:49], v[64:67], 0
	v_mfma_f32_32x32x16_bf16 v[18:33], v[42:45], v[68:71], v[18:33]
	v_mfma_f32_32x32x16_bf16 v[18:33], v[38:41], v[72:75], v[18:33]
	v_mfma_f32_32x32x16_bf16 v[18:33], v[34:37], v[76:79], v[18:33]
	s_cmp_lt_u32 s0, 0x580
	s_cbranch_scc1 .Lix_np40
	global_load_dwordx4 v[64:67], v[124:125], off
	global_load_dwordx4 v[68:71], v[124:125], off offset:32
	global_load_dwordx4 v[72:75], v[124:125], off offset:64
	global_load_dwordx4 v[76:79], v[124:125], off offset:96
	v_lshl_add_u64 v[124:125], v[124:125], 0, s[22:23]
.Lix_np40:
	s_nop 10
	v_max_f32_e32 v18, 0, v18
	v_max_f32_e32 v19, 0, v19
	v_fma_f32 v18, v143, v18, 0
	v_fmac_f32_e32 v18, v142, v19
	v_max_f32_e32 v19, 0, v20
	v_fmac_f32_e32 v18, v141, v19
	v_max_f32_e32 v19, 0, v21
	v_fmac_f32_e32 v18, v140, v19
	v_max_f32_e32 v19, 0, v22
	v_fmac_f32_e32 v18, v139, v19
	v_max_f32_e32 v19, 0, v23
	v_fmac_f32_e32 v18, v138, v19
	v_max_f32_e32 v19, 0, v24
	v_fmac_f32_e32 v18, v137, v19
	v_max_f32_e32 v19, 0, v25
	v_fmac_f32_e32 v18, v136, v19
	v_max_f32_e32 v19, 0, v26
	v_fmac_f32_e32 v18, v135, v19
	v_max_f32_e32 v19, 0, v27
	v_fmac_f32_e32 v18, v134, v19
	v_max_f32_e32 v19, 0, v28
	v_fmac_f32_e32 v18, v133, v19
	v_max_f32_e32 v19, 0, v29
	v_fmac_f32_e32 v18, v132, v19
	v_max_f32_e32 v19, 0, v30
	v_fmac_f32_e32 v18, v131, v19
	v_max_f32_e32 v19, 0, v31
	v_fmac_f32_e32 v18, v130, v19
	v_max_f32_e32 v19, 0, v32
	v_fmac_f32_e32 v18, v129, v19
	v_max_f32_e32 v19, 0, v33
	v_fmac_f32_e32 v18, v128, v19
	v_ashrrev_i32_e32 v19, 31, v18
	v_bitop3_b32 v18, v19, v18, s8 bitop3:0x36
	v_cndmask_b32_e32 v189, 0, v18, vcc
	s_cmp_lt_u32 s0, 0x520
	s_cbranch_scc1 .Lix_z41
.Lix_b41:
	s_cmp_lt_u32 s0, 0x580
	s_cbranch_scc1 .Lix_w41
	s_waitcnt vmcnt(12)
	s_branch .Lix_m41

; #define MFMA(a, b, c) __builtin_amdgcn_mfma_f32_32x32x16_bf16((a), (b), (c), 0, 0, 0)
; DI unsigned ordkey(float f) { const unsigned b = __float_as_uint(f); return b ^ ((unsigned)((int)b >> 31) | 0x80000000u); }
; DI void indexer_phase(const u16* __restrict__ P, unsigned* __restrict__ mask) {
;     ...
;     for (int kb = 0; kb < 64; ++kb) {
;       unsigned u = 0u;
;       if (kb <= kbmax) {
;         f32x16 a;
; #pragma unroll
;         for (int r = 0; r < 16; ++r) a[r] = 0.f;
;         const u16* kp = P + (brow + 32 * kb + r32) * 7808 + 3584 + 8 * hi;
; #pragma unroll
;         for (int s = 0; s < 4; ++s) { const bf16x8 bk = *(const bf16x8*)(kp + 16 * s); a = MFMA(aq[s], bk, a); }
;         float v = 0.f;
; #pragma unroll
;         for (int i = 0; i < 16; ++i) v = fmaf(wv[i], fmaxf(a[i], 0.f), v);
;         u = (32 * kb + r32 <= tme) ? ordkey(v) : 0u;
;       }
;       sc[kb] = u;
.Lix_m41:
	v_cmp_le_i32_e32 vcc, 0x520, v16
	v_mfma_f32_32x32x16_bf16 v[18:33], v[46:49], v[80:83], 0
	v_mfma_f32_32x32x16_bf16 v[18:33], v[42:45], v[84:87], v[18:33]
	v_mfma_f32_32x32x16_bf16 v[18:33], v[38:41], v[88:91], v[18:33]
	v_mfma_f32_32x32x16_bf16 v[18:33], v[34:37], v[92:95], v[18:33]
	s_cmp_lt_u32 s0, 0x5a0
	s_cbranch_scc1 .Lix_np41
	global_load_dwordx4 v[80:83], v[124:125], off
	global_load_dwordx4 v[84:87], v[124:125], off offset:32
	global_load_dwordx4 v[88:91], v[124:125], off offset:64
	global_load_dwordx4 v[92:95], v[124:125], off offset:96
	v_lshl_add_u64 v[124:125], v[124:125], 0, s[22:23]
.Lix_np41:
	s_nop 10
	v_max_f32_e32 v18, 0, v18
	v_max_f32_e32 v19, 0, v19
	v_fma_f32 v18, v143, v18, 0
	v_fmac_f32_e32 v18, v142, v19
	v_max_f32_e32 v19, 0, v20
	v_fmac_f32_e32 v18, v141, v19
	v_max_f32_e32 v19, 0, v21
	v_fmac_f32_e32 v18, v140, v19
	v_max_f32_e32 v19, 0, v22
	v_fmac_f32_e32 v18, v139, v19
	v_max_f32_e32 v19, 0, v23
	v_fmac_f32_e32 v18, v138, v19
	v_max_f32_e32 v19, 0, v24
	v_fmac_f32_e32 v18, v137, v19
	v_max_f32_e32 v19, 0, v25
	v_fmac_f32_e32 v18, v136, v19
	v_max_f32_e32 v19, 0, v26
	v_fmac_f32_e32 v18, v135, v19
	v_max_f32_e32 v19, 0, v27
	v_fmac_f32_e32 v18, v134, v19
	v_max_f32_e32 v19, 0, v28
	v_fmac_f32_e32 v18, v133, v19
	v_max_f32_e32 v19, 0, v29
	v_fmac_f32_e32 v18, v132, v19
	v_max_f32_e32 v19, 0, v30
	v_fmac_f32_e32 v18, v131, v19
	v_max_f32_e32 v19, 0, v31
	v_fmac_f32_e32 v18, v130, v19
	v_max_f32_e32 v19, 0, v32
	v_fmac_f32_e32 v18, v129, v19
	v_max_f32_e32 v19, 0, v33
	v_fmac_f32_e32 v18, v128, v19
	v_ashrrev_i32_e32 v19, 31, v18
	v_bitop3_b32 v18, v19, v18, s8 bitop3:0x36
	v_cndmask_b32_e32 v192, 0, v18, vcc
	s_cmp_lt_u32 s0, 0x540
	s_cbranch_scc1 .Lix_z42
.Lix_b42:
	s_cmp_lt_u32 s0, 0x5a0
	s_cbranch_scc1 .Lix_w42
	s_waitcnt vmcnt(12)
	s_branch .Lix_m42

; #define MFMA(a, b, c) __builtin_amdgcn_mfma_f32_32x32x16_bf16((a), (b), (c), 0, 0, 0)
; DI unsigned ordkey(float f) { const unsigned b = __float_as_uint(f); return b ^ ((unsigned)((int)b >> 31) | 0x80000000u); }
; DI void indexer_phase(const u16* __restrict__ P, unsigned* __restrict__ mask) {
;     ...
;     for (int kb = 0; kb < 64; ++kb) {
;       unsigned u = 0u;
;       if (kb <= kbmax) {
;         f32x16 a;
; #pragma unroll
;         for (int r = 0; r < 16; ++r) a[r] = 0.f;
;         const u16* kp = P + (brow + 32 * kb + r32) * 7808 + 3584 + 8 * hi;
; #pragma unroll
;         for (int s = 0; s < 4; ++s) { const bf16x8 bk = *(const bf16x8*)(kp + 16 * s); a = MFMA(aq[s], bk, a); }
;         float v = 0.f;
; #pragma unroll
;         for (int i = 0; i < 16; ++i) v = fmaf(wv[i], fmaxf(a[i], 0.f), v);
;         u = (32 * kb + r32 <= tme) ? ordkey(v) : 0u;
;       }
;       sc[kb] = u;
.Lix_m42:
	v_cmp_le_i32_e32 vcc, 0x540, v16
	v_mfma_f32_32x32x16_bf16 v[18:33], v[46:49], v[96:99], 0
	v_mfma_f32_32x32x16_bf16 v[18:33], v[42:45], v[100:103], v[18:33]
	v_mfma_f32_32x32x16_bf16 v[18:33], v[38:41], v[104:107], v[18:33]
	v_mfma_f32_32x32x16_bf16 v[18:33], v[34:37], v[108:111], v[18:33]
	s_cmp_lt_u32 s0, 0x5c0
	s_cbranch_scc1 .Lix_np42
	global_load_dwordx4 v[96:99], v[124:125], off
	global_load_dwordx4 v[100:103], v[124:125], off offset:32
	global_load_dwordx4 v[104:107], v[124:125], off offset:64
	global_load_dwordx4 v[108:111], v[124:125], off offset:96
	v_lshl_add_u64 v[124:125], v[124:125], 0, s[22:23]
.Lix_np42:
	s_nop 10
	v_max_f32_e32 v18, 0, v18
	v_max_f32_e32 v19, 0, v19
	v_fma_f32 v18, v143, v18, 0
	v_fmac_f32_e32 v18, v142, v19
	v_max_f32_e32 v19, 0, v20
	v_fmac_f32_e32 v18, v141, v19
	v_max_f32_e32 v19, 0, v21
	v_fmac_f32_e32 v18, v140, v19
	v_max_f32_e32 v19, 0, v22
	v_fmac_f32_e32 v18, v139, v19
	v_max_f32_e32 v19, 0, v23
	v_fmac_f32_e32 v18, v138, v19
	v_max_f32_e32 v19, 0, v24
	v_fmac_f32_e32 v18, v137, v19
	v_max_f32_e32 v19, 0, v25
	v_fmac_f32_e32 v18, v136, v19
	v_max_f32_e32 v19, 0, v26
	v_fmac_f32_e32 v18, v135, v19
	v_max_f32_e32 v19, 0, v27
	v_fmac_f32_e32 v18, v134, v19
	v_max_f32_e32 v19, 0, v28
	v_fmac_f32_e32 v18, v133, v19
	v_max_f32_e32 v19, 0, v29
	v_fmac_f32_e32 v18, v132, v19
	v_max_f32_e32 v19, 0, v30
	v_fmac_f32_e32 v18, v131, v19
	v_max_f32_e32 v19, 0, v31
	v_fmac_f32_e32 v18, v130, v19
	v_max_f32_e32 v19, 0, v32
	v_fmac_f32_e32 v18, v129, v19
	v_max_f32_e32 v19, 0, v33
	v_fmac_f32_e32 v18, v128, v19
	v_ashrrev_i32_e32 v19, 31, v18
	v_bitop3_b32 v18, v19, v18, s8 bitop3:0x36
	v_cndmask_b32_e32 v191, 0, v18, vcc
	s_cmp_lt_u32 s0, 0x560
	s_cbranch_scc1 .Lix_z43
.Lix_b43:
	s_cmp_lt_u32 s0, 0x5c0
	s_cbranch_scc1 .Lix_w43
	s_waitcnt vmcnt(12)
	s_branch .Lix_m43

; #define MFMA(a, b, c) __builtin_amdgcn_mfma_f32_32x32x16_bf16((a), (b), (c), 0, 0, 0)
; DI unsigned ordkey(float f) { const unsigned b = __float_as_uint(f); return b ^ ((unsigned)((int)b >> 31) | 0x80000000u); }
; DI void indexer_phase(const u16* __restrict__ P, unsigned* __restrict__ mask) {
;     ...
;     for (int kb = 0; kb < 64; ++kb) {
;       unsigned u = 0u;
;       if (kb <= kbmax) {
;         f32x16 a;
; #pragma unroll
;         for (int r = 0; r < 16; ++r) a[r] = 0.f;
;         const u16* kp = P + (brow + 32 * kb + r32) * 7808 + 3584 + 8 * hi;
; #pragma unroll
;         for (int s = 0; s < 4; ++s) { const bf16x8 bk = *(const bf16x8*)(kp + 16 * s); a = MFMA(aq[s], bk, a); }
;         float v = 0.f;
; #pragma unroll
;         for (int i = 0; i < 16; ++i) v = fmaf(wv[i], fmaxf(a[i], 0.f), v);
;         u = (32 * kb + r32 <= tme) ? ordkey(v) : 0u;
;       }
;       sc[kb] = u;
.Lix_m43:
	v_cmp_le_i32_e32 vcc, 0x560, v16
	v_mfma_f32_32x32x16_bf16 v[18:33], v[46:49], v[112:115], 0
	v_mfma_f32_32x32x16_bf16 v[18:33], v[42:45], v[116:119], v[18:33]
	v_mfma_f32_32x32x16_bf16 v[18:33], v[38:41], v[120:123], v[18:33]
	v_mfma_f32_32x32x16_bf16 v[18:33], v[34:37], v[12:15], v[18:33]
	s_cmp_lt_u32 s0, 0x5e0
	s_cbranch_scc1 .Lix_np43
	global_load_dwordx4 v[112:115], v[124:125], off
	global_load_dwordx4 v[116:119], v[124:125], off offset:32
	global_load_dwordx4 v[120:123], v[124:125], off offset:64
	global_load_dwordx4 v[12:15], v[124:125], off offset:96
	v_lshl_add_u64 v[124:125], v[124:125], 0, s[22:23]
.Lix_np43:
	s_nop 10
	v_max_f32_e32 v18, 0, v18
	v_max_f32_e32 v19, 0, v19
	v_fma_f32 v18, v143, v18, 0
	v_fmac_f32_e32 v18, v142, v19
	v_max_f32_e32 v19, 0, v20
	v_fmac_f32_e32 v18, v141, v19
	v_max_f32_e32 v19, 0, v21
	v_fmac_f32_e32 v18, v140, v19
	v_max_f32_e32 v19, 0, v22
	v_fmac_f32_e32 v18, v139, v19
	v_max_f32_e32 v19, 0, v23
	v_fmac_f32_e32 v18, v138, v19
	v_max_f32_e32 v19, 0, v24
	v_fmac_f32_e32 v18, v137, v19
	v_max_f32_e32 v19, 0, v25
	v_fmac_f32_e32 v18, v136, v19
	v_max_f32_e32 v19, 0, v26
	v_fmac_f32_e32 v18, v135, v19
	v_max_f32_e32 v19, 0, v27
	v_fmac_f32_e32 v18, v134, v19
	v_max_f32_e32 v19, 0, v28
	v_fmac_f32_e32 v18, v133, v19
	v_max_f32_e32 v19, 0, v29
	v_fmac_f32_e32 v18, v132, v19
	v_max_f32_e32 v19, 0, v30
	v_fmac_f32_e32 v18, v131, v19
	v_max_f32_e32 v19, 0, v31
	v_fmac_f32_e32 v18, v130, v19
	v_max_f32_e32 v19, 0, v32
	v_fmac_f32_e32 v18, v129, v19
	v_max_f32_e32 v19, 0, v33
	v_fmac_f32_e32 v18, v128, v19
	v_ashrrev_i32_e32 v19, 31, v18
	v_bitop3_b32 v18, v19, v18, s8 bitop3:0x36
	v_cndmask_b32_e32 v194, 0, v18, vcc
	s_cmp_lt_u32 s0, 0x580
	s_cbranch_scc1 .Lix_z44
.Lix_b44:
	s_cmp_lt_u32 s0, 0x5e0
	s_cbranch_scc1 .Lix_w44
	s_waitcnt vmcnt(12)
	s_branch .Lix_m44

; #define MFMA(a, b, c) __builtin_amdgcn_mfma_f32_32x32x16_bf16((a), (b), (c), 0, 0, 0)
; DI unsigned ordkey(float f) { const unsigned b = __float_as_uint(f); return b ^ ((unsigned)((int)b >> 31) | 0x80000000u); }
; DI void indexer_phase(const u16* __restrict__ P, unsigned* __restrict__ mask) {
;     ...
;     for (int kb = 0; kb < 64; ++kb) {
;       unsigned u = 0u;
;       if (kb <= kbmax) {
;         f32x16 a;
; #pragma unroll
;         for (int r = 0; r < 16; ++r) a[r] = 0.f;
;         const u16* kp = P + (brow + 32 * kb + r32) * 7808 + 3584 + 8 * hi;
; #pragma unroll
;         for (int s = 0; s < 4; ++s) { const bf16x8 bk = *(const bf16x8*)(kp + 16 * s); a = MFMA(aq[s], bk, a); }
;         float v = 0.f;
; #pragma unroll
;         for (int i = 0; i < 16; ++i) v = fmaf(wv[i], fmaxf(a[i], 0.f), v);
;         u = (32 * kb + r32 <= tme) ? ordkey(v) : 0u;
;       }
;       sc[kb] = u;
.Lix_m44:
	v_cmp_le_i32_e32 vcc, 0x580, v16
	v_mfma_f32_32x32x16_bf16 v[18:33], v[46:49], v[64:67], 0
	v_mfma_f32_32x32x16_bf16 v[18:33], v[42:45], v[68:71], v[18:33]
	v_mfma_f32_32x32x16_bf16 v[18:33], v[38:41], v[72:75], v[18:33]
	v_mfma_f32_32x32x16_bf16 v[18:33], v[34:37], v[76:79], v[18:33]
	s_cmp_lt_u32 s0, 0x600
	s_cbranch_scc1 .Lix_np44
	global_load_dwordx4 v[64:67], v[124:125], off
	global_load_dwordx4 v[68:71], v[124:125], off offset:32
	global_load_dwordx4 v[72:75], v[124:125], off offset:64
	global_load_dwordx4 v[76:79], v[124:125], off offset:96
	v_lshl_add_u64 v[124:125], v[124:125], 0, s[22:23]
.Lix_np44:
	s_nop 10
	v_max_f32_e32 v18, 0, v18
	v_max_f32_e32 v19, 0, v19
	v_fma_f32 v18, v143, v18, 0
	v_fmac_f32_e32 v18, v142, v19
	v_max_f32_e32 v19, 0, v20
	v_fmac_f32_e32 v18, v141, v19
	v_max_f32_e32 v19, 0, v21
	v_fmac_f32_e32 v18, v140, v19
	v_max_f32_e32 v19, 0, v22
	v_fmac_f32_e32 v18, v139, v19
	v_max_f32_e32 v19, 0, v23
	v_fmac_f32_e32 v18, v138, v19
	v_max_f32_e32 v19, 0, v24
	v_fmac_f32_e32 v18, v137, v19
	v_max_f32_e32 v19, 0, v25
	v_fmac_f32_e32 v18, v136, v19
	v_max_f32_e32 v19, 0, v26
	v_fmac_f32_e32 v18, v135, v19
	v_max_f32_e32 v19, 0, v27
	v_fmac_f32_e32 v18, v134, v19
	v_max_f32_e32 v19, 0, v28
	v_fmac_f32_e32 v18, v133, v19
	v_max_f32_e32 v19, 0, v29
	v_fmac_f32_e32 v18, v132, v19
	v_max_f32_e32 v19, 0, v30
	v_fmac_f32_e32 v18, v131, v19
	v_max_f32_e32 v19, 0, v31
	v_fmac_f32_e32 v18, v130, v19
	v_max_f32_e32 v19, 0, v32
	v_fmac_f32_e32 v18, v129, v19
	v_max_f32_e32 v19, 0, v33
	v_fmac_f32_e32 v18, v128, v19
	v_ashrrev_i32_e32 v19, 31, v18
	v_bitop3_b32 v18, v19, v18, s8 bitop3:0x36
	v_cndmask_b32_e32 v193, 0, v18, vcc
	s_cmp_lt_u32 s0, 0x5a0
	s_cbranch_scc1 .Lix_z45
.Lix_b45:
	s_cmp_lt_u32 s0, 0x600
	s_cbranch_scc1 .Lix_w45
	s_waitcnt vmcnt(12)
	s_branch .Lix_m45

; #define MFMA(a, b, c) __builtin_amdgcn_mfma_f32_32x32x16_bf16((a), (b), (c), 0, 0, 0)
; DI unsigned ordkey(float f) { const unsigned b = __float_as_uint(f); return b ^ ((unsigned)((int)b >> 31) | 0x80000000u); }
; DI void indexer_phase(const u16* __restrict__ P, unsigned* __restrict__ mask) {
;     ...
;     for (int kb = 0; kb < 64; ++kb) {
;       unsigned u = 0u;
;       if (kb <= kbmax) {
;         f32x16 a;
; #pragma unroll
;         for (int r = 0; r < 16; ++r) a[r] = 0.f;
;         const u16* kp = P + (brow + 32 * kb + r32) * 7808 + 3584 + 8 * hi;
; #pragma unroll
;         for (int s = 0; s < 4; ++s) { const bf16x8 bk = *(const bf16x8*)(kp + 16 * s); a = MFMA(aq[s], bk, a); }
;         float v = 0.f;
; #pragma unroll
;         for (int i = 0; i < 16; ++i) v = fmaf(wv[i], fmaxf(a[i], 0.f), v);
;         u = (32 * kb + r32 <= tme) ? ordkey(v) : 0u;
;       }
;       sc[kb] = u;
.Lix_m45:
	v_cmp_le_i32_e32 vcc, 0x5a0, v16
	v_mfma_f32_32x32x16_bf16 v[18:33], v[46:49], v[80:83], 0
	v_mfma_f32_32x32x16_bf16 v[18:33], v[42:45], v[84:87], v[18:33]
	v_mfma_f32_32x32x16_bf16 v[18:33], v[38:41], v[88:91], v[18:33]
	v_mfma_f32_32x32x16_bf16 v[18:33], v[34:37], v[92:95], v[18:33]
	s_cmp_lt_u32 s0, 0x620
	s_cbranch_scc1 .Lix_np45
	global_load_dwordx4 v[80:83], v[124:125], off
	global_load_dwordx4 v[84:87], v[124:125], off offset:32
	global_load_dwordx4 v[88:91], v[124:125], off offset:64
	global_load_dwordx4 v[92:95], v[124:125], off offset:96
	v_lshl_add_u64 v[124:125], v[124:125], 0, s[22:23]
.Lix_np45:
	s_nop 10
	v_max_f32_e32 v18, 0, v18
	v_max_f32_e32 v19, 0, v19
	v_fma_f32 v18, v143, v18, 0
	v_fmac_f32_e32 v18, v142, v19
	v_max_f32_e32 v19, 0, v20
	v_fmac_f32_e32 v18, v141, v19
	v_max_f32_e32 v19, 0, v21
	v_fmac_f32_e32 v18, v140, v19
	v_max_f32_e32 v19, 0, v22
	v_fmac_f32_e32 v18, v139, v19
	v_max_f32_e32 v19, 0, v23
	v_fmac_f32_e32 v18, v138, v19
	v_max_f32_e32 v19, 0, v24
	v_fmac_f32_e32 v18, v137, v19
	v_max_f32_e32 v19, 0, v25
	v_fmac_f32_e32 v18, v136, v19
	v_max_f32_e32 v19, 0, v26
	v_fmac_f32_e32 v18, v135, v19
	v_max_f32_e32 v19, 0, v27
	v_fmac_f32_e32 v18, v134, v19
	v_max_f32_e32 v19, 0, v28
	v_fmac_f32_e32 v18, v133, v19
	v_max_f32_e32 v19, 0, v29
	v_fmac_f32_e32 v18, v132, v19
	v_max_f32_e32 v19, 0, v30
	v_fmac_f32_e32 v18, v131, v19
	v_max_f32_e32 v19, 0, v31
	v_fmac_f32_e32 v18, v130, v19
	v_max_f32_e32 v19, 0, v32
	v_fmac_f32_e32 v18, v129, v19
	v_max_f32_e32 v19, 0, v33
	v_fmac_f32_e32 v18, v128, v19
	v_ashrrev_i32_e32 v19, 31, v18
	v_bitop3_b32 v18, v19, v18, s8 bitop3:0x36
	v_cndmask_b32_e32 v196, 0, v18, vcc
	s_cmp_lt_u32 s0, 0x5c0
	s_cbranch_scc1 .Lix_z46
.Lix_b46:
	s_cmp_lt_u32 s0, 0x620
	s_cbranch_scc1 .Lix_w46
	s_waitcnt vmcnt(12)
	s_branch .Lix_m46

; #define MFMA(a, b, c) __builtin_amdgcn_mfma_f32_32x32x16_bf16((a), (b), (c), 0, 0, 0)
; DI unsigned ordkey(float f) { const unsigned b = __float_as_uint(f); return b ^ ((unsigned)((int)b >> 31) | 0x80000000u); }
; DI void indexer_phase(const u16* __restrict__ P, unsigned* __restrict__ mask) {
;     ...
;     for (int kb = 0; kb < 64; ++kb) {
;       unsigned u = 0u;
;       if (kb <= kbmax) {
;         f32x16 a;
; #pragma unroll
;         for (int r = 0; r < 16; ++r) a[r] = 0.f;
;         const u16* kp = P + (brow + 32 * kb + r32) * 7808 + 3584 + 8 * hi;
; #pragma unroll
;         for (int s = 0; s < 4; ++s) { const bf16x8 bk = *(const bf16x8*)(kp + 16 * s); a = MFMA(aq[s], bk, a); }
;         float v = 0.f;
; #pragma unroll
;         for (int i = 0; i < 16; ++i) v = fmaf(wv[i], fmaxf(a[i], 0.f), v);
;         u = (32 * kb + r32 <= tme) ? ordkey(v) : 0u;
;       }
;       sc[kb] = u;
.Lix_m46:
	v_cmp_le_i32_e32 vcc, 0x5c0, v16
	v_mfma_f32_32x32x16_bf16 v[18:33], v[46:49], v[96:99], 0
	v_mfma_f32_32x32x16_bf16 v[18:33], v[42:45], v[100:103], v[18:33]
	v_mfma_f32_32x32x16_bf16 v[18:33], v[38:41], v[104:107], v[18:33]
	v_mfma_f32_32x32x16_bf16 v[18:33], v[34:37], v[108:111], v[18:33]
	s_cmp_lt_u32 s0, 0x640
	s_cbranch_scc1 .Lix_np46
	global_load_dwordx4 v[96:99], v[124:125], off
	global_load_dwordx4 v[100:103], v[124:125], off offset:32
	global_load_dwordx4 v[104:107], v[124:125], off offset:64
	global_load_dwordx4 v[108:111], v[124:125], off offset:96
	v_lshl_add_u64 v[124:125], v[124:125], 0, s[22:23]
.Lix_np46:
	s_nop 10
	v_max_f32_e32 v18, 0, v18
	v_max_f32_e32 v19, 0, v19
	v_fma_f32 v18, v143, v18, 0
	v_fmac_f32_e32 v18, v142, v19
	v_max_f32_e32 v19, 0, v20
	v_fmac_f32_e32 v18, v141, v19
	v_max_f32_e32 v19, 0, v21
	v_fmac_f32_e32 v18, v140, v19
	v_max_f32_e32 v19, 0, v22
	v_fmac_f32_e32 v18, v139, v19
	v_max_f32_e32 v19, 0, v23
	v_fmac_f32_e32 v18, v138, v19
	v_max_f32_e32 v19, 0, v24
	v_fmac_f32_e32 v18, v137, v19
	v_max_f32_e32 v19, 0, v25
	v_fmac_f32_e32 v18, v136, v19
	v_max_f32_e32 v19, 0, v26
	v_fmac_f32_e32 v18, v135, v19
	v_max_f32_e32 v19, 0, v27
	v_fmac_f32_e32 v18, v134, v19
	v_max_f32_e32 v19, 0, v28
	v_fmac_f32_e32 v18, v133, v19
	v_max_f32_e32 v19, 0, v29
	v_fmac_f32_e32 v18, v132, v19
	v_max_f32_e32 v19, 0, v30
	v_fmac_f32_e32 v18, v131, v19
	v_max_f32_e32 v19, 0, v31
	v_fmac_f32_e32 v18, v130, v19
	v_max_f32_e32 v19, 0, v32
	v_fmac_f32_e32 v18, v129, v19
	v_max_f32_e32 v19, 0, v33
	v_fmac_f32_e32 v18, v128, v19
	v_ashrrev_i32_e32 v19, 31, v18
	v_bitop3_b32 v18, v19, v18, s8 bitop3:0x36
	v_cndmask_b32_e32 v195, 0, v18, vcc
	s_cmp_lt_u32 s0, 0x5e0
	s_cbranch_scc1 .Lix_z47
.Lix_b47:
	s_cmp_lt_u32 s0, 0x640
	s_cbranch_scc1 .Lix_w47
	s_waitcnt vmcnt(12)
	s_branch .Lix_m47

; #define MFMA(a, b, c) __builtin_amdgcn_mfma_f32_32x32x16_bf16((a), (b), (c), 0, 0, 0)
; DI unsigned ordkey(float f) { const unsigned b = __float_as_uint(f); return b ^ ((unsigned)((int)b >> 31) | 0x80000000u); }
; DI void indexer_phase(const u16* __restrict__ P, unsigned* __restrict__ mask) {
;     ...
;     for (int kb = 0; kb < 64; ++kb) {
;       unsigned u = 0u;
;       if (kb <= kbmax) {
;         f32x16 a;
; #pragma unroll
;         for (int r = 0; r < 16; ++r) a[r] = 0.f;
;         const u16* kp = P + (brow + 32 * kb + r32) * 7808 + 3584 + 8 * hi;
; #pragma unroll
;         for (int s = 0; s < 4; ++s) { const bf16x8 bk = *(const bf16x8*)(kp + 16 * s); a = MFMA(aq[s], bk, a); }
;         float v = 0.f;
; #pragma unroll
;         for (int i = 0; i < 16; ++i) v = fmaf(wv[i], fmaxf(a[i], 0.f), v);
;         u = (32 * kb + r32 <= tme) ? ordkey(v) : 0u;
;       }
;       sc[kb] = u;
.Lix_m47:
	v_cmp_le_i32_e32 vcc, 0x5e0, v16
	v_mfma_f32_32x32x16_bf16 v[18:33], v[46:49], v[112:115], 0
	v_mfma_f32_32x32x16_bf16 v[18:33], v[42:45], v[116:119], v[18:33]
	v_mfma_f32_32x32x16_bf16 v[18:33], v[38:41], v[120:123], v[18:33]
	v_mfma_f32_32x32x16_bf16 v[18:33], v[34:37], v[12:15], v[18:33]
	s_cmp_lt_u32 s0, 0x660
	s_cbranch_scc1 .Lix_np47
	global_load_dwordx4 v[112:115], v[124:125], off
	global_load_dwordx4 v[116:119], v[124:125], off offset:32
	global_load_dwordx4 v[120:123], v[124:125], off offset:64
	global_load_dwordx4 v[12:15], v[124:125], off offset:96
	v_lshl_add_u64 v[124:125], v[124:125], 0, s[22:23]
.Lix_np47:
	s_nop 10
	v_max_f32_e32 v18, 0, v18
	v_max_f32_e32 v19, 0, v19
	v_fma_f32 v18, v143, v18, 0
	v_fmac_f32_e32 v18, v142, v19
	v_max_f32_e32 v19, 0, v20
	v_fmac_f32_e32 v18, v141, v19
	v_max_f32_e32 v19, 0, v21
	v_fmac_f32_e32 v18, v140, v19
	v_max_f32_e32 v19, 0, v22
	v_fmac_f32_e32 v18, v139, v19
	v_max_f32_e32 v19, 0, v23
	v_fmac_f32_e32 v18, v138, v19
	v_max_f32_e32 v19, 0, v24
	v_fmac_f32_e32 v18, v137, v19
	v_max_f32_e32 v19, 0, v25
	v_fmac_f32_e32 v18, v136, v19
	v_max_f32_e32 v19, 0, v26
	v_fmac_f32_e32 v18, v135, v19
	v_max_f32_e32 v19, 0, v27
	v_fmac_f32_e32 v18, v134, v19
	v_max_f32_e32 v19, 0, v28
	v_fmac_f32_e32 v18, v133, v19
	v_max_f32_e32 v19, 0, v29
	v_fmac_f32_e32 v18, v132, v19
	v_max_f32_e32 v19, 0, v30
	v_fmac_f32_e32 v18, v131, v19
	v_max_f32_e32 v19, 0, v31
	v_fmac_f32_e32 v18, v130, v19
	v_max_f32_e32 v19, 0, v32
	v_fmac_f32_e32 v18, v129, v19
	v_max_f32_e32 v19, 0, v33
	v_fmac_f32_e32 v18, v128, v19
	v_ashrrev_i32_e32 v19, 31, v18
	v_bitop3_b32 v18, v19, v18, s8 bitop3:0x36
	v_cndmask_b32_e32 v198, 0, v18, vcc
	s_cmp_lt_u32 s0, 0x600
	s_cbranch_scc1 .Lix_z48
.Lix_b48:
	s_cmp_lt_u32 s0, 0x660
	s_cbranch_scc1 .Lix_w48
	s_waitcnt vmcnt(12)
	s_branch .Lix_m48

; #define MFMA(a, b, c) __builtin_amdgcn_mfma_f32_32x32x16_bf16((a), (b), (c), 0, 0, 0)
; DI unsigned ordkey(float f) { const unsigned b = __float_as_uint(f); return b ^ ((unsigned)((int)b >> 31) | 0x80000000u); }
; DI void indexer_phase(const u16* __restrict__ P, unsigned* __restrict__ mask) {
;     ...
;     for (int kb = 0; kb < 64; ++kb) {
;       unsigned u = 0u;
;       if (kb <= kbmax) {
;         f32x16 a;
; #pragma unroll
;         for (int r = 0; r < 16; ++r) a[r] = 0.f;
;         const u16* kp = P + (brow + 32 * kb + r32) * 7808 + 3584 + 8 * hi;
; #pragma unroll
;         for (int s = 0; s < 4; ++s) { const bf16x8 bk = *(const bf16x8*)(kp + 16 * s); a = MFMA(aq[s], bk, a); }
;         float v = 0.f;
; #pragma unroll
;         for (int i = 0; i < 16; ++i) v = fmaf(wv[i], fmaxf(a[i], 0.f), v);
;         u = (32 * kb + r32 <= tme) ? ordkey(v) : 0u;
;       }
;       sc[kb] = u;
.Lix_m48:
	v_cmp_le_i32_e32 vcc, 0x600, v16
	v_mfma_f32_32x32x16_bf16 v[18:33], v[46:49], v[64:67], 0
	v_mfma_f32_32x32x16_bf16 v[18:33], v[42:45], v[68:71], v[18:33]
	v_mfma_f32_32x32x16_bf16 v[18:33], v[38:41], v[72:75], v[18:33]
	v_mfma_f32_32x32x16_bf16 v[18:33], v[34:37], v[76:79], v[18:33]
	s_cmp_lt_u32 s0, 0x680
	s_cbranch_scc1 .Lix_np48
	global_load_dwordx4 v[64:67], v[124:125], off
	global_load_dwordx4 v[68:71], v[124:125], off offset:32
	global_load_dwordx4 v[72:75], v[124:125], off offset:64
	global_load_dwordx4 v[76:79], v[124:125], off offset:96
	v_lshl_add_u64 v[124:125], v[124:125], 0, s[22:23]
.Lix_np48:
	s_nop 10
	v_max_f32_e32 v18, 0, v18
	v_max_f32_e32 v19, 0, v19
	v_fma_f32 v18, v143, v18, 0
	v_fmac_f32_e32 v18, v142, v19
	v_max_f32_e32 v19, 0, v20
	v_fmac_f32_e32 v18, v141, v19
	v_max_f32_e32 v19, 0, v21
	v_fmac_f32_e32 v18, v140, v19
	v_max_f32_e32 v19, 0, v22
	v_fmac_f32_e32 v18, v139, v19
	v_max_f32_e32 v19, 0, v23
	v_fmac_f32_e32 v18, v138, v19
	v_max_f32_e32 v19, 0, v24
	v_fmac_f32_e32 v18, v137, v19
	v_max_f32_e32 v19, 0, v25
	v_fmac_f32_e32 v18, v136, v19
	v_max_f32_e32 v19, 0, v26
	v_fmac_f32_e32 v18, v135, v19
	v_max_f32_e32 v19, 0, v27
	v_fmac_f32_e32 v18, v134, v19
	v_max_f32_e32 v19, 0, v28
	v_fmac_f32_e32 v18, v133, v19
	v_max_f32_e32 v19, 0, v29
	v_fmac_f32_e32 v18, v132, v19
	v_max_f32_e32 v19, 0, v30
	v_fmac_f32_e32 v18, v131, v19
	v_max_f32_e32 v19, 0, v31
	v_fmac_f32_e32 v18, v130, v19
	v_max_f32_e32 v19, 0, v32
	v_fmac_f32_e32 v18, v129, v19
	v_max_f32_e32 v19, 0, v33
	v_fmac_f32_e32 v18, v128, v19
	v_ashrrev_i32_e32 v19, 31, v18
	v_bitop3_b32 v18, v19, v18, s8 bitop3:0x36
	v_cndmask_b32_e32 v197, 0, v18, vcc
	s_cmp_lt_u32 s0, 0x620
	s_cbranch_scc1 .Lix_z49
.Lix_b49:
	s_cmp_lt_u32 s0, 0x680
	s_cbranch_scc1 .Lix_w49
	s_waitcnt vmcnt(12)
	s_branch .Lix_m49

; #define MFMA(a, b, c) __builtin_amdgcn_mfma_f32_32x32x16_bf16((a), (b), (c), 0, 0, 0)
; DI unsigned ordkey(float f) { const unsigned b = __float_as_uint(f); return b ^ ((unsigned)((int)b >> 31) | 0x80000000u); }
; DI void indexer_phase(const u16* __restrict__ P, unsigned* __restrict__ mask) {
;     ...
;     for (int kb = 0; kb < 64; ++kb) {
;       unsigned u = 0u;
;       if (kb <= kbmax) {
;         f32x16 a;
; #pragma unroll
;         for (int r = 0; r < 16; ++r) a[r] = 0.f;
;         const u16* kp = P + (brow + 32 * kb + r32) * 7808 + 3584 + 8 * hi;
; #pragma unroll
;         for (int s = 0; s < 4; ++s) { const bf16x8 bk = *(const bf16x8*)(kp + 16 * s); a = MFMA(aq[s], bk, a); }
;         float v = 0.f;
; #pragma unroll
;         for (int i = 0; i < 16; ++i) v = fmaf(wv[i], fmaxf(a[i], 0.f), v);
;         u = (32 * kb + r32 <= tme) ? ordkey(v) : 0u;
;       }
;       sc[kb] = u;
.Lix_m49:
	v_cmp_le_i32_e32 vcc, 0x620, v16
	v_mfma_f32_32x32x16_bf16 v[18:33], v[46:49], v[80:83], 0
	v_mfma_f32_32x32x16_bf16 v[18:33], v[42:45], v[84:87], v[18:33]
	v_mfma_f32_32x32x16_bf16 v[18:33], v[38:41], v[88:91], v[18:33]
	v_mfma_f32_32x32x16_bf16 v[18:33], v[34:37], v[92:95], v[18:33]
	s_cmp_lt_u32 s0, 0x6a0
	s_cbranch_scc1 .Lix_np49
	global_load_dwordx4 v[80:83], v[124:125], off
	global_load_dwordx4 v[84:87], v[124:125], off offset:32
	global_load_dwordx4 v[88:91], v[124:125], off offset:64
	global_load_dwordx4 v[92:95], v[124:125], off offset:96
	v_lshl_add_u64 v[124:125], v[124:125], 0, s[22:23]
.Lix_np49:
	s_nop 10
	v_max_f32_e32 v18, 0, v18
	v_max_f32_e32 v19, 0, v19
	v_fma_f32 v18, v143, v18, 0
	v_fmac_f32_e32 v18, v142, v19
	v_max_f32_e32 v19, 0, v20
	v_fmac_f32_e32 v18, v141, v19
	v_max_f32_e32 v19, 0, v21
	v_fmac_f32_e32 v18, v140, v19
	v_max_f32_e32 v19, 0, v22
	v_fmac_f32_e32 v18, v139, v19
	v_max_f32_e32 v19, 0, v23
	v_fmac_f32_e32 v18, v138, v19
	v_max_f32_e32 v19, 0, v24
	v_fmac_f32_e32 v18, v137, v19
	v_max_f32_e32 v19, 0, v25
	v_fmac_f32_e32 v18, v136, v19
	v_max_f32_e32 v19, 0, v26
	v_fmac_f32_e32 v18, v135, v19
	v_max_f32_e32 v19, 0, v27
	v_fmac_f32_e32 v18, v134, v19
	v_max_f32_e32 v19, 0, v28
	v_fmac_f32_e32 v18, v133, v19
	v_max_f32_e32 v19, 0, v29
	v_fmac_f32_e32 v18, v132, v19
	v_max_f32_e32 v19, 0, v30
	v_fmac_f32_e32 v18, v131, v19
	v_max_f32_e32 v19, 0, v31
	v_fmac_f32_e32 v18, v130, v19
	v_max_f32_e32 v19, 0, v32
	v_fmac_f32_e32 v18, v129, v19
	v_max_f32_e32 v19, 0, v33
	v_fmac_f32_e32 v18, v128, v19
	v_ashrrev_i32_e32 v19, 31, v18
	v_bitop3_b32 v18, v19, v18, s8 bitop3:0x36
	v_cndmask_b32_e32 v200, 0, v18, vcc
	s_cmp_lt_u32 s0, 0x640
	s_cbranch_scc1 .Lix_z50
.Lix_b50:
	s_cmp_lt_u32 s0, 0x6a0
	s_cbranch_scc1 .Lix_w50
	s_waitcnt vmcnt(12)
	s_branch .Lix_m50

; #define MFMA(a, b, c) __builtin_amdgcn_mfma_f32_32x32x16_bf16((a), (b), (c), 0, 0, 0)
; DI unsigned ordkey(float f) { const unsigned b = __float_as_uint(f); return b ^ ((unsigned)((int)b >> 31) | 0x80000000u); }
; DI void indexer_phase(const u16* __restrict__ P, unsigned* __restrict__ mask) {
;     ...
;     for (int kb = 0; kb < 64; ++kb) {
;       unsigned u = 0u;
;       if (kb <= kbmax) {
;         f32x16 a;
; #pragma unroll
;         for (int r = 0; r < 16; ++r) a[r] = 0.f;
;         const u16* kp = P + (brow + 32 * kb + r32) * 7808 + 3584 + 8 * hi;
; #pragma unroll
;         for (int s = 0; s < 4; ++s) { const bf16x8 bk = *(const bf16x8*)(kp + 16 * s); a = MFMA(aq[s], bk, a); }
;         float v = 0.f;
; #pragma unroll
;         for (int i = 0; i < 16; ++i) v = fmaf(wv[i], fmaxf(a[i], 0.f), v);
;         u = (32 * kb + r32 <= tme) ? ordkey(v) : 0u;
;       }
;       sc[kb] = u;
.Lix_m50:
	v_cmp_le_i32_e32 vcc, 0x640, v16
	v_mfma_f32_32x32x16_bf16 v[18:33], v[46:49], v[96:99], 0
	v_mfma_f32_32x32x16_bf16 v[18:33], v[42:45], v[100:103], v[18:33]
	v_mfma_f32_32x32x16_bf16 v[18:33], v[38:41], v[104:107], v[18:33]
	v_mfma_f32_32x32x16_bf16 v[18:33], v[34:37], v[108:111], v[18:33]
	s_cmp_lt_u32 s0, 0x6c0
	s_cbranch_scc1 .Lix_np50
	global_load_dwordx4 v[96:99], v[124:125], off
	global_load_dwordx4 v[100:103], v[124:125], off offset:32
	global_load_dwordx4 v[104:107], v[124:125], off offset:64
	global_load_dwordx4 v[108:111], v[124:125], off offset:96
	v_lshl_add_u64 v[124:125], v[124:125], 0, s[22:23]
.Lix_np50:
	s_nop 10
	v_max_f32_e32 v18, 0, v18
	v_max_f32_e32 v19, 0, v19
	v_fma_f32 v18, v143, v18, 0
	v_fmac_f32_e32 v18, v142, v19
	v_max_f32_e32 v19, 0, v20
	v_fmac_f32_e32 v18, v141, v19
	v_max_f32_e32 v19, 0, v21
	v_fmac_f32_e32 v18, v140, v19
	v_max_f32_e32 v19, 0, v22
	v_fmac_f32_e32 v18, v139, v19
	v_max_f32_e32 v19, 0, v23
	v_fmac_f32_e32 v18, v138, v19
	v_max_f32_e32 v19, 0, v24
	v_fmac_f32_e32 v18, v137, v19
	v_max_f32_e32 v19, 0, v25
	v_fmac_f32_e32 v18, v136, v19
	v_max_f32_e32 v19, 0, v26
	v_fmac_f32_e32 v18, v135, v19
	v_max_f32_e32 v19, 0, v27
	v_fmac_f32_e32 v18, v134, v19
	v_max_f32_e32 v19, 0, v28
	v_fmac_f32_e32 v18, v133, v19
	v_max_f32_e32 v19, 0, v29
	v_fmac_f32_e32 v18, v132, v19
	v_max_f32_e32 v19, 0, v30
	v_fmac_f32_e32 v18, v131, v19
	v_max_f32_e32 v19, 0, v31
	v_fmac_f32_e32 v18, v130, v19
	v_max_f32_e32 v19, 0, v32
	v_fmac_f32_e32 v18, v129, v19
	v_max_f32_e32 v19, 0, v33
	v_fmac_f32_e32 v18, v128, v19
	v_ashrrev_i32_e32 v19, 31, v18
	v_bitop3_b32 v18, v19, v18, s8 bitop3:0x36
	v_cndmask_b32_e32 v199, 0, v18, vcc
	s_cmp_lt_u32 s0, 0x660
	s_cbranch_scc1 .Lix_z51
.Lix_b51:
	s_cmp_lt_u32 s0, 0x6c0
	s_cbranch_scc1 .Lix_w51
	s_waitcnt vmcnt(12)
	s_branch .Lix_m51

; #define MFMA(a, b, c) __builtin_amdgcn_mfma_f32_32x32x16_bf16((a), (b), (c), 0, 0, 0)
; DI unsigned ordkey(float f) { const unsigned b = __float_as_uint(f); return b ^ ((unsigned)((int)b >> 31) | 0x80000000u); }
; DI void indexer_phase(const u16* __restrict__ P, unsigned* __restrict__ mask) {
;     ...
;     for (int kb = 0; kb < 64; ++kb) {
;       unsigned u = 0u;
;       if (kb <= kbmax) {
;         f32x16 a;
; #pragma unroll
;         for (int r = 0; r < 16; ++r) a[r] = 0.f;
;         const u16* kp = P + (brow + 32 * kb + r32) * 7808 + 3584 + 8 * hi;
; #pragma unroll
;         for (int s = 0; s < 4; ++s) { const bf16x8 bk = *(const bf16x8*)(kp + 16 * s); a = MFMA(aq[s], bk, a); }
;         float v = 0.f;
; #pragma unroll
;         for (int i = 0; i < 16; ++i) v = fmaf(wv[i], fmaxf(a[i], 0.f), v);
;         u = (32 * kb + r32 <= tme) ? ordkey(v) : 0u;
;       }
;       sc[kb] = u;
.Lix_m51:
	v_cmp_le_i32_e32 vcc, 0x660, v16
	v_mfma_f32_32x32x16_bf16 v[18:33], v[46:49], v[112:115], 0
	v_mfma_f32_32x32x16_bf16 v[18:33], v[42:45], v[116:119], v[18:33]
	v_mfma_f32_32x32x16_bf16 v[18:33], v[38:41], v[120:123], v[18:33]
	v_mfma_f32_32x32x16_bf16 v[18:33], v[34:37], v[12:15], v[18:33]
	s_cmp_lt_u32 s0, 0x6e0
	s_cbranch_scc1 .Lix_np51
	global_load_dwordx4 v[112:115], v[124:125], off
	global_load_dwordx4 v[116:119], v[124:125], off offset:32
	global_load_dwordx4 v[120:123], v[124:125], off offset:64
	global_load_dwordx4 v[12:15], v[124:125], off offset:96
	v_lshl_add_u64 v[124:125], v[124:125], 0, s[22:23]
.Lix_np51:
	s_nop 10
	v_max_f32_e32 v18, 0, v18
	v_max_f32_e32 v19, 0, v19
	v_fma_f32 v18, v143, v18, 0
	v_fmac_f32_e32 v18, v142, v19
	v_max_f32_e32 v19, 0, v20
	v_fmac_f32_e32 v18, v141, v19
	v_max_f32_e32 v19, 0, v21
	v_fmac_f32_e32 v18, v140, v19
	v_max_f32_e32 v19, 0, v22
	v_fmac_f32_e32 v18, v139, v19
	v_max_f32_e32 v19, 0, v23
	v_fmac_f32_e32 v18, v138, v19
	v_max_f32_e32 v19, 0, v24
	v_fmac_f32_e32 v18, v137, v19
	v_max_f32_e32 v19, 0, v25
	v_fmac_f32_e32 v18, v136, v19
	v_max_f32_e32 v19, 0, v26
	v_fmac_f32_e32 v18, v135, v19
	v_max_f32_e32 v19, 0, v27
	v_fmac_f32_e32 v18, v134, v19
	v_max_f32_e32 v19, 0, v28
	v_fmac_f32_e32 v18, v133, v19
	v_max_f32_e32 v19, 0, v29
	v_fmac_f32_e32 v18, v132, v19
	v_max_f32_e32 v19, 0, v30
	v_fmac_f32_e32 v18, v131, v19
	v_max_f32_e32 v19, 0, v31
	v_fmac_f32_e32 v18, v130, v19
	v_max_f32_e32 v19, 0, v32
	v_fmac_f32_e32 v18, v129, v19
	v_max_f32_e32 v19, 0, v33
	v_fmac_f32_e32 v18, v128, v19
	v_ashrrev_i32_e32 v19, 31, v18
	v_bitop3_b32 v18, v19, v18, s8 bitop3:0x36
	v_cndmask_b32_e32 v202, 0, v18, vcc
	s_cmp_lt_u32 s0, 0x680
	s_cbranch_scc1 .Lix_z52
.Lix_b52:
	s_cmp_lt_u32 s0, 0x6e0
	s_cbranch_scc1 .Lix_w52
	s_waitcnt vmcnt(12)
	s_branch .Lix_m52

; #define MFMA(a, b, c) __builtin_amdgcn_mfma_f32_32x32x16_bf16((a), (b), (c), 0, 0, 0)
; DI unsigned ordkey(float f) { const unsigned b = __float_as_uint(f); return b ^ ((unsigned)((int)b >> 31) | 0x80000000u); }
; DI void indexer_phase(const u16* __restrict__ P, unsigned* __restrict__ mask) {
;     ...
;     for (int kb = 0; kb < 64; ++kb) {
;       unsigned u = 0u;
;       if (kb <= kbmax) {
;         f32x16 a;
; #pragma unroll
;         for (int r = 0; r < 16; ++r) a[r] = 0.f;
;         const u16* kp = P + (brow + 32 * kb + r32) * 7808 + 3584 + 8 * hi;
; #pragma unroll
;         for (int s = 0; s < 4; ++s) { const bf16x8 bk = *(const bf16x8*)(kp + 16 * s); a = MFMA(aq[s], bk, a); }
;         float v = 0.f;
; #pragma unroll
;         for (int i = 0; i < 16; ++i) v = fmaf(wv[i], fmaxf(a[i], 0.f), v);
;         u = (32 * kb + r32 <= tme) ? ordkey(v) : 0u;
;       }
;       sc[kb] = u;
.Lix_m52:
	v_cmp_le_i32_e32 vcc, 0x680, v16
	v_mfma_f32_32x32x16_bf16 v[18:33], v[46:49], v[64:67], 0
	v_mfma_f32_32x32x16_bf16 v[18:33], v[42:45], v[68:71], v[18:33]
	v_mfma_f32_32x32x16_bf16 v[18:33], v[38:41], v[72:75], v[18:33]
	v_mfma_f32_32x32x16_bf16 v[18:33], v[34:37], v[76:79], v[18:33]
	s_cmp_lt_u32 s0, 0x700
	s_cbranch_scc1 .Lix_np52
	global_load_dwordx4 v[64:67], v[124:125], off
	global_load_dwordx4 v[68:71], v[124:125], off offset:32
	global_load_dwordx4 v[72:75], v[124:125], off offset:64
	global_load_dwordx4 v[76:79], v[124:125], off offset:96
	v_lshl_add_u64 v[124:125], v[124:125], 0, s[22:23]
.Lix_np52:
	s_nop 10
	v_max_f32_e32 v18, 0, v18
	v_max_f32_e32 v19, 0, v19
	v_fma_f32 v18, v143, v18, 0
	v_fmac_f32_e32 v18, v142, v19
	v_max_f32_e32 v19, 0, v20
	v_fmac_f32_e32 v18, v141, v19
	v_max_f32_e32 v19, 0, v21
	v_fmac_f32_e32 v18, v140, v19
	v_max_f32_e32 v19, 0, v22
	v_fmac_f32_e32 v18, v139, v19
	v_max_f32_e32 v19, 0, v23
	v_fmac_f32_e32 v18, v138, v19
	v_max_f32_e32 v19, 0, v24
	v_fmac_f32_e32 v18, v137, v19
	v_max_f32_e32 v19, 0, v25
	v_fmac_f32_e32 v18, v136, v19
	v_max_f32_e32 v19, 0, v26
	v_fmac_f32_e32 v18, v135, v19
	v_max_f32_e32 v19, 0, v27
	v_fmac_f32_e32 v18, v134, v19
	v_max_f32_e32 v19, 0, v28
	v_fmac_f32_e32 v18, v133, v19
	v_max_f32_e32 v19, 0, v29
	v_fmac_f32_e32 v18, v132, v19
	v_max_f32_e32 v19, 0, v30
	v_fmac_f32_e32 v18, v131, v19
	v_max_f32_e32 v19, 0, v31
	v_fmac_f32_e32 v18, v130, v19
	v_max_f32_e32 v19, 0, v32
	v_fmac_f32_e32 v18, v129, v19
	v_max_f32_e32 v19, 0, v33
	v_fmac_f32_e32 v18, v128, v19
	v_ashrrev_i32_e32 v19, 31, v18
	v_bitop3_b32 v18, v19, v18, s8 bitop3:0x36
	v_cndmask_b32_e32 v201, 0, v18, vcc
	s_cmp_lt_u32 s0, 0x6a0
	s_cbranch_scc1 .Lix_z53
.Lix_b53:
	s_cmp_lt_u32 s0, 0x700
	s_cbranch_scc1 .Lix_w53
	s_waitcnt vmcnt(12)
	s_branch .Lix_m53

; #define MFMA(a, b, c) __builtin_amdgcn_mfma_f32_32x32x16_bf16((a), (b), (c), 0, 0, 0)
; DI unsigned ordkey(float f) { const unsigned b = __float_as_uint(f); return b ^ ((unsigned)((int)b >> 31) | 0x80000000u); }
; DI void indexer_phase(const u16* __restrict__ P, unsigned* __restrict__ mask) {
;     ...
;     for (int kb = 0; kb < 64; ++kb) {
;       unsigned u = 0u;
;       if (kb <= kbmax) {
;         f32x16 a;
; #pragma unroll
;         for (int r = 0; r < 16; ++r) a[r] = 0.f;
;         const u16* kp = P + (brow + 32 * kb + r32) * 7808 + 3584 + 8 * hi;
; #pragma unroll
;         for (int s = 0; s < 4; ++s) { const bf16x8 bk = *(const bf16x8*)(kp + 16 * s); a = MFMA(aq[s], bk, a); }
;         float v = 0.f;
; #pragma unroll
;         for (int i = 0; i < 16; ++i) v = fmaf(wv[i], fmaxf(a[i], 0.f), v);
;         u = (32 * kb + r32 <= tme) ? ordkey(v) : 0u;
;       }
;       sc[kb] = u;
.Lix_m53:
	v_cmp_le_i32_e32 vcc, 0x6a0, v16
	v_mfma_f32_32x32x16_bf16 v[18:33], v[46:49], v[80:83], 0
	v_mfma_f32_32x32x16_bf16 v[18:33], v[42:45], v[84:87], v[18:33]
	v_mfma_f32_32x32x16_bf16 v[18:33], v[38:41], v[88:91], v[18:33]
	v_mfma_f32_32x32x16_bf16 v[18:33], v[34:37], v[92:95], v[18:33]
	s_cmp_lt_u32 s0, 0x720
	s_cbranch_scc1 .Lix_np53
	global_load_dwordx4 v[80:83], v[124:125], off
	global_load_dwordx4 v[84:87], v[124:125], off offset:32
	global_load_dwordx4 v[88:91], v[124:125], off offset:64
	global_load_dwordx4 v[92:95], v[124:125], off offset:96
	v_lshl_add_u64 v[124:125], v[124:125], 0, s[22:23]
.Lix_np53:
	s_nop 10
	v_max_f32_e32 v18, 0, v18
	v_max_f32_e32 v19, 0, v19
	v_fma_f32 v18, v143, v18, 0
	v_fmac_f32_e32 v18, v142, v19
	v_max_f32_e32 v19, 0, v20
	v_fmac_f32_e32 v18, v141, v19
	v_max_f32_e32 v19, 0, v21
	v_fmac_f32_e32 v18, v140, v19
	v_max_f32_e32 v19, 0, v22
	v_fmac_f32_e32 v18, v139, v19
	v_max_f32_e32 v19, 0, v23
	v_fmac_f32_e32 v18, v138, v19
	v_max_f32_e32 v19, 0, v24
	v_fmac_f32_e32 v18, v137, v19
	v_max_f32_e32 v19, 0, v25
	v_fmac_f32_e32 v18, v136, v19
	v_max_f32_e32 v19, 0, v26
	v_fmac_f32_e32 v18, v135, v19
	v_max_f32_e32 v19, 0, v27
	v_fmac_f32_e32 v18, v134, v19
	v_max_f32_e32 v19, 0, v28
	v_fmac_f32_e32 v18, v133, v19
	v_max_f32_e32 v19, 0, v29
	v_fmac_f32_e32 v18, v132, v19
	v_max_f32_e32 v19, 0, v30
	v_fmac_f32_e32 v18, v131, v19
	v_max_f32_e32 v19, 0, v31
	v_fmac_f32_e32 v18, v130, v19
	v_max_f32_e32 v19, 0, v32
	v_fmac_f32_e32 v18, v129, v19
	v_max_f32_e32 v19, 0, v33
	v_fmac_f32_e32 v18, v128, v19
	v_ashrrev_i32_e32 v19, 31, v18
	v_bitop3_b32 v18, v19, v18, s8 bitop3:0x36
	v_cndmask_b32_e32 v204, 0, v18, vcc
	s_cmp_lt_u32 s0, 0x6c0
	s_cbranch_scc1 .Lix_z54
.Lix_b54:
	s_cmp_lt_u32 s0, 0x720
	s_cbranch_scc1 .Lix_w54
	s_waitcnt vmcnt(12)
	s_branch .Lix_m54

; #define MFMA(a, b, c) __builtin_amdgcn_mfma_f32_32x32x16_bf16((a), (b), (c), 0, 0, 0)
; DI unsigned ordkey(float f) { const unsigned b = __float_as_uint(f); return b ^ ((unsigned)((int)b >> 31) | 0x80000000u); }
; DI void indexer_phase(const u16* __restrict__ P, unsigned* __restrict__ mask) {
;     ...
;     for (int kb = 0; kb < 64; ++kb) {
;       unsigned u = 0u;
;       if (kb <= kbmax) {
;         f32x16 a;
; #pragma unroll
;         for (int r = 0; r < 16; ++r) a[r] = 0.f;
;         const u16* kp = P + (brow + 32 * kb + r32) * 7808 + 3584 + 8 * hi;
; #pragma unroll
;         for (int s = 0; s < 4; ++s) { const bf16x8 bk = *(const bf16x8*)(kp + 16 * s); a = MFMA(aq[s], bk, a); }
;         float v = 0.f;
; #pragma unroll
;         for (int i = 0; i < 16; ++i) v = fmaf(wv[i], fmaxf(a[i], 0.f), v);
;         u = (32 * kb + r32 <= tme) ? ordkey(v) : 0u;
;       }
;       sc[kb] = u;
.Lix_m54:
	v_cmp_le_i32_e32 vcc, 0x6c0, v16
	v_mfma_f32_32x32x16_bf16 v[18:33], v[46:49], v[96:99], 0
	v_mfma_f32_32x32x16_bf16 v[18:33], v[42:45], v[100:103], v[18:33]
	v_mfma_f32_32x32x16_bf16 v[18:33], v[38:41], v[104:107], v[18:33]
	v_mfma_f32_32x32x16_bf16 v[18:33], v[34:37], v[108:111], v[18:33]
	s_cmp_lt_u32 s0, 0x740
	s_cbranch_scc1 .Lix_np54
	global_load_dwordx4 v[96:99], v[124:125], off
	global_load_dwordx4 v[100:103], v[124:125], off offset:32
	global_load_dwordx4 v[104:107], v[124:125], off offset:64
	global_load_dwordx4 v[108:111], v[124:125], off offset:96
	v_lshl_add_u64 v[124:125], v[124:125], 0, s[22:23]
.Lix_np54:
	s_nop 10
	v_max_f32_e32 v18, 0, v18
	v_max_f32_e32 v19, 0, v19
	v_fma_f32 v18, v143, v18, 0
	v_fmac_f32_e32 v18, v142, v19
	v_max_f32_e32 v19, 0, v20
	v_fmac_f32_e32 v18, v141, v19
	v_max_f32_e32 v19, 0, v21
	v_fmac_f32_e32 v18, v140, v19
	v_max_f32_e32 v19, 0, v22
	v_fmac_f32_e32 v18, v139, v19
	v_max_f32_e32 v19, 0, v23
	v_fmac_f32_e32 v18, v138, v19
	v_max_f32_e32 v19, 0, v24
	v_fmac_f32_e32 v18, v137, v19
	v_max_f32_e32 v19, 0, v25
	v_fmac_f32_e32 v18, v136, v19
	v_max_f32_e32 v19, 0, v26
	v_fmac_f32_e32 v18, v135, v19
	v_max_f32_e32 v19, 0, v27
	v_fmac_f32_e32 v18, v134, v19
	v_max_f32_e32 v19, 0, v28
	v_fmac_f32_e32 v18, v133, v19
	v_max_f32_e32 v19, 0, v29
	v_fmac_f32_e32 v18, v132, v19
	v_max_f32_e32 v19, 0, v30
	v_fmac_f32_e32 v18, v131, v19
	v_max_f32_e32 v19, 0, v31
	v_fmac_f32_e32 v18, v130, v19
	v_max_f32_e32 v19, 0, v32
	v_fmac_f32_e32 v18, v129, v19
	v_max_f32_e32 v19, 0, v33
	v_fmac_f32_e32 v18, v128, v19
	v_ashrrev_i32_e32 v19, 31, v18
	v_bitop3_b32 v18, v19, v18, s8 bitop3:0x36
	v_cndmask_b32_e32 v203, 0, v18, vcc
	s_cmp_lt_u32 s0, 0x6e0
	s_cbranch_scc1 .Lix_z55
.Lix_b55:
	s_cmp_lt_u32 s0, 0x740
	s_cbranch_scc1 .Lix_w55
	s_waitcnt vmcnt(12)
	s_branch .Lix_m55

; #define MFMA(a, b, c) __builtin_amdgcn_mfma_f32_32x32x16_bf16((a), (b), (c), 0, 0, 0)
; DI unsigned ordkey(float f) { const unsigned b = __float_as_uint(f); return b ^ ((unsigned)((int)b >> 31) | 0x80000000u); }
; DI void indexer_phase(const u16* __restrict__ P, unsigned* __restrict__ mask) {
;     ...
;     for (int kb = 0; kb < 64; ++kb) {
;       unsigned u = 0u;
;       if (kb <= kbmax) {
;         f32x16 a;
; #pragma unroll
;         for (int r = 0; r < 16; ++r) a[r] = 0.f;
;         const u16* kp = P + (brow + 32 * kb + r32) * 7808 + 3584 + 8 * hi;
; #pragma unroll
;         for (int s = 0; s < 4; ++s) { const bf16x8 bk = *(const bf16x8*)(kp + 16 * s); a = MFMA(aq[s], bk, a); }
;         float v = 0.f;
; #pragma unroll
;         for (int i = 0; i < 16; ++i) v = fmaf(wv[i], fmaxf(a[i], 0.f), v);
;         u = (32 * kb + r32 <= tme) ? ordkey(v) : 0u;
;       }
;       sc[kb] = u;
.Lix_m55:
	v_cmp_le_i32_e32 vcc, 0x6e0, v16
	v_mfma_f32_32x32x16_bf16 v[18:33], v[46:49], v[112:115], 0
	v_mfma_f32_32x32x16_bf16 v[18:33], v[42:45], v[116:119], v[18:33]
	v_mfma_f32_32x32x16_bf16 v[18:33], v[38:41], v[120:123], v[18:33]
	v_mfma_f32_32x32x16_bf16 v[18:33], v[34:37], v[12:15], v[18:33]
	s_cmp_lt_u32 s0, 0x760
	s_cbranch_scc1 .Lix_np55
	global_load_dwordx4 v[112:115], v[124:125], off
	global_load_dwordx4 v[116:119], v[124:125], off offset:32
	global_load_dwordx4 v[120:123], v[124:125], off offset:64
	global_load_dwordx4 v[12:15], v[124:125], off offset:96
	v_lshl_add_u64 v[124:125], v[124:125], 0, s[22:23]
.Lix_np55:
	s_nop 10
	v_max_f32_e32 v18, 0, v18
	v_max_f32_e32 v19, 0, v19
	v_fma_f32 v18, v143, v18, 0
	v_fmac_f32_e32 v18, v142, v19
	v_max_f32_e32 v19, 0, v20
	v_fmac_f32_e32 v18, v141, v19
	v_max_f32_e32 v19, 0, v21
	v_fmac_f32_e32 v18, v140, v19
	v_max_f32_e32 v19, 0, v22
	v_fmac_f32_e32 v18, v139, v19
	v_max_f32_e32 v19, 0, v23
	v_fmac_f32_e32 v18, v138, v19
	v_max_f32_e32 v19, 0, v24
	v_fmac_f32_e32 v18, v137, v19
	v_max_f32_e32 v19, 0, v25
	v_fmac_f32_e32 v18, v136, v19
	v_max_f32_e32 v19, 0, v26
	v_fmac_f32_e32 v18, v135, v19
	v_max_f32_e32 v19, 0, v27
	v_fmac_f32_e32 v18, v134, v19
	v_max_f32_e32 v19, 0, v28
	v_fmac_f32_e32 v18, v133, v19
	v_max_f32_e32 v19, 0, v29
	v_fmac_f32_e32 v18, v132, v19
	v_max_f32_e32 v19, 0, v30
	v_fmac_f32_e32 v18, v131, v19
	v_max_f32_e32 v19, 0, v31
	v_fmac_f32_e32 v18, v130, v19
	v_max_f32_e32 v19, 0, v32
	v_fmac_f32_e32 v18, v129, v19
	v_max_f32_e32 v19, 0, v33
	v_fmac_f32_e32 v18, v128, v19
	v_ashrrev_i32_e32 v19, 31, v18
	v_bitop3_b32 v18, v19, v18, s8 bitop3:0x36
	v_cndmask_b32_e32 v206, 0, v18, vcc
	s_cmp_lt_u32 s0, 0x700
	s_cbranch_scc1 .Lix_z56
.Lix_b56:
	s_cmp_lt_u32 s0, 0x760
	s_cbranch_scc1 .Lix_w56
	s_waitcnt vmcnt(12)
	s_branch .Lix_m56

; #define MFMA(a, b, c) __builtin_amdgcn_mfma_f32_32x32x16_bf16((a), (b), (c), 0, 0, 0)
; DI unsigned ordkey(float f) { const unsigned b = __float_as_uint(f); return b ^ ((unsigned)((int)b >> 31) | 0x80000000u); }
; DI void indexer_phase(const u16* __restrict__ P, unsigned* __restrict__ mask) {
;     ...
;     for (int kb = 0; kb < 64; ++kb) {
;       unsigned u = 0u;
;       if (kb <= kbmax) {
;         f32x16 a;
; #pragma unroll
;         for (int r = 0; r < 16; ++r) a[r] = 0.f;
;         const u16* kp = P + (brow + 32 * kb + r32) * 7808 + 3584 + 8 * hi;
; #pragma unroll
;         for (int s = 0; s < 4; ++s) { const bf16x8 bk = *(const bf16x8*)(kp + 16 * s); a = MFMA(aq[s], bk, a); }
;         float v = 0.f;
; #pragma unroll
;         for (int i = 0; i < 16; ++i) v = fmaf(wv[i], fmaxf(a[i], 0.f), v);
;         u = (32 * kb + r32 <= tme) ? ordkey(v) : 0u;
;       }
;       sc[kb] = u;
.Lix_m56:
	v_cmp_le_i32_e32 vcc, 0x700, v16
	v_mfma_f32_32x32x16_bf16 v[18:33], v[46:49], v[64:67], 0
	v_mfma_f32_32x32x16_bf16 v[18:33], v[42:45], v[68:71], v[18:33]
	v_mfma_f32_32x32x16_bf16 v[18:33], v[38:41], v[72:75], v[18:33]
	v_mfma_f32_32x32x16_bf16 v[18:33], v[34:37], v[76:79], v[18:33]
	s_cmp_lt_u32 s0, 0x780
	s_cbranch_scc1 .Lix_np56
	global_load_dwordx4 v[64:67], v[124:125], off
	global_load_dwordx4 v[68:71], v[124:125], off offset:32
	global_load_dwordx4 v[72:75], v[124:125], off offset:64
	global_load_dwordx4 v[76:79], v[124:125], off offset:96
	v_lshl_add_u64 v[124:125], v[124:125], 0, s[22:23]
.Lix_np56:
	s_nop 10
	v_max_f32_e32 v18, 0, v18
	v_max_f32_e32 v19, 0, v19
	v_fma_f32 v18, v143, v18, 0
	v_fmac_f32_e32 v18, v142, v19
	v_max_f32_e32 v19, 0, v20
	v_fmac_f32_e32 v18, v141, v19
	v_max_f32_e32 v19, 0, v21
	v_fmac_f32_e32 v18, v140, v19
	v_max_f32_e32 v19, 0, v22
	v_fmac_f32_e32 v18, v139, v19
	v_max_f32_e32 v19, 0, v23
	v_fmac_f32_e32 v18, v138, v19
	v_max_f32_e32 v19, 0, v24
	v_fmac_f32_e32 v18, v137, v19
	v_max_f32_e32 v19, 0, v25
	v_fmac_f32_e32 v18, v136, v19
	v_max_f32_e32 v19, 0, v26
	v_fmac_f32_e32 v18, v135, v19
	v_max_f32_e32 v19, 0, v27
	v_fmac_f32_e32 v18, v134, v19
	v_max_f32_e32 v19, 0, v28
	v_fmac_f32_e32 v18, v133, v19
	v_max_f32_e32 v19, 0, v29
	v_fmac_f32_e32 v18, v132, v19
	v_max_f32_e32 v19, 0, v30
	v_fmac_f32_e32 v18, v131, v19
	v_max_f32_e32 v19, 0, v31
	v_fmac_f32_e32 v18, v130, v19
	v_max_f32_e32 v19, 0, v32
	v_fmac_f32_e32 v18, v129, v19
	v_max_f32_e32 v19, 0, v33
	v_fmac_f32_e32 v18, v128, v19
	v_ashrrev_i32_e32 v19, 31, v18
	v_bitop3_b32 v18, v19, v18, s8 bitop3:0x36
	v_cndmask_b32_e32 v205, 0, v18, vcc
	s_cmp_lt_u32 s0, 0x720
	s_cbranch_scc1 .Lix_z57
.Lix_b57:
	s_cmp_lt_u32 s0, 0x780
	s_cbranch_scc1 .Lix_w57
	s_waitcnt vmcnt(12)
	s_branch .Lix_m57

; #define MFMA(a, b, c) __builtin_amdgcn_mfma_f32_32x32x16_bf16((a), (b), (c), 0, 0, 0)
; DI unsigned ordkey(float f) { const unsigned b = __float_as_uint(f); return b ^ ((unsigned)((int)b >> 31) | 0x80000000u); }
; DI void indexer_phase(const u16* __restrict__ P, unsigned* __restrict__ mask) {
;     ...
;     for (int kb = 0; kb < 64; ++kb) {
;       unsigned u = 0u;
;       if (kb <= kbmax) {
;         f32x16 a;
; #pragma unroll
;         for (int r = 0; r < 16; ++r) a[r] = 0.f;
;         const u16* kp = P + (brow + 32 * kb + r32) * 7808 + 3584 + 8 * hi;
; #pragma unroll
;         for (int s = 0; s < 4; ++s) { const bf16x8 bk = *(const bf16x8*)(kp + 16 * s); a = MFMA(aq[s], bk, a); }
;         float v = 0.f;
; #pragma unroll
;         for (int i = 0; i < 16; ++i) v = fmaf(wv[i], fmaxf(a[i], 0.f), v);
;         u = (32 * kb + r32 <= tme) ? ordkey(v) : 0u;
;       }
;       sc[kb] = u;
.Lix_m57:
	v_cmp_le_i32_e32 vcc, 0x720, v16
	v_mfma_f32_32x32x16_bf16 v[18:33], v[46:49], v[80:83], 0
	v_mfma_f32_32x32x16_bf16 v[18:33], v[42:45], v[84:87], v[18:33]
	v_mfma_f32_32x32x16_bf16 v[18:33], v[38:41], v[88:91], v[18:33]
	v_mfma_f32_32x32x16_bf16 v[18:33], v[34:37], v[92:95], v[18:33]
	s_cmp_lt_u32 s0, 0x7a0
	s_cbranch_scc1 .Lix_np57
	global_load_dwordx4 v[80:83], v[124:125], off
	global_load_dwordx4 v[84:87], v[124:125], off offset:32
	global_load_dwordx4 v[88:91], v[124:125], off offset:64
	global_load_dwordx4 v[92:95], v[124:125], off offset:96
	v_lshl_add_u64 v[124:125], v[124:125], 0, s[22:23]
.Lix_np57:
	s_nop 10
	v_max_f32_e32 v18, 0, v18
	v_max_f32_e32 v19, 0, v19
	v_fma_f32 v18, v143, v18, 0
	v_fmac_f32_e32 v18, v142, v19
	v_max_f32_e32 v19, 0, v20
	v_fmac_f32_e32 v18, v141, v19
	v_max_f32_e32 v19, 0, v21
	v_fmac_f32_e32 v18, v140, v19
	v_max_f32_e32 v19, 0, v22
	v_fmac_f32_e32 v18, v139, v19
	v_max_f32_e32 v19, 0, v23
	v_fmac_f32_e32 v18, v138, v19
	v_max_f32_e32 v19, 0, v24
	v_fmac_f32_e32 v18, v137, v19
	v_max_f32_e32 v19, 0, v25
	v_fmac_f32_e32 v18, v136, v19
	v_max_f32_e32 v19, 0, v26
	v_fmac_f32_e32 v18, v135, v19
	v_max_f32_e32 v19, 0, v27
	v_fmac_f32_e32 v18, v134, v19
	v_max_f32_e32 v19, 0, v28
	v_fmac_f32_e32 v18, v133, v19
	v_max_f32_e32 v19, 0, v29
	v_fmac_f32_e32 v18, v132, v19
	v_max_f32_e32 v19, 0, v30
	v_fmac_f32_e32 v18, v131, v19
	v_max_f32_e32 v19, 0, v31
	v_fmac_f32_e32 v18, v130, v19
	v_max_f32_e32 v19, 0, v32
	v_fmac_f32_e32 v18, v129, v19
	v_max_f32_e32 v19, 0, v33
	v_fmac_f32_e32 v18, v128, v19
	v_ashrrev_i32_e32 v19, 31, v18
	v_bitop3_b32 v18, v19, v18, s8 bitop3:0x36
	v_cndmask_b32_e32 v236, 0, v18, vcc
	s_cmp_lt_u32 s0, 0x740
	s_cbranch_scc1 .Lix_z58
.Lix_b58:
	s_cmp_lt_u32 s0, 0x7a0
	s_cbranch_scc1 .Lix_w58
	s_waitcnt vmcnt(12)
	s_branch .Lix_m58

; #define MFMA(a, b, c) __builtin_amdgcn_mfma_f32_32x32x16_bf16((a), (b), (c), 0, 0, 0)
; DI unsigned ordkey(float f) { const unsigned b = __float_as_uint(f); return b ^ ((unsigned)((int)b >> 31) | 0x80000000u); }
; DI void indexer_phase(const u16* __restrict__ P, unsigned* __restrict__ mask) {
;     ...
;     for (int kb = 0; kb < 64; ++kb) {
;       unsigned u = 0u;
;       if (kb <= kbmax) {
;         f32x16 a;
; #pragma unroll
;         for (int r = 0; r < 16; ++r) a[r] = 0.f;
;         const u16* kp = P + (brow + 32 * kb + r32) * 7808 + 3584 + 8 * hi;
; #pragma unroll
;         for (int s = 0; s < 4; ++s) { const bf16x8 bk = *(const bf16x8*)(kp + 16 * s); a = MFMA(aq[s], bk, a); }
;         float v = 0.f;
; #pragma unroll
;         for (int i = 0; i < 16; ++i) v = fmaf(wv[i], fmaxf(a[i], 0.f), v);
;         u = (32 * kb + r32 <= tme) ? ordkey(v) : 0u;
;       }
;       sc[kb] = u;
.Lix_m58:
	v_cmp_le_i32_e32 vcc, 0x740, v16
	v_mfma_f32_32x32x16_bf16 v[18:33], v[46:49], v[96:99], 0
	v_mfma_f32_32x32x16_bf16 v[18:33], v[42:45], v[100:103], v[18:33]
	v_mfma_f32_32x32x16_bf16 v[18:33], v[38:41], v[104:107], v[18:33]
	v_mfma_f32_32x32x16_bf16 v[18:33], v[34:37], v[108:111], v[18:33]
	s_cmp_lt_u32 s0, 0x7c0
	s_cbranch_scc1 .Lix_np58
	global_load_dwordx4 v[96:99], v[124:125], off
	global_load_dwordx4 v[100:103], v[124:125], off offset:32
	global_load_dwordx4 v[104:107], v[124:125], off offset:64
	global_load_dwordx4 v[108:111], v[124:125], off offset:96
	v_lshl_add_u64 v[124:125], v[124:125], 0, s[22:23]
.Lix_np58:
	s_nop 10
	v_max_f32_e32 v18, 0, v18
	v_max_f32_e32 v19, 0, v19
	v_fma_f32 v18, v143, v18, 0
	v_fmac_f32_e32 v18, v142, v19
	v_max_f32_e32 v19, 0, v20
	v_fmac_f32_e32 v18, v141, v19
	v_max_f32_e32 v19, 0, v21
	v_fmac_f32_e32 v18, v140, v19
	v_max_f32_e32 v19, 0, v22
	v_fmac_f32_e32 v18, v139, v19
	v_max_f32_e32 v19, 0, v23
	v_fmac_f32_e32 v18, v138, v19
	v_max_f32_e32 v19, 0, v24
	v_fmac_f32_e32 v18, v137, v19
	v_max_f32_e32 v19, 0, v25
	v_fmac_f32_e32 v18, v136, v19
	v_max_f32_e32 v19, 0, v26
	v_fmac_f32_e32 v18, v135, v19
	v_max_f32_e32 v19, 0, v27
	v_fmac_f32_e32 v18, v134, v19
	v_max_f32_e32 v19, 0, v28
	v_fmac_f32_e32 v18, v133, v19
	v_max_f32_e32 v19, 0, v29
	v_fmac_f32_e32 v18, v132, v19
	v_max_f32_e32 v19, 0, v30
	v_fmac_f32_e32 v18, v131, v19
	v_max_f32_e32 v19, 0, v31
	v_fmac_f32_e32 v18, v130, v19
	v_max_f32_e32 v19, 0, v32
	v_fmac_f32_e32 v18, v129, v19
	v_max_f32_e32 v19, 0, v33
	v_fmac_f32_e32 v18, v128, v19
	v_ashrrev_i32_e32 v19, 31, v18
	v_bitop3_b32 v18, v19, v18, s8 bitop3:0x36
	v_cndmask_b32_e32 v207, 0, v18, vcc
	s_cmp_lt_u32 s0, 0x760
	s_cbranch_scc1 .Lix_z59
.Lix_b59:
	s_cmp_lt_u32 s0, 0x7c0
	s_cbranch_scc1 .Lix_w59
	s_waitcnt vmcnt(12)
	s_branch .Lix_m59

; #define MFMA(a, b, c) __builtin_amdgcn_mfma_f32_32x32x16_bf16((a), (b), (c), 0, 0, 0)
; DI unsigned ordkey(float f) { const unsigned b = __float_as_uint(f); return b ^ ((unsigned)((int)b >> 31) | 0x80000000u); }
; DI void indexer_phase(const u16* __restrict__ P, unsigned* __restrict__ mask) {
;     ...
;     for (int kb = 0; kb < 64; ++kb) {
;       unsigned u = 0u;
;       if (kb <= kbmax) {
;         f32x16 a;
; #pragma unroll
;         for (int r = 0; r < 16; ++r) a[r] = 0.f;
;         const u16* kp = P + (brow + 32 * kb + r32) * 7808 + 3584 + 8 * hi;
; #pragma unroll
;         for (int s = 0; s < 4; ++s) { const bf16x8 bk = *(const bf16x8*)(kp + 16 * s); a = MFMA(aq[s], bk, a); }
;         float v = 0.f;
; #pragma unroll
;         for (int i = 0; i < 16; ++i) v = fmaf(wv[i], fmaxf(a[i], 0.f), v);
;         u = (32 * kb + r32 <= tme) ? ordkey(v) : 0u;
;       }
;       sc[kb] = u;
.Lix_m59:
	v_cmp_le_i32_e32 vcc, 0x760, v16
	v_mfma_f32_32x32x16_bf16 v[18:33], v[46:49], v[112:115], 0
	v_mfma_f32_32x32x16_bf16 v[18:33], v[42:45], v[116:119], v[18:33]
	v_mfma_f32_32x32x16_bf16 v[18:33], v[38:41], v[120:123], v[18:33]
	v_mfma_f32_32x32x16_bf16 v[18:33], v[34:37], v[12:15], v[18:33]
	s_cmp_lt_u32 s0, 0x7e0
	s_cbranch_scc1 .Lix_np59
	global_load_dwordx4 v[112:115], v[124:125], off
	global_load_dwordx4 v[116:119], v[124:125], off offset:32
	global_load_dwordx4 v[120:123], v[124:125], off offset:64
	global_load_dwordx4 v[12:15], v[124:125], off offset:96
	v_lshl_add_u64 v[124:125], v[124:125], 0, s[22:23]
.Lix_np59:
	s_nop 10
	v_max_f32_e32 v18, 0, v18
	v_max_f32_e32 v19, 0, v19
	v_fma_f32 v18, v143, v18, 0
	v_fmac_f32_e32 v18, v142, v19
	v_max_f32_e32 v19, 0, v20
	v_fmac_f32_e32 v18, v141, v19
	v_max_f32_e32 v19, 0, v21
	v_fmac_f32_e32 v18, v140, v19
	v_max_f32_e32 v19, 0, v22
	v_fmac_f32_e32 v18, v139, v19
	v_max_f32_e32 v19, 0, v23
	v_fmac_f32_e32 v18, v138, v19
	v_max_f32_e32 v19, 0, v24
	v_fmac_f32_e32 v18, v137, v19
	v_max_f32_e32 v19, 0, v25
	v_fmac_f32_e32 v18, v136, v19
	v_max_f32_e32 v19, 0, v26
	v_fmac_f32_e32 v18, v135, v19
	v_max_f32_e32 v19, 0, v27
	v_fmac_f32_e32 v18, v134, v19
	v_max_f32_e32 v19, 0, v28
	v_fmac_f32_e32 v18, v133, v19
	v_max_f32_e32 v19, 0, v29
	v_fmac_f32_e32 v18, v132, v19
	v_max_f32_e32 v19, 0, v30
	v_fmac_f32_e32 v18, v131, v19
	v_max_f32_e32 v19, 0, v31
	v_fmac_f32_e32 v18, v130, v19
	v_max_f32_e32 v19, 0, v32
	v_fmac_f32_e32 v18, v129, v19
	v_max_f32_e32 v19, 0, v33
	v_fmac_f32_e32 v18, v128, v19
	v_ashrrev_i32_e32 v19, 31, v18
	v_bitop3_b32 v18, v19, v18, s8 bitop3:0x36
	v_cndmask_b32_e32 v238, 0, v18, vcc
	s_cmp_lt_u32 s0, 0x780
	s_cbranch_scc1 .Lix_z60
.Lix_b60:
	s_cmp_lt_u32 s0, 0x7e0
	s_cbranch_scc1 .Lix_w60
	s_waitcnt vmcnt(12)
	s_branch .Lix_m60

; #define MFMA(a, b, c) __builtin_amdgcn_mfma_f32_32x32x16_bf16((a), (b), (c), 0, 0, 0)
; DI unsigned ordkey(float f) { const unsigned b = __float_as_uint(f); return b ^ ((unsigned)((int)b >> 31) | 0x80000000u); }
; DI void indexer_phase(const u16* __restrict__ P, unsigned* __restrict__ mask) {
;     ...
;     for (int kb = 0; kb < 64; ++kb) {
;       unsigned u = 0u;
;       if (kb <= kbmax) {
;         f32x16 a;
; #pragma unroll
;         for (int r = 0; r < 16; ++r) a[r] = 0.f;
;         const u16* kp = P + (brow + 32 * kb + r32) * 7808 + 3584 + 8 * hi;
; #pragma unroll
;         for (int s = 0; s < 4; ++s) { const bf16x8 bk = *(const bf16x8*)(kp + 16 * s); a = MFMA(aq[s], bk, a); }
;         float v = 0.f;
; #pragma unroll
;         for (int i = 0; i < 16; ++i) v = fmaf(wv[i], fmaxf(a[i], 0.f), v);
;         u = (32 * kb + r32 <= tme) ? ordkey(v) : 0u;
;       }
;       sc[kb] = u;
.Lix_m60:
	v_cmp_le_i32_e32 vcc, 0x780, v16
	v_mfma_f32_32x32x16_bf16 v[18:33], v[46:49], v[64:67], 0
	v_mfma_f32_32x32x16_bf16 v[18:33], v[42:45], v[68:71], v[18:33]
	v_mfma_f32_32x32x16_bf16 v[18:33], v[38:41], v[72:75], v[18:33]
	v_mfma_f32_32x32x16_bf16 v[18:33], v[34:37], v[76:79], v[18:33]
	s_nop 12
	v_max_f32_e32 v18, 0, v18
	v_max_f32_e32 v19, 0, v19
	v_fma_f32 v18, v143, v18, 0
	v_fmac_f32_e32 v18, v142, v19
	v_max_f32_e32 v19, 0, v20
	v_fmac_f32_e32 v18, v141, v19
	v_max_f32_e32 v19, 0, v21
	v_fmac_f32_e32 v18, v140, v19
	v_max_f32_e32 v19, 0, v22
	v_fmac_f32_e32 v18, v139, v19
	v_max_f32_e32 v19, 0, v23
	v_fmac_f32_e32 v18, v138, v19
	v_max_f32_e32 v19, 0, v24
	v_fmac_f32_e32 v18, v137, v19
	v_max_f32_e32 v19, 0, v25
	v_fmac_f32_e32 v18, v136, v19
	v_max_f32_e32 v19, 0, v26
	v_fmac_f32_e32 v18, v135, v19
	v_max_f32_e32 v19, 0, v27
	v_fmac_f32_e32 v18, v134, v19
	v_max_f32_e32 v19, 0, v28
	v_fmac_f32_e32 v18, v133, v19
	v_max_f32_e32 v19, 0, v29
	v_fmac_f32_e32 v18, v132, v19
	v_max_f32_e32 v19, 0, v30
	v_fmac_f32_e32 v18, v131, v19
	v_max_f32_e32 v19, 0, v31
	v_fmac_f32_e32 v18, v130, v19
	v_max_f32_e32 v19, 0, v32
	v_fmac_f32_e32 v18, v129, v19
	v_max_f32_e32 v19, 0, v33
	v_fmac_f32_e32 v18, v128, v19
	v_ashrrev_i32_e32 v19, 31, v18
	v_bitop3_b32 v18, v19, v18, s8 bitop3:0x36
	v_cndmask_b32_e32 v237, 0, v18, vcc
	s_cmp_lt_u32 s0, 0x7a0
	s_cbranch_scc1 .Lix_z61
.Lix_b61:
	s_waitcnt vmcnt(0)
	v_cmp_le_i32_e32 vcc, 0x7a0, v16
	v_mfma_f32_32x32x16_bf16 v[18:33], v[46:49], v[80:83], 0
	v_mfma_f32_32x32x16_bf16 v[18:33], v[42:45], v[84:87], v[18:33]
	v_mfma_f32_32x32x16_bf16 v[18:33], v[38:41], v[88:91], v[18:33]
	v_mfma_f32_32x32x16_bf16 v[18:33], v[34:37], v[92:95], v[18:33]
	s_nop 12
	v_max_f32_e32 v18, 0, v18
	v_max_f32_e32 v19, 0, v19
	v_fma_f32 v18, v143, v18, 0
	v_fmac_f32_e32 v18, v142, v19
	v_max_f32_e32 v19, 0, v20
	v_fmac_f32_e32 v18, v141, v19
	v_max_f32_e32 v19, 0, v21
	v_fmac_f32_e32 v18, v140, v19
	v_max_f32_e32 v19, 0, v22
	v_fmac_f32_e32 v18, v139, v19
	v_max_f32_e32 v19, 0, v23
	v_fmac_f32_e32 v18, v138, v19
	v_max_f32_e32 v19, 0, v24
	v_fmac_f32_e32 v18, v137, v19
	v_max_f32_e32 v19, 0, v25
	v_fmac_f32_e32 v18, v136, v19
	v_max_f32_e32 v19, 0, v26
	v_fmac_f32_e32 v18, v135, v19
	v_max_f32_e32 v19, 0, v27
	v_fmac_f32_e32 v18, v134, v19
	v_max_f32_e32 v19, 0, v28
	v_fmac_f32_e32 v18, v133, v19
	v_max_f32_e32 v19, 0, v29
	v_fmac_f32_e32 v18, v132, v19
	v_max_f32_e32 v19, 0, v30
	v_fmac_f32_e32 v18, v131, v19
	v_max_f32_e32 v19, 0, v31
	v_fmac_f32_e32 v18, v130, v19
	v_max_f32_e32 v19, 0, v32
	v_fmac_f32_e32 v18, v129, v19
	v_max_f32_e32 v19, 0, v33
	v_fmac_f32_e32 v18, v128, v19
	v_ashrrev_i32_e32 v19, 31, v18
	v_bitop3_b32 v18, v19, v18, s8 bitop3:0x36
	v_cndmask_b32_e32 v240, 0, v18, vcc
	s_cmp_lt_u32 s0, 0x7c0
	s_cbranch_scc1 .Lix_z62
.Lix_b62:
	s_waitcnt vmcnt(0)
	v_cmp_le_i32_e32 vcc, 0x7c0, v16
	v_mfma_f32_32x32x16_bf16 v[18:33], v[46:49], v[96:99], 0
	v_mfma_f32_32x32x16_bf16 v[18:33], v[42:45], v[100:103], v[18:33]
	v_mfma_f32_32x32x16_bf16 v[18:33], v[38:41], v[104:107], v[18:33]
	v_mfma_f32_32x32x16_bf16 v[18:33], v[34:37], v[108:111], v[18:33]
	s_nop 12
	v_max_f32_e32 v18, 0, v18
	v_max_f32_e32 v19, 0, v19
	v_fma_f32 v18, v143, v18, 0
	v_fmac_f32_e32 v18, v142, v19
	v_max_f32_e32 v19, 0, v20
	v_fmac_f32_e32 v18, v141, v19
	v_max_f32_e32 v19, 0, v21
	v_fmac_f32_e32 v18, v140, v19
	v_max_f32_e32 v19, 0, v22
	v_fmac_f32_e32 v18, v139, v19
	v_max_f32_e32 v19, 0, v23
	v_fmac_f32_e32 v18, v138, v19
	v_max_f32_e32 v19, 0, v24
	v_fmac_f32_e32 v18, v137, v19
	v_max_f32_e32 v19, 0, v25
	v_fmac_f32_e32 v18, v136, v19
	v_max_f32_e32 v19, 0, v26
	v_fmac_f32_e32 v18, v135, v19
	v_max_f32_e32 v19, 0, v27
	v_fmac_f32_e32 v18, v134, v19
	v_max_f32_e32 v19, 0, v28
	v_fmac_f32_e32 v18, v133, v19
	v_max_f32_e32 v19, 0, v29
	v_fmac_f32_e32 v18, v132, v19
	v_max_f32_e32 v19, 0, v30
	v_fmac_f32_e32 v18, v131, v19
	v_max_f32_e32 v19, 0, v31
	v_fmac_f32_e32 v18, v130, v19
	v_max_f32_e32 v19, 0, v32
	v_fmac_f32_e32 v18, v129, v19
	v_max_f32_e32 v19, 0, v33
	v_fmac_f32_e32 v18, v128, v19
	v_ashrrev_i32_e32 v19, 31, v18
	v_bitop3_b32 v18, v19, v18, s8 bitop3:0x36
	v_cndmask_b32_e32 v239, 0, v18, vcc
	s_cmp_lt_u32 s0, 0x7e0
	s_cbranch_scc1 .Lix_z63
; #define MFMA(a, b, c) __builtin_amdgcn_mfma_f32_32x32x16_bf16((a), (b), (c), 0, 0, 0)
; DI unsigned ordkey(float f) { const unsigned b = __float_as_uint(f); return b ^ ((unsigned)((int)b >> 31) | 0x80000000u); }
; DI void indexer_phase(const u16* __restrict__ P, unsigned* __restrict__ mask) {
;     ...
;     for (int kb = 0; kb < 64; ++kb) {
;       unsigned u = 0u;
;       if (kb <= kbmax) {
;         f32x16 a;
; #pragma unroll
;         for (int r = 0; r < 16; ++r) a[r] = 0.f;
;         const u16* kp = P + (brow + 32 * kb + r32) * 7808 + 3584 + 8 * hi;
; #pragma unroll
;         for (int s = 0; s < 4; ++s) { const bf16x8 bk = *(const bf16x8*)(kp + 16 * s); a = MFMA(aq[s], bk, a); }
;         float v = 0.f;
; #pragma unroll
;         for (int i = 0; i < 16; ++i) v = fmaf(wv[i], fmaxf(a[i], 0.f), v);
;         u = (32 * kb + r32 <= tme) ? ordkey(v) : 0u;
;       }
;       sc[kb] = u;
;     }
;     const int target = (tme + 1 < 256) ? tme + 1 : 256;
.Lix_b63:
	s_waitcnt vmcnt(0)
	v_cmp_le_i32_e32 vcc, 0x7e0, v16
	v_mfma_f32_32x32x16_bf16 v[18:33], v[46:49], v[112:115], 0
	v_mfma_f32_32x32x16_bf16 v[18:33], v[42:45], v[116:119], v[18:33]
	v_mfma_f32_32x32x16_bf16 v[18:33], v[38:41], v[120:123], v[18:33]
	v_mfma_f32_32x32x16_bf16 v[18:33], v[34:37], v[12:15], v[18:33]
	s_nop 12
	v_max_f32_e32 v18, 0, v18
	v_max_f32_e32 v19, 0, v19
	v_fma_f32 v18, v143, v18, 0
	v_fmac_f32_e32 v18, v142, v19
	v_max_f32_e32 v19, 0, v20
	v_fmac_f32_e32 v18, v141, v19
	v_max_f32_e32 v19, 0, v21
	v_fmac_f32_e32 v18, v140, v19
	v_max_f32_e32 v19, 0, v22
	v_fmac_f32_e32 v18, v139, v19
	v_max_f32_e32 v19, 0, v23
	v_fmac_f32_e32 v18, v138, v19
	v_max_f32_e32 v19, 0, v24
	v_fmac_f32_e32 v18, v137, v19
	v_max_f32_e32 v19, 0, v25
	v_fmac_f32_e32 v18, v136, v19
	v_max_f32_e32 v19, 0, v26
	v_fmac_f32_e32 v18, v135, v19
	v_max_f32_e32 v19, 0, v27
	v_fmac_f32_e32 v18, v134, v19
	v_max_f32_e32 v19, 0, v28
	v_fmac_f32_e32 v18, v133, v19
	v_max_f32_e32 v19, 0, v29
	v_fmac_f32_e32 v18, v132, v19
	v_max_f32_e32 v19, 0, v30
	v_fmac_f32_e32 v18, v131, v19
	v_max_f32_e32 v19, 0, v31
	v_fmac_f32_e32 v18, v130, v19
	v_max_f32_e32 v19, 0, v32
	v_fmac_f32_e32 v18, v129, v19
	v_max_f32_e32 v19, 0, v33
	v_fmac_f32_e32 v18, v128, v19
	v_ashrrev_i32_e32 v19, 31, v18
	v_bitop3_b32 v18, v19, v18, s8 bitop3:0x36
	v_cndmask_b32_e32 v18, 0, v18, vcc
	s_branch .Lix_done
.Lix_z1:
	v_mov_b32_e32 v146, 0
.Lix_z2:
	v_mov_b32_e32 v145, 0
.Lix_z3:
	v_mov_b32_e32 v148, 0
.Lix_z4:
	v_mov_b32_e32 v147, 0
.Lix_z5:
	v_mov_b32_e32 v150, 0
.Lix_z6:
	v_mov_b32_e32 v149, 0
.Lix_z7:
	v_mov_b32_e32 v152, 0
.Lix_z8:
	v_mov_b32_e32 v151, 0
.Lix_z9:
	v_mov_b32_e32 v154, 0
.Lix_z10:
	v_mov_b32_e32 v153, 0
.Lix_z11:
	v_mov_b32_e32 v156, 0
.Lix_z12:
	v_mov_b32_e32 v155, 0
.Lix_z13:
	v_mov_b32_e32 v158, 0
.Lix_z14:
	v_mov_b32_e32 v157, 0
.Lix_z15:
	v_mov_b32_e32 v160, 0
.Lix_z16:
	v_mov_b32_e32 v159, 0
.Lix_z17:
	v_mov_b32_e32 v162, 0
.Lix_z18:
	v_mov_b32_e32 v161, 0
.Lix_z19:
	v_mov_b32_e32 v164, 0
.Lix_z20:
	v_mov_b32_e32 v163, 0
.Lix_z21:
	v_mov_b32_e32 v166, 0
.Lix_z22:
	v_mov_b32_e32 v165, 0
.Lix_z23:
	v_mov_b32_e32 v168, 0
.Lix_z24:
	v_mov_b32_e32 v167, 0
.Lix_z25:
	v_mov_b32_e32 v170, 0
.Lix_z26:
	v_mov_b32_e32 v169, 0
.Lix_z27:
	v_mov_b32_e32 v172, 0
.Lix_z28:
	v_mov_b32_e32 v171, 0
.Lix_z29:
	v_mov_b32_e32 v174, 0
.Lix_z30:
	v_mov_b32_e32 v173, 0
.Lix_z31:
	v_mov_b32_e32 v182, 0
.Lix_z32:
	v_mov_b32_e32 v175, 0
.Lix_z33:
	v_mov_b32_e32 v184, 0
.Lix_z34:
	v_mov_b32_e32 v183, 0
.Lix_z35:
	v_mov_b32_e32 v186, 0
.Lix_z36:
	v_mov_b32_e32 v185, 0
.Lix_z37:
	v_mov_b32_e32 v188, 0
.Lix_z38:
	v_mov_b32_e32 v187, 0
.Lix_z39:
	v_mov_b32_e32 v190, 0
.Lix_z40:
	v_mov_b32_e32 v189, 0
.Lix_z41:
	v_mov_b32_e32 v192, 0
.Lix_z42:
	v_mov_b32_e32 v191, 0
.Lix_z43:
	v_mov_b32_e32 v194, 0
.Lix_z44:
	v_mov_b32_e32 v193, 0
.Lix_z45:
	v_mov_b32_e32 v196, 0
.Lix_z46:
	v_mov_b32_e32 v195, 0
.Lix_z47:
	v_mov_b32_e32 v198, 0
.Lix_z48:
	v_mov_b32_e32 v197, 0
.Lix_z49:
	v_mov_b32_e32 v200, 0
.Lix_z50:
	v_mov_b32_e32 v199, 0
.Lix_z51:
	v_mov_b32_e32 v202, 0
.Lix_z52:
	v_mov_b32_e32 v201, 0
.Lix_z53:
	v_mov_b32_e32 v204, 0
.Lix_z54:
	v_mov_b32_e32 v203, 0
.Lix_z55:
	v_mov_b32_e32 v206, 0
.Lix_z56:
	v_mov_b32_e32 v205, 0
.Lix_z57:
	v_mov_b32_e32 v236, 0
.Lix_z58:
	v_mov_b32_e32 v207, 0
.Lix_z59:
	v_mov_b32_e32 v238, 0
.Lix_z60:
	v_mov_b32_e32 v237, 0
.Lix_z61:
	v_mov_b32_e32 v240, 0
.Lix_z62:
	v_mov_b32_e32 v239, 0
.Lix_z63:
	v_mov_b32_e32 v18, 0
.Lix_done:
	s_mov_b32 s63, s3
	s_mov_b32 s79, s84
	s_mov_b64 s[84:85], s[4:5]
	s_mov_b32 s59, s55
	s_mov_b32 s78, s28
	s_mov_b32 s86, s35
	s_mov_b64 s[16:17], s[90:91]
	s_mov_b64 s[96:97], s[52:53]
	s_mov_b64 s[76:77], s[42:43]
	v_mov_b32_e32 v144, 0
	s_mov_b32 s0, 31
	v_min_i32_e32 v3, 0xff, v127
	v_cmp_lt_i32_e32 vcc, v221, v248
	s_nop 1
	v_cndmask_b32_e32 v4, v234, v221, vcc
	v_cmp_lt_i32_e32 vcc, v220, v248
	v_lshlrev_b32_e32 v4, 2, v4
	s_nop 0
	v_cndmask_b32_e32 v5, v234, v220, vcc
	v_cmp_lt_i32_e32 vcc, v219, v248
	v_lshlrev_b32_e32 v5, 2, v5
	s_nop 0
	v_cndmask_b32_e32 v6, v234, v219, vcc
	v_cmp_lt_i32_e32 vcc, v218, v248
	v_lshlrev_b32_e32 v6, 2, v6
	s_nop 0
	v_cndmask_b32_e32 v7, v234, v218, vcc
	v_cmp_lt_i32_e32 vcc, v249, v248
	v_lshlrev_b32_e32 v7, 2, v7
	s_nop 0
	v_cndmask_b32_e32 v8, v234, v249, vcc
	v_lshlrev_b32_e32 v8, 2, v8
